# P2 requant rows: first half of the next row prefetched into spare registers during the current row (row loads no longer exposed at each row start)
# baseline (speedup 1.0000x reference)
.LBB0_177:
	v_readlane_b32 s2, v252, 30
	s_cmp_lt_i32 s2, 3
	s_cselect_b64 s[0:1], -1, 0
	s_and_b64 s[0:1], s[0:1], s[4:5]
	s_cmpk_lt_i32 s86, 0x400
	s_cselect_b64 s[4:5], -1, 0
	v_writelane_b32 v251, s4, 47
	v_readlane_b32 s3, v252, 31
	s_nop 0
	v_writelane_b32 v251, s5, 48
	s_nop 0
	v_readlane_b32 s4, v251, 44
	s_lshl_b32 s2, s4, 7
	s_cmp_gt_i32 s3, 3
	v_writelane_b32 v251, s2, 49
	s_cselect_b64 s[10:11], -1, 0
	s_andn2_b64 vcc, exec, s[0:1]
	s_mul_i32 s0, s4, 0x81
	v_writelane_b32 v251, s0, 50
	s_cbranch_vccnz .LBB0_317
	v_mov_b32_e32 v2, v0
	s_nop 0
	v_readfirstlane_b32 s0, v2
	s_ashr_i32 s3, s0, 6
	v_readlane_b32 s0, v251, 42
	s_lshl_b32 s12, s0, 3
	s_add_i32 s2, s12, s3
	s_cmpk_gt_i32 s2, 0x3fff
	s_cbranch_scc1 .LBB0_187
	v_and_b32_e32 v4, 4, v2
	v_cmp_eq_u32_e32 vcc, 0, v4
	v_and_b32_e32 v4, 2, v2
	v_and_b32_e32 v3, 63, v2
	v_cndmask_b32_e64 v90, -1.0, 1.0, vcc
	v_cmp_eq_u32_e32 vcc, 0, v4
	v_and_b32_e32 v2, 1, v2
	v_readlane_b32 s0, v252, 2
	v_cndmask_b32_e64 v92, -1.0, 1.0, vcc
	v_cmp_eq_u32_e32 vcc, 0, v2
	v_mbcnt_lo_u32_b32 v2, -1, 0
	v_mbcnt_hi_u32_b32 v2, -1, v2
	v_and_b32_e32 v4, 64, v2
	v_add_u32_e32 v4, 64, v4
	v_xor_b32_e32 v5, 1, v2
	v_cndmask_b32_e64 v94, -1.0, 1.0, vcc
	v_cmp_lt_i32_e32 vcc, v5, v4
	s_lshl_b32 s28, s0, 3
	s_ashr_i32 s13, s3, 31
	v_cndmask_b32_e32 v5, v2, v5, vcc
	v_lshlrev_b32_e32 v104, 2, v5
	v_xor_b32_e32 v5, 2, v2
	v_cmp_lt_i32_e32 vcc, v5, v4
	s_ashr_i32 s15, s12, 31
	s_add_u32 s14, s3, s12
	v_cndmask_b32_e32 v5, v2, v5, vcc
	v_lshlrev_b32_e32 v105, 2, v5
	v_xor_b32_e32 v5, 4, v2
	v_cmp_lt_i32_e32 vcc, v5, v4
	s_addc_u32 s15, s13, s15
	s_lshl_b64 s[12:13], s[14:15], 2
	v_cndmask_b32_e32 v5, v2, v5, vcc
	v_lshlrev_b32_e32 v106, 2, v5
	v_xor_b32_e32 v5, 8, v2
	v_cmp_lt_i32_e32 vcc, v5, v4
	s_add_u32 s3, s12, 0x80000
	v_lshlrev_b32_e32 v96, 3, v3
	v_cndmask_b32_e32 v5, v2, v5, vcc
	v_lshlrev_b32_e32 v107, 2, v5
	v_xor_b32_e32 v5, 16, v2
	v_cmp_lt_i32_e32 vcc, v5, v4
	v_mov_b32_e32 v97, 0
	s_addc_u32 s12, s13, 0
	v_cndmask_b32_e32 v5, v2, v5, vcc
	v_lshlrev_b32_e32 v108, 2, v5
	v_xor_b32_e32 v5, 32, v2
	v_cmp_lt_i32_e32 vcc, v5, v4
	s_mul_i32 s13, s15, 0x2b00
	v_readlane_b32 s1, v252, 3
	v_cndmask_b32_e32 v2, v2, v5, vcc
	v_lshlrev_b32_e32 v109, 2, v2
	v_mov_b32_e32 v2, 0x2b00
	v_mad_u64_u32 v[98:99], s[16:17], s14, v2, v[96:97]
	v_lshlrev_b32_e32 v96, 4, v3
	v_mov_b32_e32 v2, 0x5600
	s_mov_b32 s18, s0
	s_ashr_i32 s29, s28, 31
	v_add_u32_e32 v99, s13, v99
	s_mul_i32 s13, s15, 0x5600
	v_mad_u64_u32 v[100:101], s[14:15], s14, v2, v[96:97]
	v_cmp_gt_u32_e64 s[0:1], 32, v3
	v_cmp_eq_u32_e64 s[4:5], 0, v3
	v_mov_b32_e32 v91, v90
	v_mov_b32_e32 v93, v92
	v_mov_b32_e32 v95, v94
	s_lshl_b64 s[30:31], s[28:29], 2
	s_mul_i32 s36, s18, 0x15800
	s_mul_hi_i32 s37, s28, 0x2b00
	v_add_u32_e32 v101, s13, v101
	s_mul_i32 s38, s18, 0x2b000
	s_mul_hi_i32 s39, s28, 0x5600
	s_mov_b32 s40, 0x3e000000
	s_mov_b32 s13, 0x42fe0000
	s_mov_b32 s14, 0x40c0c00
	s_mov_b32 s96, 0x26400000
	s_mov_b32 s97, 0
	v_lshl_add_u64 v[254:255], s[94:95], 0, v[100:101]
	v_lshl_add_u64 v[254:255], v[254:255], 0, s[96:97]
	global_load_dwordx4 v[206:209], v[254:255], off nt
	global_load_dwordx4 v[210:213], v[254:255], off offset:1024 nt
	global_load_dwordx4 v[214:217], v[254:255], off offset:2048 nt
	global_load_dwordx4 v[218:221], v[254:255], off offset:3072 nt
	v_add_co_u32_e32 v254, vcc, 0x1000, v254
	s_nop 1
	v_addc_co_u32_e32 v255, vcc, 0, v255, vcc
	global_load_dwordx4 v[222:225], v[254:255], off nt
	global_load_dwordx4 v[226:229], v[254:255], off offset:1024 nt
	global_load_dwordx4 v[230:233], v[254:255], off offset:2048 nt
	global_load_dwordx4 v[234:237], v[254:255], off offset:3072 nt
	v_add_co_u32_e32 v254, vcc, 0x1000, v254
	s_nop 1
	v_addc_co_u32_e32 v255, vcc, 0, v255, vcc
	global_load_dwordx4 v[238:241], v[254:255], off nt
	global_load_dwordx4 v[242:245], v[254:255], off offset:1024 nt
	global_load_dwordx4 v[246:249], v[254:255], off offset:2048 nt
	s_waitcnt vmcnt(0)
	s_branch .LBB0_181

.LBB0_181:
	v_lshl_add_u64 v[102:103], s[94:95], 0, v[100:101]
	v_add_co_u32_e32 v2, vcc, 0x26400000, v102
	v_mov_b32_e32 v4, 0
	s_nop 0
	v_addc_co_u32_e32 v3, vcc, 0, v103, vcc
	s_waitcnt vmcnt(20)
	v_mov_b64_e32 v[86:87], v[206:207]
	v_mov_b64_e32 v[88:89], v[208:209]
	v_mov_b64_e32 v[82:83], v[210:211]
	v_mov_b64_e32 v[84:85], v[212:213]
	v_mov_b64_e32 v[78:79], v[214:215]
	v_mov_b64_e32 v[80:81], v[216:217]
	v_mov_b64_e32 v[74:75], v[218:219]
	v_mov_b64_e32 v[76:77], v[220:221]
	v_mov_b64_e32 v[70:71], v[222:223]
	v_mov_b64_e32 v[72:73], v[224:225]
	v_mov_b64_e32 v[66:67], v[226:227]
	v_mov_b64_e32 v[68:69], v[228:229]
	v_mov_b64_e32 v[62:63], v[230:231]
	v_mov_b64_e32 v[64:65], v[232:233]
	v_mov_b64_e32 v[58:59], v[234:235]
	v_mov_b64_e32 v[60:61], v[236:237]
	v_mov_b64_e32 v[54:55], v[238:239]
	v_mov_b64_e32 v[56:57], v[240:241]
	v_mov_b64_e32 v[50:51], v[242:243]
	v_mov_b64_e32 v[52:53], v[244:245]
	v_mov_b64_e32 v[46:47], v[246:247]
	v_mov_b64_e32 v[48:49], v[248:249]
	v_lshl_add_u64 v[254:255], v[102:103], 0, s[38:39]
	v_lshl_add_u64 v[254:255], v[254:255], 0, s[96:97]
	global_load_dwordx4 v[206:209], v[254:255], off nt
	global_load_dwordx4 v[210:213], v[254:255], off offset:1024 nt
	global_load_dwordx4 v[214:217], v[254:255], off offset:2048 nt
	global_load_dwordx4 v[218:221], v[254:255], off offset:3072 nt
	v_add_co_u32_e32 v254, vcc, 0x1000, v254
	s_nop 1
	v_addc_co_u32_e32 v255, vcc, 0, v255, vcc
	global_load_dwordx4 v[222:225], v[254:255], off nt
	global_load_dwordx4 v[226:229], v[254:255], off offset:1024 nt
	global_load_dwordx4 v[230:233], v[254:255], off offset:2048 nt
	global_load_dwordx4 v[234:237], v[254:255], off offset:3072 nt
	v_add_co_u32_e32 v254, vcc, 0x1000, v254
	s_nop 1
	v_addc_co_u32_e32 v255, vcc, 0, v255, vcc
	global_load_dwordx4 v[238:241], v[254:255], off nt
	global_load_dwordx4 v[242:245], v[254:255], off offset:1024 nt
	global_load_dwordx4 v[246:249], v[254:255], off offset:2048 nt
	s_nop 0
	s_nop 0
	s_nop 0
	s_nop 0
	v_add_co_u32_e32 v2, vcc, 0x26401000, v102
	v_mov_b32_e32 v5, 0
	s_nop 0
	v_addc_co_u32_e32 v3, vcc, 0, v103, vcc
	s_nop 0
	s_nop 0
	s_nop 0
	s_nop 0
	v_add_co_u32_e32 v2, vcc, 0x26402000, v102
	s_nop 1
	v_addc_co_u32_e32 v3, vcc, 0, v103, vcc
	s_nop 0
	s_nop 0
	s_nop 0
	global_load_dwordx4 v[42:45], v[2:3], off offset:3072 nt
	v_add_co_u32_e32 v2, vcc, 0x26403000, v102
	s_nop 1
	v_addc_co_u32_e32 v3, vcc, 0, v103, vcc
	global_load_dwordx4 v[38:41], v[2:3], off nt
	global_load_dwordx4 v[34:37], v[2:3], off offset:1024 nt
	global_load_dwordx4 v[30:33], v[2:3], off offset:2048 nt
	global_load_dwordx4 v[26:29], v[2:3], off offset:3072 nt
	v_add_co_u32_e32 v2, vcc, 0x26404000, v102
	s_nop 1
	v_addc_co_u32_e32 v3, vcc, 0, v103, vcc
	global_load_dwordx4 v[22:25], v[2:3], off nt
	global_load_dwordx4 v[18:21], v[2:3], off offset:1024 nt
	global_load_dwordx4 v[14:17], v[2:3], off offset:2048 nt
	global_load_dwordx4 v[10:13], v[2:3], off offset:3072 nt
	v_add_co_u32_e32 v2, vcc, 0x26405000, v102
	s_nop 1
	v_addc_co_u32_e32 v3, vcc, 0, v103, vcc
	global_load_dwordx4 v[6:9], v[2:3], off nt
	v_mov_b32_e32 v2, 0
	v_mov_b32_e32 v3, 0
	s_and_saveexec_b64 s[42:43], s[0:1]
	s_cbranch_execz .LBB0_183
	v_add_co_u32_e32 v2, vcc, 0x26405000, v102
	s_nop 1
	v_addc_co_u32_e32 v3, vcc, 0, v103, vcc
	global_load_dwordx4 v[2:5], v[2:3], off offset:1024 nt
.LBB0_183:
	s_or_b64 exec, exec, s[42:43]
	s_nop 0
	v_lshlrev_b32_e32 v96, 16, v86
	v_and_b32_e32 v102, 0xffff0000, v86
	v_lshlrev_b32_e32 v103, 16, v87
	v_and_b32_e32 v110, 0xffff0000, v87
	v_lshlrev_b32_e32 v111, 16, v88
	v_and_b32_e32 v112, 0xffff0000, v88
	v_lshlrev_b32_e32 v113, 16, v89
	v_and_b32_e32 v114, 0xffff0000, v89
	v_add_f32_e32 v86, v96, v102
	v_sub_f32_e32 v87, v96, v102
	v_add_f32_e32 v88, v103, v110
	v_sub_f32_e32 v89, v103, v110
	v_add_f32_e32 v102, v111, v112
	v_sub_f32_e32 v103, v111, v112
	v_add_f32_e32 v110, v113, v114
	v_sub_f32_e32 v111, v113, v114
	v_pk_add_f32 v[112:113], v[86:87], v[88:89] neg_lo:[0,1] neg_hi:[0,1]
	v_pk_add_f32 v[114:115], v[102:103], v[110:111] neg_lo:[0,1] neg_hi:[0,1]
	v_pk_add_f32 v[86:87], v[86:87], v[88:89]
	v_pk_add_f32 v[116:117], v[112:113], v[114:115] neg_lo:[0,1] neg_hi:[0,1]
	v_pk_add_f32 v[112:113], v[112:113], v[114:115]
	v_pk_add_f32 v[88:89], v[102:103], v[110:111]
	v_mov_b32_dpp v118, v116 quad_perm:[1,0,3,2] row_mask:0xf bank_mask:0xf bound_ctrl:1
	v_mov_b32_dpp v114, v112 quad_perm:[1,0,3,2] row_mask:0xf bank_mask:0xf bound_ctrl:1
	v_mov_b32_dpp v115, v113 quad_perm:[1,0,3,2] row_mask:0xf bank_mask:0xf bound_ctrl:1
	v_pk_fma_f32 v[112:113], v[94:95], v[112:113], v[114:115]
	v_pk_add_f32 v[102:103], v[86:87], v[88:89] neg_lo:[0,1] neg_hi:[0,1]
	v_pk_add_f32 v[86:87], v[86:87], v[88:89]
	v_mov_b32_dpp v114, v112 quad_perm:[2,3,0,1] row_mask:0xf bank_mask:0xf bound_ctrl:1
	v_mov_b32_dpp v115, v113 quad_perm:[2,3,0,1] row_mask:0xf bank_mask:0xf bound_ctrl:1
	v_pk_fma_f32 v[112:113], v[92:93], v[112:113], v[114:115]
	ds_swizzle_b32 v114, v112 offset:swizzle(SWAP,4)
	ds_swizzle_b32 v115, v113 offset:swizzle(SWAP,4)
	v_mov_b32_dpp v88, v86 quad_perm:[1,0,3,2] row_mask:0xf bank_mask:0xf bound_ctrl:1
	v_mov_b32_dpp v89, v87 quad_perm:[1,0,3,2] row_mask:0xf bank_mask:0xf bound_ctrl:1
	v_mov_b32_dpp v119, v117 quad_perm:[1,0,3,2] row_mask:0xf bank_mask:0xf bound_ctrl:1
	v_mov_b32_dpp v110, v102 quad_perm:[1,0,3,2] row_mask:0xf bank_mask:0xf bound_ctrl:1
	v_mov_b32_dpp v111, v103 quad_perm:[1,0,3,2] row_mask:0xf bank_mask:0xf bound_ctrl:1
	v_pk_fma_f32 v[86:87], v[94:95], v[86:87], v[88:89]
	v_pk_fma_f32 v[116:117], v[94:95], v[116:117], v[118:119]
	v_pk_fma_f32 v[102:103], v[94:95], v[102:103], v[110:111]
	v_mov_b32_dpp v88, v86 quad_perm:[2,3,0,1] row_mask:0xf bank_mask:0xf bound_ctrl:1
	v_mov_b32_dpp v89, v87 quad_perm:[2,3,0,1] row_mask:0xf bank_mask:0xf bound_ctrl:1
	v_mov_b32_dpp v118, v116 quad_perm:[2,3,0,1] row_mask:0xf bank_mask:0xf bound_ctrl:1
	v_mov_b32_dpp v119, v117 quad_perm:[2,3,0,1] row_mask:0xf bank_mask:0xf bound_ctrl:1
	v_mov_b32_dpp v110, v102 quad_perm:[2,3,0,1] row_mask:0xf bank_mask:0xf bound_ctrl:1
	v_mov_b32_dpp v111, v103 quad_perm:[2,3,0,1] row_mask:0xf bank_mask:0xf bound_ctrl:1
	v_pk_fma_f32 v[86:87], v[92:93], v[86:87], v[88:89]
	v_pk_fma_f32 v[116:117], v[92:93], v[116:117], v[118:119]
	v_pk_fma_f32 v[102:103], v[92:93], v[102:103], v[110:111]
	ds_swizzle_b32 v88, v86 offset:swizzle(SWAP,4)
	ds_swizzle_b32 v89, v87 offset:swizzle(SWAP,4)
	s_waitcnt lgkmcnt(2)
	v_pk_fma_f32 v[112:113], v[90:91], v[112:113], v[114:115]
	ds_swizzle_b32 v110, v102 offset:swizzle(SWAP,4)
	ds_swizzle_b32 v111, v103 offset:swizzle(SWAP,4)
	ds_swizzle_b32 v114, v116 offset:swizzle(SWAP,4)
	ds_swizzle_b32 v115, v117 offset:swizzle(SWAP,4)
	s_waitcnt lgkmcnt(4)
	v_pk_fma_f32 v[86:87], v[90:91], v[86:87], v[88:89]
	v_pk_mul_f32 v[112:113], v[112:113], s[40:41] op_sel_hi:[1,0]
	v_pk_mul_f32 v[86:87], v[86:87], s[40:41] op_sel_hi:[1,0]
	s_waitcnt lgkmcnt(2)
	v_pk_fma_f32 v[88:89], v[90:91], v[102:103], v[110:111]
	s_waitcnt lgkmcnt(0)
	v_pk_fma_f32 v[102:103], v[90:91], v[116:117], v[114:115]
	v_pk_mul_f32 v[88:89], v[88:89], s[40:41] op_sel_hi:[1,0]
	v_pk_mul_f32 v[102:103], v[102:103], s[40:41] op_sel_hi:[1,0]
	v_cvt_pk_bf16_f32 v86, v86, v87
	v_cvt_pk_bf16_f32 v88, v88, v89
	v_cvt_pk_bf16_f32 v89, v102, v103
	v_lshlrev_b32_e32 v96, 16, v86
	v_and_b32_e32 v102, 0xffff0000, v86
	v_cvt_pk_bf16_f32 v87, v112, v113
	v_and_b32_e32 v86, 0x7fffffff, v102
	v_max_f32_e64 v103, |v96|, |v96|
	v_max_f32_e32 v111, v103, v86
	v_lshlrev_b32_e32 v103, 16, v87
	v_and_b32_e32 v110, 0xffff0000, v87
	v_and_b32_e32 v86, 0x7fffffff, v110
	v_max_f32_e64 v87, |v103|, |v103|
	v_max_f32_e32 v112, v87, v86
	v_lshlrev_b32_e32 v86, 16, v88
	v_and_b32_e32 v87, 0xffff0000, v88
	v_lshlrev_b32_e32 v88, 16, v89
	v_and_b32_e32 v89, 0xffff0000, v89
	v_and_b32_e32 v113, 0x7fffffff, v89
	v_max_f32_e64 v114, |v88|, |v88|
	v_max_f32_e32 v113, v114, v113
	v_max3_f32 v113, |v86|, |v87|, v113
	v_max3_f32 v124, v111, v112, v113
	s_nop 0
	v_lshlrev_b32_e32 v111, 16, v82
	v_and_b32_e32 v112, 0xffff0000, v82
	v_lshlrev_b32_e32 v113, 16, v83
	v_and_b32_e32 v114, 0xffff0000, v83
	v_lshlrev_b32_e32 v115, 16, v84
	v_and_b32_e32 v116, 0xffff0000, v84
	v_lshlrev_b32_e32 v117, 16, v85
	v_and_b32_e32 v118, 0xffff0000, v85
	v_add_f32_e32 v82, v111, v112
	v_sub_f32_e32 v83, v111, v112
	v_add_f32_e32 v84, v113, v114
	v_sub_f32_e32 v85, v113, v114
	v_add_f32_e32 v112, v115, v116
	v_sub_f32_e32 v113, v115, v116
	v_add_f32_e32 v114, v117, v118
	v_sub_f32_e32 v115, v117, v118
	v_pk_add_f32 v[116:117], v[82:83], v[84:85] neg_lo:[0,1] neg_hi:[0,1]
	v_pk_add_f32 v[118:119], v[112:113], v[114:115] neg_lo:[0,1] neg_hi:[0,1]
	v_pk_add_f32 v[82:83], v[82:83], v[84:85]
	v_pk_add_f32 v[120:121], v[116:117], v[118:119] neg_lo:[0,1] neg_hi:[0,1]
	v_pk_add_f32 v[116:117], v[116:117], v[118:119]
	v_pk_add_f32 v[84:85], v[112:113], v[114:115]
	v_mov_b32_dpp v122, v120 quad_perm:[1,0,3,2] row_mask:0xf bank_mask:0xf bound_ctrl:1
	v_mov_b32_dpp v118, v116 quad_perm:[1,0,3,2] row_mask:0xf bank_mask:0xf bound_ctrl:1
	v_mov_b32_dpp v119, v117 quad_perm:[1,0,3,2] row_mask:0xf bank_mask:0xf bound_ctrl:1
	v_pk_fma_f32 v[116:117], v[94:95], v[116:117], v[118:119]
	v_pk_add_f32 v[112:113], v[82:83], v[84:85] neg_lo:[0,1] neg_hi:[0,1]
	v_pk_add_f32 v[82:83], v[82:83], v[84:85]
	v_mov_b32_dpp v118, v116 quad_perm:[2,3,0,1] row_mask:0xf bank_mask:0xf bound_ctrl:1
	v_mov_b32_dpp v119, v117 quad_perm:[2,3,0,1] row_mask:0xf bank_mask:0xf bound_ctrl:1
	v_pk_fma_f32 v[116:117], v[92:93], v[116:117], v[118:119]
	ds_swizzle_b32 v118, v116 offset:swizzle(SWAP,4)
	ds_swizzle_b32 v119, v117 offset:swizzle(SWAP,4)
	v_mov_b32_dpp v84, v82 quad_perm:[1,0,3,2] row_mask:0xf bank_mask:0xf bound_ctrl:1
	v_mov_b32_dpp v85, v83 quad_perm:[1,0,3,2] row_mask:0xf bank_mask:0xf bound_ctrl:1
	v_mov_b32_dpp v123, v121 quad_perm:[1,0,3,2] row_mask:0xf bank_mask:0xf bound_ctrl:1
	v_mov_b32_dpp v114, v112 quad_perm:[1,0,3,2] row_mask:0xf bank_mask:0xf bound_ctrl:1
	v_mov_b32_dpp v115, v113 quad_perm:[1,0,3,2] row_mask:0xf bank_mask:0xf bound_ctrl:1
	v_pk_fma_f32 v[82:83], v[94:95], v[82:83], v[84:85]
	v_pk_fma_f32 v[120:121], v[94:95], v[120:121], v[122:123]
	v_pk_fma_f32 v[112:113], v[94:95], v[112:113], v[114:115]
	v_mov_b32_dpp v84, v82 quad_perm:[2,3,0,1] row_mask:0xf bank_mask:0xf bound_ctrl:1
	v_mov_b32_dpp v85, v83 quad_perm:[2,3,0,1] row_mask:0xf bank_mask:0xf bound_ctrl:1
	v_mov_b32_dpp v122, v120 quad_perm:[2,3,0,1] row_mask:0xf bank_mask:0xf bound_ctrl:1
	v_mov_b32_dpp v123, v121 quad_perm:[2,3,0,1] row_mask:0xf bank_mask:0xf bound_ctrl:1
	v_mov_b32_dpp v114, v112 quad_perm:[2,3,0,1] row_mask:0xf bank_mask:0xf bound_ctrl:1
	v_mov_b32_dpp v115, v113 quad_perm:[2,3,0,1] row_mask:0xf bank_mask:0xf bound_ctrl:1
	v_pk_fma_f32 v[82:83], v[92:93], v[82:83], v[84:85]
	v_pk_fma_f32 v[120:121], v[92:93], v[120:121], v[122:123]
	v_pk_fma_f32 v[112:113], v[92:93], v[112:113], v[114:115]
	ds_swizzle_b32 v84, v82 offset:swizzle(SWAP,4)
	ds_swizzle_b32 v85, v83 offset:swizzle(SWAP,4)
	s_waitcnt lgkmcnt(2)
	v_pk_fma_f32 v[116:117], v[90:91], v[116:117], v[118:119]
	ds_swizzle_b32 v114, v112 offset:swizzle(SWAP,4)
	ds_swizzle_b32 v115, v113 offset:swizzle(SWAP,4)
	ds_swizzle_b32 v118, v120 offset:swizzle(SWAP,4)
	ds_swizzle_b32 v119, v121 offset:swizzle(SWAP,4)
	s_waitcnt lgkmcnt(4)
	v_pk_fma_f32 v[82:83], v[90:91], v[82:83], v[84:85]
	v_pk_mul_f32 v[116:117], v[116:117], s[40:41] op_sel_hi:[1,0]
	v_pk_mul_f32 v[82:83], v[82:83], s[40:41] op_sel_hi:[1,0]
	s_waitcnt lgkmcnt(2)
	v_pk_fma_f32 v[84:85], v[90:91], v[112:113], v[114:115]
	s_waitcnt lgkmcnt(0)
	v_pk_fma_f32 v[112:113], v[90:91], v[120:121], v[118:119]
	v_pk_mul_f32 v[84:85], v[84:85], s[40:41] op_sel_hi:[1,0]
	v_pk_mul_f32 v[112:113], v[112:113], s[40:41] op_sel_hi:[1,0]
	v_cvt_pk_bf16_f32 v82, v82, v83
	v_cvt_pk_bf16_f32 v84, v84, v85
	v_cvt_pk_bf16_f32 v85, v112, v113
	v_lshlrev_b32_e32 v111, 16, v82
	v_and_b32_e32 v112, 0xffff0000, v82
	v_cvt_pk_bf16_f32 v83, v116, v117
	v_and_b32_e32 v82, 0x7fffffff, v112
	v_max_f32_e64 v113, |v111|, |v111|
	v_max_f32_e32 v115, v113, v82
	v_lshlrev_b32_e32 v113, 16, v83
	v_and_b32_e32 v114, 0xffff0000, v83
	v_and_b32_e32 v82, 0x7fffffff, v114
	v_max_f32_e64 v83, |v113|, |v113|
	v_max_f32_e32 v116, v83, v82
	v_lshlrev_b32_e32 v82, 16, v84
	v_and_b32_e32 v83, 0xffff0000, v84
	v_lshlrev_b32_e32 v84, 16, v85
	v_and_b32_e32 v85, 0xffff0000, v85
	v_and_b32_e32 v117, 0x7fffffff, v85
	v_max_f32_e64 v118, |v84|, |v84|
	v_max_f32_e32 v117, v118, v117
	v_max3_f32 v117, |v82|, |v83|, v117
	v_max3_f32 v115, v115, v116, v117
	v_max3_f32 v132, v124, 0, v115
	s_nop 0
	v_lshlrev_b32_e32 v115, 16, v78
	v_and_b32_e32 v116, 0xffff0000, v78
	v_lshlrev_b32_e32 v117, 16, v79
	v_and_b32_e32 v118, 0xffff0000, v79
	v_lshlrev_b32_e32 v119, 16, v80
	v_and_b32_e32 v120, 0xffff0000, v80
	v_lshlrev_b32_e32 v121, 16, v81
	v_and_b32_e32 v122, 0xffff0000, v81
	v_add_f32_e32 v78, v115, v116
	v_sub_f32_e32 v79, v115, v116
	v_add_f32_e32 v80, v117, v118
	v_sub_f32_e32 v81, v117, v118
	v_add_f32_e32 v116, v119, v120
	v_sub_f32_e32 v117, v119, v120
	v_add_f32_e32 v118, v121, v122
	v_sub_f32_e32 v119, v121, v122
	v_pk_add_f32 v[120:121], v[78:79], v[80:81] neg_lo:[0,1] neg_hi:[0,1]
	v_pk_add_f32 v[122:123], v[116:117], v[118:119] neg_lo:[0,1] neg_hi:[0,1]
	v_pk_add_f32 v[78:79], v[78:79], v[80:81]
	v_pk_add_f32 v[124:125], v[120:121], v[122:123] neg_lo:[0,1] neg_hi:[0,1]
	v_pk_add_f32 v[120:121], v[120:121], v[122:123]
	v_pk_add_f32 v[80:81], v[116:117], v[118:119]
	v_mov_b32_dpp v126, v124 quad_perm:[1,0,3,2] row_mask:0xf bank_mask:0xf bound_ctrl:1
	v_mov_b32_dpp v122, v120 quad_perm:[1,0,3,2] row_mask:0xf bank_mask:0xf bound_ctrl:1
	v_mov_b32_dpp v123, v121 quad_perm:[1,0,3,2] row_mask:0xf bank_mask:0xf bound_ctrl:1
	v_pk_fma_f32 v[120:121], v[94:95], v[120:121], v[122:123]
	v_pk_add_f32 v[116:117], v[78:79], v[80:81] neg_lo:[0,1] neg_hi:[0,1]
	v_pk_add_f32 v[78:79], v[78:79], v[80:81]
	v_mov_b32_dpp v122, v120 quad_perm:[2,3,0,1] row_mask:0xf bank_mask:0xf bound_ctrl:1
	v_mov_b32_dpp v123, v121 quad_perm:[2,3,0,1] row_mask:0xf bank_mask:0xf bound_ctrl:1
	v_pk_fma_f32 v[120:121], v[92:93], v[120:121], v[122:123]
	ds_swizzle_b32 v122, v120 offset:swizzle(SWAP,4)
	ds_swizzle_b32 v123, v121 offset:swizzle(SWAP,4)
	v_mov_b32_dpp v80, v78 quad_perm:[1,0,3,2] row_mask:0xf bank_mask:0xf bound_ctrl:1
	v_mov_b32_dpp v81, v79 quad_perm:[1,0,3,2] row_mask:0xf bank_mask:0xf bound_ctrl:1
	v_mov_b32_dpp v127, v125 quad_perm:[1,0,3,2] row_mask:0xf bank_mask:0xf bound_ctrl:1
	v_mov_b32_dpp v118, v116 quad_perm:[1,0,3,2] row_mask:0xf bank_mask:0xf bound_ctrl:1
	v_mov_b32_dpp v119, v117 quad_perm:[1,0,3,2] row_mask:0xf bank_mask:0xf bound_ctrl:1
	v_pk_fma_f32 v[78:79], v[94:95], v[78:79], v[80:81]
	v_pk_fma_f32 v[124:125], v[94:95], v[124:125], v[126:127]
	v_pk_fma_f32 v[116:117], v[94:95], v[116:117], v[118:119]
	v_mov_b32_dpp v80, v78 quad_perm:[2,3,0,1] row_mask:0xf bank_mask:0xf bound_ctrl:1
	v_mov_b32_dpp v81, v79 quad_perm:[2,3,0,1] row_mask:0xf bank_mask:0xf bound_ctrl:1
	v_mov_b32_dpp v126, v124 quad_perm:[2,3,0,1] row_mask:0xf bank_mask:0xf bound_ctrl:1
	v_mov_b32_dpp v127, v125 quad_perm:[2,3,0,1] row_mask:0xf bank_mask:0xf bound_ctrl:1
	v_mov_b32_dpp v118, v116 quad_perm:[2,3,0,1] row_mask:0xf bank_mask:0xf bound_ctrl:1
	v_mov_b32_dpp v119, v117 quad_perm:[2,3,0,1] row_mask:0xf bank_mask:0xf bound_ctrl:1
	v_pk_fma_f32 v[78:79], v[92:93], v[78:79], v[80:81]
	v_pk_fma_f32 v[124:125], v[92:93], v[124:125], v[126:127]
	v_pk_fma_f32 v[116:117], v[92:93], v[116:117], v[118:119]
	ds_swizzle_b32 v80, v78 offset:swizzle(SWAP,4)
	ds_swizzle_b32 v81, v79 offset:swizzle(SWAP,4)
	s_waitcnt lgkmcnt(2)
	v_pk_fma_f32 v[120:121], v[90:91], v[120:121], v[122:123]
	ds_swizzle_b32 v118, v116 offset:swizzle(SWAP,4)
	ds_swizzle_b32 v119, v117 offset:swizzle(SWAP,4)
	ds_swizzle_b32 v122, v124 offset:swizzle(SWAP,4)
	ds_swizzle_b32 v123, v125 offset:swizzle(SWAP,4)
	s_waitcnt lgkmcnt(4)
	v_pk_fma_f32 v[78:79], v[90:91], v[78:79], v[80:81]
	v_pk_mul_f32 v[120:121], v[120:121], s[40:41] op_sel_hi:[1,0]
	v_pk_mul_f32 v[78:79], v[78:79], s[40:41] op_sel_hi:[1,0]
	s_waitcnt lgkmcnt(2)
	v_pk_fma_f32 v[80:81], v[90:91], v[116:117], v[118:119]
	s_waitcnt lgkmcnt(0)
	v_pk_fma_f32 v[116:117], v[90:91], v[124:125], v[122:123]
	v_pk_mul_f32 v[80:81], v[80:81], s[40:41] op_sel_hi:[1,0]
	v_pk_mul_f32 v[116:117], v[116:117], s[40:41] op_sel_hi:[1,0]
	v_cvt_pk_bf16_f32 v78, v78, v79
	v_cvt_pk_bf16_f32 v80, v80, v81
	v_cvt_pk_bf16_f32 v81, v116, v117
	v_lshlrev_b32_e32 v115, 16, v78
	v_and_b32_e32 v116, 0xffff0000, v78
	v_cvt_pk_bf16_f32 v79, v120, v121
	v_and_b32_e32 v78, 0x7fffffff, v116
	v_max_f32_e64 v117, |v115|, |v115|
	v_max_f32_e32 v119, v117, v78
	v_lshlrev_b32_e32 v117, 16, v79
	v_and_b32_e32 v118, 0xffff0000, v79
	v_and_b32_e32 v78, 0x7fffffff, v118
	v_max_f32_e64 v79, |v117|, |v117|
	v_max_f32_e32 v120, v79, v78
	v_lshlrev_b32_e32 v78, 16, v80
	v_and_b32_e32 v79, 0xffff0000, v80
	v_lshlrev_b32_e32 v80, 16, v81
	v_and_b32_e32 v81, 0xffff0000, v81
	v_and_b32_e32 v121, 0x7fffffff, v81
	v_max_f32_e64 v122, |v80|, |v80|
	v_max_f32_e32 v121, v122, v121
	v_max3_f32 v121, |v78|, |v79|, v121
	v_max3_f32 v133, v119, v120, v121
	s_nop 0
	v_lshlrev_b32_e32 v119, 16, v74
	v_and_b32_e32 v120, 0xffff0000, v74
	v_lshlrev_b32_e32 v121, 16, v75
	v_and_b32_e32 v122, 0xffff0000, v75
	v_lshlrev_b32_e32 v123, 16, v76
	v_and_b32_e32 v124, 0xffff0000, v76
	v_lshlrev_b32_e32 v125, 16, v77
	v_and_b32_e32 v126, 0xffff0000, v77
	v_add_f32_e32 v74, v119, v120
	v_sub_f32_e32 v75, v119, v120
	v_add_f32_e32 v76, v121, v122
	v_sub_f32_e32 v77, v121, v122
	v_add_f32_e32 v120, v123, v124
	v_sub_f32_e32 v121, v123, v124
	v_add_f32_e32 v122, v125, v126
	v_sub_f32_e32 v123, v125, v126
	v_pk_add_f32 v[124:125], v[74:75], v[76:77] neg_lo:[0,1] neg_hi:[0,1]
	v_pk_add_f32 v[126:127], v[120:121], v[122:123] neg_lo:[0,1] neg_hi:[0,1]
	v_pk_add_f32 v[74:75], v[74:75], v[76:77]
	v_pk_add_f32 v[128:129], v[124:125], v[126:127] neg_lo:[0,1] neg_hi:[0,1]
	v_pk_add_f32 v[124:125], v[124:125], v[126:127]
	v_pk_add_f32 v[76:77], v[120:121], v[122:123]
	v_mov_b32_dpp v130, v128 quad_perm:[1,0,3,2] row_mask:0xf bank_mask:0xf bound_ctrl:1
	v_mov_b32_dpp v126, v124 quad_perm:[1,0,3,2] row_mask:0xf bank_mask:0xf bound_ctrl:1
	v_mov_b32_dpp v127, v125 quad_perm:[1,0,3,2] row_mask:0xf bank_mask:0xf bound_ctrl:1
	v_pk_fma_f32 v[124:125], v[94:95], v[124:125], v[126:127]
	v_pk_add_f32 v[120:121], v[74:75], v[76:77] neg_lo:[0,1] neg_hi:[0,1]
	v_pk_add_f32 v[74:75], v[74:75], v[76:77]
	v_mov_b32_dpp v126, v124 quad_perm:[2,3,0,1] row_mask:0xf bank_mask:0xf bound_ctrl:1
	v_mov_b32_dpp v127, v125 quad_perm:[2,3,0,1] row_mask:0xf bank_mask:0xf bound_ctrl:1
	v_pk_fma_f32 v[124:125], v[92:93], v[124:125], v[126:127]
	ds_swizzle_b32 v126, v124 offset:swizzle(SWAP,4)
	ds_swizzle_b32 v127, v125 offset:swizzle(SWAP,4)
	v_mov_b32_dpp v76, v74 quad_perm:[1,0,3,2] row_mask:0xf bank_mask:0xf bound_ctrl:1
	v_mov_b32_dpp v77, v75 quad_perm:[1,0,3,2] row_mask:0xf bank_mask:0xf bound_ctrl:1
	v_mov_b32_dpp v131, v129 quad_perm:[1,0,3,2] row_mask:0xf bank_mask:0xf bound_ctrl:1
	v_mov_b32_dpp v122, v120 quad_perm:[1,0,3,2] row_mask:0xf bank_mask:0xf bound_ctrl:1
	v_mov_b32_dpp v123, v121 quad_perm:[1,0,3,2] row_mask:0xf bank_mask:0xf bound_ctrl:1
	v_pk_fma_f32 v[74:75], v[94:95], v[74:75], v[76:77]
	v_pk_fma_f32 v[128:129], v[94:95], v[128:129], v[130:131]
	v_pk_fma_f32 v[120:121], v[94:95], v[120:121], v[122:123]
	v_mov_b32_dpp v76, v74 quad_perm:[2,3,0,1] row_mask:0xf bank_mask:0xf bound_ctrl:1
	v_mov_b32_dpp v77, v75 quad_perm:[2,3,0,1] row_mask:0xf bank_mask:0xf bound_ctrl:1
	v_mov_b32_dpp v130, v128 quad_perm:[2,3,0,1] row_mask:0xf bank_mask:0xf bound_ctrl:1
	v_mov_b32_dpp v131, v129 quad_perm:[2,3,0,1] row_mask:0xf bank_mask:0xf bound_ctrl:1
	v_mov_b32_dpp v122, v120 quad_perm:[2,3,0,1] row_mask:0xf bank_mask:0xf bound_ctrl:1
	v_mov_b32_dpp v123, v121 quad_perm:[2,3,0,1] row_mask:0xf bank_mask:0xf bound_ctrl:1
	v_pk_fma_f32 v[74:75], v[92:93], v[74:75], v[76:77]
	v_pk_fma_f32 v[128:129], v[92:93], v[128:129], v[130:131]
	v_pk_fma_f32 v[120:121], v[92:93], v[120:121], v[122:123]
	ds_swizzle_b32 v76, v74 offset:swizzle(SWAP,4)
	ds_swizzle_b32 v77, v75 offset:swizzle(SWAP,4)
	s_waitcnt lgkmcnt(2)
	v_pk_fma_f32 v[124:125], v[90:91], v[124:125], v[126:127]
	ds_swizzle_b32 v122, v120 offset:swizzle(SWAP,4)
	ds_swizzle_b32 v123, v121 offset:swizzle(SWAP,4)
	ds_swizzle_b32 v126, v128 offset:swizzle(SWAP,4)
	ds_swizzle_b32 v127, v129 offset:swizzle(SWAP,4)
	s_waitcnt lgkmcnt(4)
	v_pk_fma_f32 v[74:75], v[90:91], v[74:75], v[76:77]
	v_pk_mul_f32 v[124:125], v[124:125], s[40:41] op_sel_hi:[1,0]
	v_pk_mul_f32 v[74:75], v[74:75], s[40:41] op_sel_hi:[1,0]
	s_waitcnt lgkmcnt(2)
	v_pk_fma_f32 v[76:77], v[90:91], v[120:121], v[122:123]
	s_waitcnt lgkmcnt(0)
	v_pk_fma_f32 v[120:121], v[90:91], v[128:129], v[126:127]
	v_pk_mul_f32 v[76:77], v[76:77], s[40:41] op_sel_hi:[1,0]
	v_pk_mul_f32 v[120:121], v[120:121], s[40:41] op_sel_hi:[1,0]
	v_cvt_pk_bf16_f32 v74, v74, v75
	v_cvt_pk_bf16_f32 v76, v76, v77
	v_cvt_pk_bf16_f32 v77, v120, v121
	v_lshlrev_b32_e32 v119, 16, v74
	v_and_b32_e32 v120, 0xffff0000, v74
	v_cvt_pk_bf16_f32 v75, v124, v125
	v_and_b32_e32 v74, 0x7fffffff, v120
	v_max_f32_e64 v121, |v119|, |v119|
	v_max_f32_e32 v123, v121, v74
	v_lshlrev_b32_e32 v121, 16, v75
	v_and_b32_e32 v122, 0xffff0000, v75
	v_and_b32_e32 v74, 0x7fffffff, v122
	v_max_f32_e64 v75, |v121|, |v121|
	v_max_f32_e32 v124, v75, v74
	v_lshlrev_b32_e32 v74, 16, v76
	v_and_b32_e32 v75, 0xffff0000, v76
	v_lshlrev_b32_e32 v76, 16, v77
	v_and_b32_e32 v77, 0xffff0000, v77
	v_and_b32_e32 v125, 0x7fffffff, v77
	v_max_f32_e64 v126, |v76|, |v76|
	v_max_f32_e32 v125, v126, v125
	v_max3_f32 v125, |v74|, |v75|, v125
	v_max3_f32 v123, v123, v124, v125
	v_max3_f32 v140, v132, v133, v123
	s_nop 0
	v_lshlrev_b32_e32 v123, 16, v70
	v_and_b32_e32 v124, 0xffff0000, v70
	v_lshlrev_b32_e32 v125, 16, v71
	v_and_b32_e32 v126, 0xffff0000, v71
	v_lshlrev_b32_e32 v127, 16, v72
	v_and_b32_e32 v128, 0xffff0000, v72
	v_lshlrev_b32_e32 v129, 16, v73
	v_and_b32_e32 v130, 0xffff0000, v73
	v_add_f32_e32 v70, v123, v124
	v_sub_f32_e32 v71, v123, v124
	v_add_f32_e32 v72, v125, v126
	v_sub_f32_e32 v73, v125, v126
	v_add_f32_e32 v124, v127, v128
	v_sub_f32_e32 v125, v127, v128
	v_add_f32_e32 v126, v129, v130
	v_sub_f32_e32 v127, v129, v130
	v_pk_add_f32 v[128:129], v[70:71], v[72:73] neg_lo:[0,1] neg_hi:[0,1]
	v_pk_add_f32 v[130:131], v[124:125], v[126:127] neg_lo:[0,1] neg_hi:[0,1]
	v_pk_add_f32 v[70:71], v[70:71], v[72:73]
	v_pk_add_f32 v[132:133], v[128:129], v[130:131] neg_lo:[0,1] neg_hi:[0,1]
	v_pk_add_f32 v[128:129], v[128:129], v[130:131]
	v_pk_add_f32 v[72:73], v[124:125], v[126:127]
	v_mov_b32_dpp v134, v132 quad_perm:[1,0,3,2] row_mask:0xf bank_mask:0xf bound_ctrl:1
	v_mov_b32_dpp v130, v128 quad_perm:[1,0,3,2] row_mask:0xf bank_mask:0xf bound_ctrl:1
	v_mov_b32_dpp v131, v129 quad_perm:[1,0,3,2] row_mask:0xf bank_mask:0xf bound_ctrl:1
	v_pk_fma_f32 v[128:129], v[94:95], v[128:129], v[130:131]
	v_pk_add_f32 v[124:125], v[70:71], v[72:73] neg_lo:[0,1] neg_hi:[0,1]
	v_pk_add_f32 v[70:71], v[70:71], v[72:73]
	v_mov_b32_dpp v130, v128 quad_perm:[2,3,0,1] row_mask:0xf bank_mask:0xf bound_ctrl:1
	v_mov_b32_dpp v131, v129 quad_perm:[2,3,0,1] row_mask:0xf bank_mask:0xf bound_ctrl:1
	v_pk_fma_f32 v[128:129], v[92:93], v[128:129], v[130:131]
	ds_swizzle_b32 v130, v128 offset:swizzle(SWAP,4)
	ds_swizzle_b32 v131, v129 offset:swizzle(SWAP,4)
	v_mov_b32_dpp v72, v70 quad_perm:[1,0,3,2] row_mask:0xf bank_mask:0xf bound_ctrl:1
	v_mov_b32_dpp v73, v71 quad_perm:[1,0,3,2] row_mask:0xf bank_mask:0xf bound_ctrl:1
	v_mov_b32_dpp v135, v133 quad_perm:[1,0,3,2] row_mask:0xf bank_mask:0xf bound_ctrl:1
	v_mov_b32_dpp v126, v124 quad_perm:[1,0,3,2] row_mask:0xf bank_mask:0xf bound_ctrl:1
	v_mov_b32_dpp v127, v125 quad_perm:[1,0,3,2] row_mask:0xf bank_mask:0xf bound_ctrl:1
	v_pk_fma_f32 v[70:71], v[94:95], v[70:71], v[72:73]
	v_pk_fma_f32 v[132:133], v[94:95], v[132:133], v[134:135]
	v_pk_fma_f32 v[124:125], v[94:95], v[124:125], v[126:127]
	v_mov_b32_dpp v72, v70 quad_perm:[2,3,0,1] row_mask:0xf bank_mask:0xf bound_ctrl:1
	v_mov_b32_dpp v73, v71 quad_perm:[2,3,0,1] row_mask:0xf bank_mask:0xf bound_ctrl:1
	v_mov_b32_dpp v134, v132 quad_perm:[2,3,0,1] row_mask:0xf bank_mask:0xf bound_ctrl:1
	v_mov_b32_dpp v135, v133 quad_perm:[2,3,0,1] row_mask:0xf bank_mask:0xf bound_ctrl:1
	v_mov_b32_dpp v126, v124 quad_perm:[2,3,0,1] row_mask:0xf bank_mask:0xf bound_ctrl:1
	v_mov_b32_dpp v127, v125 quad_perm:[2,3,0,1] row_mask:0xf bank_mask:0xf bound_ctrl:1
	v_pk_fma_f32 v[70:71], v[92:93], v[70:71], v[72:73]
	v_pk_fma_f32 v[132:133], v[92:93], v[132:133], v[134:135]
	v_pk_fma_f32 v[124:125], v[92:93], v[124:125], v[126:127]
	ds_swizzle_b32 v72, v70 offset:swizzle(SWAP,4)
	ds_swizzle_b32 v73, v71 offset:swizzle(SWAP,4)
	s_waitcnt lgkmcnt(2)
	v_pk_fma_f32 v[128:129], v[90:91], v[128:129], v[130:131]
	ds_swizzle_b32 v126, v124 offset:swizzle(SWAP,4)
	ds_swizzle_b32 v127, v125 offset:swizzle(SWAP,4)
	ds_swizzle_b32 v130, v132 offset:swizzle(SWAP,4)
	ds_swizzle_b32 v131, v133 offset:swizzle(SWAP,4)
	s_waitcnt lgkmcnt(4)
	v_pk_fma_f32 v[70:71], v[90:91], v[70:71], v[72:73]
	v_pk_mul_f32 v[128:129], v[128:129], s[40:41] op_sel_hi:[1,0]
	v_pk_mul_f32 v[70:71], v[70:71], s[40:41] op_sel_hi:[1,0]
	s_waitcnt lgkmcnt(2)
	v_pk_fma_f32 v[72:73], v[90:91], v[124:125], v[126:127]
	s_waitcnt lgkmcnt(0)
	v_pk_fma_f32 v[124:125], v[90:91], v[132:133], v[130:131]
	v_pk_mul_f32 v[72:73], v[72:73], s[40:41] op_sel_hi:[1,0]
	v_pk_mul_f32 v[124:125], v[124:125], s[40:41] op_sel_hi:[1,0]
	v_cvt_pk_bf16_f32 v70, v70, v71
	v_cvt_pk_bf16_f32 v72, v72, v73
	v_cvt_pk_bf16_f32 v73, v124, v125
	v_lshlrev_b32_e32 v123, 16, v70
	v_and_b32_e32 v124, 0xffff0000, v70
	v_cvt_pk_bf16_f32 v71, v128, v129
	v_and_b32_e32 v70, 0x7fffffff, v124
	v_max_f32_e64 v125, |v123|, |v123|
	v_max_f32_e32 v127, v125, v70
	v_lshlrev_b32_e32 v125, 16, v71
	v_and_b32_e32 v126, 0xffff0000, v71
	v_and_b32_e32 v70, 0x7fffffff, v126
	v_max_f32_e64 v71, |v125|, |v125|
	v_max_f32_e32 v128, v71, v70
	v_lshlrev_b32_e32 v70, 16, v72
	v_and_b32_e32 v71, 0xffff0000, v72
	v_lshlrev_b32_e32 v72, 16, v73
	v_and_b32_e32 v73, 0xffff0000, v73
	v_and_b32_e32 v129, 0x7fffffff, v73
	v_max_f32_e64 v130, |v72|, |v72|
	v_max_f32_e32 v129, v130, v129
	v_max3_f32 v129, |v70|, |v71|, v129
	v_max3_f32 v141, v127, v128, v129
	s_nop 0
	v_lshlrev_b32_e32 v127, 16, v66
	v_and_b32_e32 v128, 0xffff0000, v66
	v_lshlrev_b32_e32 v129, 16, v67
	v_and_b32_e32 v130, 0xffff0000, v67
	v_lshlrev_b32_e32 v131, 16, v68
	v_and_b32_e32 v132, 0xffff0000, v68
	v_lshlrev_b32_e32 v133, 16, v69
	v_and_b32_e32 v134, 0xffff0000, v69
	v_add_f32_e32 v66, v127, v128
	v_sub_f32_e32 v67, v127, v128
	v_add_f32_e32 v68, v129, v130
	v_sub_f32_e32 v69, v129, v130
	v_add_f32_e32 v128, v131, v132
	v_sub_f32_e32 v129, v131, v132
	v_add_f32_e32 v130, v133, v134
	v_sub_f32_e32 v131, v133, v134
	v_pk_add_f32 v[132:133], v[66:67], v[68:69] neg_lo:[0,1] neg_hi:[0,1]
	v_pk_add_f32 v[134:135], v[128:129], v[130:131] neg_lo:[0,1] neg_hi:[0,1]
	v_pk_add_f32 v[66:67], v[66:67], v[68:69]
	v_pk_add_f32 v[136:137], v[132:133], v[134:135] neg_lo:[0,1] neg_hi:[0,1]
	v_pk_add_f32 v[132:133], v[132:133], v[134:135]
	v_pk_add_f32 v[68:69], v[128:129], v[130:131]
	v_mov_b32_dpp v138, v136 quad_perm:[1,0,3,2] row_mask:0xf bank_mask:0xf bound_ctrl:1
	v_mov_b32_dpp v134, v132 quad_perm:[1,0,3,2] row_mask:0xf bank_mask:0xf bound_ctrl:1
	v_mov_b32_dpp v135, v133 quad_perm:[1,0,3,2] row_mask:0xf bank_mask:0xf bound_ctrl:1
	v_pk_fma_f32 v[132:133], v[94:95], v[132:133], v[134:135]
	v_pk_add_f32 v[128:129], v[66:67], v[68:69] neg_lo:[0,1] neg_hi:[0,1]
	v_pk_add_f32 v[66:67], v[66:67], v[68:69]
	v_mov_b32_dpp v134, v132 quad_perm:[2,3,0,1] row_mask:0xf bank_mask:0xf bound_ctrl:1
	v_mov_b32_dpp v135, v133 quad_perm:[2,3,0,1] row_mask:0xf bank_mask:0xf bound_ctrl:1
	v_pk_fma_f32 v[132:133], v[92:93], v[132:133], v[134:135]
	ds_swizzle_b32 v134, v132 offset:swizzle(SWAP,4)
	ds_swizzle_b32 v135, v133 offset:swizzle(SWAP,4)
	v_mov_b32_dpp v68, v66 quad_perm:[1,0,3,2] row_mask:0xf bank_mask:0xf bound_ctrl:1
	v_mov_b32_dpp v69, v67 quad_perm:[1,0,3,2] row_mask:0xf bank_mask:0xf bound_ctrl:1
	v_mov_b32_dpp v139, v137 quad_perm:[1,0,3,2] row_mask:0xf bank_mask:0xf bound_ctrl:1
	v_mov_b32_dpp v130, v128 quad_perm:[1,0,3,2] row_mask:0xf bank_mask:0xf bound_ctrl:1
	v_mov_b32_dpp v131, v129 quad_perm:[1,0,3,2] row_mask:0xf bank_mask:0xf bound_ctrl:1
	v_pk_fma_f32 v[66:67], v[94:95], v[66:67], v[68:69]
	v_pk_fma_f32 v[136:137], v[94:95], v[136:137], v[138:139]
	v_pk_fma_f32 v[128:129], v[94:95], v[128:129], v[130:131]
	v_mov_b32_dpp v68, v66 quad_perm:[2,3,0,1] row_mask:0xf bank_mask:0xf bound_ctrl:1
	v_mov_b32_dpp v69, v67 quad_perm:[2,3,0,1] row_mask:0xf bank_mask:0xf bound_ctrl:1
	v_mov_b32_dpp v138, v136 quad_perm:[2,3,0,1] row_mask:0xf bank_mask:0xf bound_ctrl:1
	v_mov_b32_dpp v139, v137 quad_perm:[2,3,0,1] row_mask:0xf bank_mask:0xf bound_ctrl:1
	v_mov_b32_dpp v130, v128 quad_perm:[2,3,0,1] row_mask:0xf bank_mask:0xf bound_ctrl:1
	v_mov_b32_dpp v131, v129 quad_perm:[2,3,0,1] row_mask:0xf bank_mask:0xf bound_ctrl:1
	v_pk_fma_f32 v[66:67], v[92:93], v[66:67], v[68:69]
	v_pk_fma_f32 v[136:137], v[92:93], v[136:137], v[138:139]
	v_pk_fma_f32 v[128:129], v[92:93], v[128:129], v[130:131]
	ds_swizzle_b32 v68, v66 offset:swizzle(SWAP,4)
	ds_swizzle_b32 v69, v67 offset:swizzle(SWAP,4)
	s_waitcnt lgkmcnt(2)
	v_pk_fma_f32 v[132:133], v[90:91], v[132:133], v[134:135]
	ds_swizzle_b32 v130, v128 offset:swizzle(SWAP,4)
	ds_swizzle_b32 v131, v129 offset:swizzle(SWAP,4)
	ds_swizzle_b32 v134, v136 offset:swizzle(SWAP,4)
	ds_swizzle_b32 v135, v137 offset:swizzle(SWAP,4)
	s_waitcnt lgkmcnt(4)
	v_pk_fma_f32 v[66:67], v[90:91], v[66:67], v[68:69]
	v_pk_mul_f32 v[132:133], v[132:133], s[40:41] op_sel_hi:[1,0]
	v_pk_mul_f32 v[66:67], v[66:67], s[40:41] op_sel_hi:[1,0]
	s_waitcnt lgkmcnt(2)
	v_pk_fma_f32 v[68:69], v[90:91], v[128:129], v[130:131]
	s_waitcnt lgkmcnt(0)
	v_pk_fma_f32 v[128:129], v[90:91], v[136:137], v[134:135]
	v_pk_mul_f32 v[68:69], v[68:69], s[40:41] op_sel_hi:[1,0]
	v_pk_mul_f32 v[128:129], v[128:129], s[40:41] op_sel_hi:[1,0]
	v_cvt_pk_bf16_f32 v66, v66, v67
	v_cvt_pk_bf16_f32 v68, v68, v69
	v_cvt_pk_bf16_f32 v69, v128, v129
	v_lshlrev_b32_e32 v127, 16, v66
	v_and_b32_e32 v128, 0xffff0000, v66
	v_cvt_pk_bf16_f32 v67, v132, v133
	v_and_b32_e32 v66, 0x7fffffff, v128
	v_max_f32_e64 v129, |v127|, |v127|
	v_max_f32_e32 v131, v129, v66
	v_lshlrev_b32_e32 v129, 16, v67
	v_and_b32_e32 v130, 0xffff0000, v67
	v_and_b32_e32 v66, 0x7fffffff, v130
	v_max_f32_e64 v67, |v129|, |v129|
	v_max_f32_e32 v132, v67, v66
	v_lshlrev_b32_e32 v66, 16, v68
	v_and_b32_e32 v67, 0xffff0000, v68
	v_lshlrev_b32_e32 v68, 16, v69
	v_and_b32_e32 v69, 0xffff0000, v69
	v_and_b32_e32 v133, 0x7fffffff, v69
	v_max_f32_e64 v134, |v68|, |v68|
	v_max_f32_e32 v133, v134, v133
	v_max3_f32 v133, |v66|, |v67|, v133
	v_max3_f32 v131, v131, v132, v133
	v_max3_f32 v148, v140, v141, v131
	s_nop 0
	v_lshlrev_b32_e32 v131, 16, v62
	v_and_b32_e32 v132, 0xffff0000, v62
	v_lshlrev_b32_e32 v133, 16, v63
	v_and_b32_e32 v134, 0xffff0000, v63
	v_lshlrev_b32_e32 v135, 16, v64
	v_and_b32_e32 v136, 0xffff0000, v64
	v_lshlrev_b32_e32 v137, 16, v65
	v_and_b32_e32 v138, 0xffff0000, v65
	v_add_f32_e32 v62, v131, v132
	v_sub_f32_e32 v63, v131, v132
	v_add_f32_e32 v64, v133, v134
	v_sub_f32_e32 v65, v133, v134
	v_add_f32_e32 v132, v135, v136
	v_sub_f32_e32 v133, v135, v136
	v_add_f32_e32 v134, v137, v138
	v_sub_f32_e32 v135, v137, v138
	v_pk_add_f32 v[136:137], v[62:63], v[64:65] neg_lo:[0,1] neg_hi:[0,1]
	v_pk_add_f32 v[138:139], v[132:133], v[134:135] neg_lo:[0,1] neg_hi:[0,1]
	v_pk_add_f32 v[62:63], v[62:63], v[64:65]
	v_pk_add_f32 v[140:141], v[136:137], v[138:139] neg_lo:[0,1] neg_hi:[0,1]
	v_pk_add_f32 v[136:137], v[136:137], v[138:139]
	v_pk_add_f32 v[64:65], v[132:133], v[134:135]
	v_mov_b32_dpp v142, v140 quad_perm:[1,0,3,2] row_mask:0xf bank_mask:0xf bound_ctrl:1
	v_mov_b32_dpp v138, v136 quad_perm:[1,0,3,2] row_mask:0xf bank_mask:0xf bound_ctrl:1
	v_mov_b32_dpp v139, v137 quad_perm:[1,0,3,2] row_mask:0xf bank_mask:0xf bound_ctrl:1
	v_pk_fma_f32 v[136:137], v[94:95], v[136:137], v[138:139]
	v_pk_add_f32 v[132:133], v[62:63], v[64:65] neg_lo:[0,1] neg_hi:[0,1]
	v_pk_add_f32 v[62:63], v[62:63], v[64:65]
	v_mov_b32_dpp v138, v136 quad_perm:[2,3,0,1] row_mask:0xf bank_mask:0xf bound_ctrl:1
	v_mov_b32_dpp v139, v137 quad_perm:[2,3,0,1] row_mask:0xf bank_mask:0xf bound_ctrl:1
	v_pk_fma_f32 v[136:137], v[92:93], v[136:137], v[138:139]
	ds_swizzle_b32 v138, v136 offset:swizzle(SWAP,4)
	ds_swizzle_b32 v139, v137 offset:swizzle(SWAP,4)
	v_mov_b32_dpp v64, v62 quad_perm:[1,0,3,2] row_mask:0xf bank_mask:0xf bound_ctrl:1
	v_mov_b32_dpp v65, v63 quad_perm:[1,0,3,2] row_mask:0xf bank_mask:0xf bound_ctrl:1
	v_mov_b32_dpp v143, v141 quad_perm:[1,0,3,2] row_mask:0xf bank_mask:0xf bound_ctrl:1
	v_mov_b32_dpp v134, v132 quad_perm:[1,0,3,2] row_mask:0xf bank_mask:0xf bound_ctrl:1
	v_mov_b32_dpp v135, v133 quad_perm:[1,0,3,2] row_mask:0xf bank_mask:0xf bound_ctrl:1
	v_pk_fma_f32 v[62:63], v[94:95], v[62:63], v[64:65]
	v_pk_fma_f32 v[140:141], v[94:95], v[140:141], v[142:143]
	v_pk_fma_f32 v[132:133], v[94:95], v[132:133], v[134:135]
	v_mov_b32_dpp v64, v62 quad_perm:[2,3,0,1] row_mask:0xf bank_mask:0xf bound_ctrl:1
	v_mov_b32_dpp v65, v63 quad_perm:[2,3,0,1] row_mask:0xf bank_mask:0xf bound_ctrl:1
	v_mov_b32_dpp v142, v140 quad_perm:[2,3,0,1] row_mask:0xf bank_mask:0xf bound_ctrl:1
	v_mov_b32_dpp v143, v141 quad_perm:[2,3,0,1] row_mask:0xf bank_mask:0xf bound_ctrl:1
	v_mov_b32_dpp v134, v132 quad_perm:[2,3,0,1] row_mask:0xf bank_mask:0xf bound_ctrl:1
	v_mov_b32_dpp v135, v133 quad_perm:[2,3,0,1] row_mask:0xf bank_mask:0xf bound_ctrl:1
	v_pk_fma_f32 v[62:63], v[92:93], v[62:63], v[64:65]
	v_pk_fma_f32 v[140:141], v[92:93], v[140:141], v[142:143]
	v_pk_fma_f32 v[132:133], v[92:93], v[132:133], v[134:135]
	ds_swizzle_b32 v64, v62 offset:swizzle(SWAP,4)
	ds_swizzle_b32 v65, v63 offset:swizzle(SWAP,4)
	s_waitcnt lgkmcnt(2)
	v_pk_fma_f32 v[136:137], v[90:91], v[136:137], v[138:139]
	ds_swizzle_b32 v134, v132 offset:swizzle(SWAP,4)
	ds_swizzle_b32 v135, v133 offset:swizzle(SWAP,4)
	ds_swizzle_b32 v138, v140 offset:swizzle(SWAP,4)
	ds_swizzle_b32 v139, v141 offset:swizzle(SWAP,4)
	s_waitcnt lgkmcnt(4)
	v_pk_fma_f32 v[62:63], v[90:91], v[62:63], v[64:65]
	v_pk_mul_f32 v[136:137], v[136:137], s[40:41] op_sel_hi:[1,0]
	v_pk_mul_f32 v[62:63], v[62:63], s[40:41] op_sel_hi:[1,0]
	s_waitcnt lgkmcnt(2)
	v_pk_fma_f32 v[64:65], v[90:91], v[132:133], v[134:135]
	s_waitcnt lgkmcnt(0)
	v_pk_fma_f32 v[132:133], v[90:91], v[140:141], v[138:139]
	v_pk_mul_f32 v[64:65], v[64:65], s[40:41] op_sel_hi:[1,0]
	v_pk_mul_f32 v[132:133], v[132:133], s[40:41] op_sel_hi:[1,0]
	v_cvt_pk_bf16_f32 v62, v62, v63
	v_cvt_pk_bf16_f32 v64, v64, v65
	v_cvt_pk_bf16_f32 v65, v132, v133
	v_lshlrev_b32_e32 v131, 16, v62
	v_and_b32_e32 v132, 0xffff0000, v62
	v_cvt_pk_bf16_f32 v63, v136, v137
	v_and_b32_e32 v62, 0x7fffffff, v132
	v_max_f32_e64 v133, |v131|, |v131|
	v_max_f32_e32 v135, v133, v62
	v_lshlrev_b32_e32 v133, 16, v63
	v_and_b32_e32 v134, 0xffff0000, v63
	v_and_b32_e32 v62, 0x7fffffff, v134
	v_max_f32_e64 v63, |v133|, |v133|
	v_max_f32_e32 v136, v63, v62
	v_lshlrev_b32_e32 v62, 16, v64
	v_and_b32_e32 v63, 0xffff0000, v64
	v_lshlrev_b32_e32 v64, 16, v65
	v_and_b32_e32 v65, 0xffff0000, v65
	v_and_b32_e32 v137, 0x7fffffff, v65
	v_max_f32_e64 v138, |v64|, |v64|
	v_max_f32_e32 v137, v138, v137
	v_max3_f32 v137, |v62|, |v63|, v137
	v_max3_f32 v149, v135, v136, v137
	s_nop 0
	v_lshlrev_b32_e32 v135, 16, v58
	v_and_b32_e32 v136, 0xffff0000, v58
	v_lshlrev_b32_e32 v137, 16, v59
	v_and_b32_e32 v138, 0xffff0000, v59
	v_lshlrev_b32_e32 v139, 16, v60
	v_and_b32_e32 v140, 0xffff0000, v60
	v_lshlrev_b32_e32 v141, 16, v61
	v_and_b32_e32 v142, 0xffff0000, v61
	v_add_f32_e32 v58, v135, v136
	v_sub_f32_e32 v59, v135, v136
	v_add_f32_e32 v60, v137, v138
	v_sub_f32_e32 v61, v137, v138
	v_add_f32_e32 v136, v139, v140
	v_sub_f32_e32 v137, v139, v140
	v_add_f32_e32 v138, v141, v142
	v_sub_f32_e32 v139, v141, v142
	v_pk_add_f32 v[140:141], v[58:59], v[60:61] neg_lo:[0,1] neg_hi:[0,1]
	v_pk_add_f32 v[142:143], v[136:137], v[138:139] neg_lo:[0,1] neg_hi:[0,1]
	v_pk_add_f32 v[58:59], v[58:59], v[60:61]
	v_pk_add_f32 v[144:145], v[140:141], v[142:143] neg_lo:[0,1] neg_hi:[0,1]
	v_pk_add_f32 v[140:141], v[140:141], v[142:143]
	v_pk_add_f32 v[60:61], v[136:137], v[138:139]
	v_mov_b32_dpp v146, v144 quad_perm:[1,0,3,2] row_mask:0xf bank_mask:0xf bound_ctrl:1
	v_mov_b32_dpp v142, v140 quad_perm:[1,0,3,2] row_mask:0xf bank_mask:0xf bound_ctrl:1
	v_mov_b32_dpp v143, v141 quad_perm:[1,0,3,2] row_mask:0xf bank_mask:0xf bound_ctrl:1
	v_pk_fma_f32 v[140:141], v[94:95], v[140:141], v[142:143]
	v_pk_add_f32 v[136:137], v[58:59], v[60:61] neg_lo:[0,1] neg_hi:[0,1]
	v_pk_add_f32 v[58:59], v[58:59], v[60:61]
	v_mov_b32_dpp v142, v140 quad_perm:[2,3,0,1] row_mask:0xf bank_mask:0xf bound_ctrl:1
	v_mov_b32_dpp v143, v141 quad_perm:[2,3,0,1] row_mask:0xf bank_mask:0xf bound_ctrl:1
	v_pk_fma_f32 v[140:141], v[92:93], v[140:141], v[142:143]
	ds_swizzle_b32 v142, v140 offset:swizzle(SWAP,4)
	ds_swizzle_b32 v143, v141 offset:swizzle(SWAP,4)
	v_mov_b32_dpp v60, v58 quad_perm:[1,0,3,2] row_mask:0xf bank_mask:0xf bound_ctrl:1
	v_mov_b32_dpp v61, v59 quad_perm:[1,0,3,2] row_mask:0xf bank_mask:0xf bound_ctrl:1
	v_mov_b32_dpp v147, v145 quad_perm:[1,0,3,2] row_mask:0xf bank_mask:0xf bound_ctrl:1
	v_mov_b32_dpp v138, v136 quad_perm:[1,0,3,2] row_mask:0xf bank_mask:0xf bound_ctrl:1
	v_mov_b32_dpp v139, v137 quad_perm:[1,0,3,2] row_mask:0xf bank_mask:0xf bound_ctrl:1
	v_pk_fma_f32 v[58:59], v[94:95], v[58:59], v[60:61]
	v_pk_fma_f32 v[144:145], v[94:95], v[144:145], v[146:147]
	v_pk_fma_f32 v[136:137], v[94:95], v[136:137], v[138:139]
	v_mov_b32_dpp v60, v58 quad_perm:[2,3,0,1] row_mask:0xf bank_mask:0xf bound_ctrl:1
	v_mov_b32_dpp v61, v59 quad_perm:[2,3,0,1] row_mask:0xf bank_mask:0xf bound_ctrl:1
	v_mov_b32_dpp v146, v144 quad_perm:[2,3,0,1] row_mask:0xf bank_mask:0xf bound_ctrl:1
	v_mov_b32_dpp v147, v145 quad_perm:[2,3,0,1] row_mask:0xf bank_mask:0xf bound_ctrl:1
	v_mov_b32_dpp v138, v136 quad_perm:[2,3,0,1] row_mask:0xf bank_mask:0xf bound_ctrl:1
	v_mov_b32_dpp v139, v137 quad_perm:[2,3,0,1] row_mask:0xf bank_mask:0xf bound_ctrl:1
	v_pk_fma_f32 v[58:59], v[92:93], v[58:59], v[60:61]
	v_pk_fma_f32 v[144:145], v[92:93], v[144:145], v[146:147]
	v_pk_fma_f32 v[136:137], v[92:93], v[136:137], v[138:139]
	ds_swizzle_b32 v60, v58 offset:swizzle(SWAP,4)
	ds_swizzle_b32 v61, v59 offset:swizzle(SWAP,4)
	s_waitcnt lgkmcnt(2)
	v_pk_fma_f32 v[140:141], v[90:91], v[140:141], v[142:143]
	ds_swizzle_b32 v138, v136 offset:swizzle(SWAP,4)
	ds_swizzle_b32 v139, v137 offset:swizzle(SWAP,4)
	ds_swizzle_b32 v142, v144 offset:swizzle(SWAP,4)
	ds_swizzle_b32 v143, v145 offset:swizzle(SWAP,4)
	s_waitcnt lgkmcnt(4)
	v_pk_fma_f32 v[58:59], v[90:91], v[58:59], v[60:61]
	v_pk_mul_f32 v[140:141], v[140:141], s[40:41] op_sel_hi:[1,0]
	v_pk_mul_f32 v[58:59], v[58:59], s[40:41] op_sel_hi:[1,0]
	s_waitcnt lgkmcnt(2)
	v_pk_fma_f32 v[60:61], v[90:91], v[136:137], v[138:139]
	s_waitcnt lgkmcnt(0)
	v_pk_fma_f32 v[136:137], v[90:91], v[144:145], v[142:143]
	v_pk_mul_f32 v[60:61], v[60:61], s[40:41] op_sel_hi:[1,0]
	v_pk_mul_f32 v[136:137], v[136:137], s[40:41] op_sel_hi:[1,0]
	v_cvt_pk_bf16_f32 v58, v58, v59
	v_cvt_pk_bf16_f32 v60, v60, v61
	v_cvt_pk_bf16_f32 v61, v136, v137
	v_lshlrev_b32_e32 v135, 16, v58
	v_and_b32_e32 v136, 0xffff0000, v58
	v_cvt_pk_bf16_f32 v59, v140, v141
	v_and_b32_e32 v58, 0x7fffffff, v136
	v_max_f32_e64 v137, |v135|, |v135|
	v_max_f32_e32 v139, v137, v58
	v_lshlrev_b32_e32 v137, 16, v59
	v_and_b32_e32 v138, 0xffff0000, v59
	v_and_b32_e32 v58, 0x7fffffff, v138
	v_max_f32_e64 v59, |v137|, |v137|
	v_max_f32_e32 v140, v59, v58
	v_lshlrev_b32_e32 v58, 16, v60
	v_and_b32_e32 v59, 0xffff0000, v60
	v_lshlrev_b32_e32 v60, 16, v61
	v_and_b32_e32 v61, 0xffff0000, v61
	v_and_b32_e32 v141, 0x7fffffff, v61
	v_max_f32_e64 v142, |v60|, |v60|
	v_max_f32_e32 v141, v142, v141
	v_max3_f32 v141, |v58|, |v59|, v141
	v_max3_f32 v139, v139, v140, v141
	v_max3_f32 v156, v148, v149, v139
	s_nop 0
	v_lshlrev_b32_e32 v139, 16, v54
	v_and_b32_e32 v140, 0xffff0000, v54
	v_lshlrev_b32_e32 v141, 16, v55
	v_and_b32_e32 v142, 0xffff0000, v55
	v_lshlrev_b32_e32 v143, 16, v56
	v_and_b32_e32 v144, 0xffff0000, v56
	v_lshlrev_b32_e32 v145, 16, v57
	v_and_b32_e32 v146, 0xffff0000, v57
	v_add_f32_e32 v54, v139, v140
	v_sub_f32_e32 v55, v139, v140
	v_add_f32_e32 v56, v141, v142
	v_sub_f32_e32 v57, v141, v142
	v_add_f32_e32 v140, v143, v144
	v_sub_f32_e32 v141, v143, v144
	v_add_f32_e32 v142, v145, v146
	v_sub_f32_e32 v143, v145, v146
	v_pk_add_f32 v[144:145], v[54:55], v[56:57] neg_lo:[0,1] neg_hi:[0,1]
	v_pk_add_f32 v[146:147], v[140:141], v[142:143] neg_lo:[0,1] neg_hi:[0,1]
	v_pk_add_f32 v[54:55], v[54:55], v[56:57]
	v_pk_add_f32 v[148:149], v[144:145], v[146:147] neg_lo:[0,1] neg_hi:[0,1]
	v_pk_add_f32 v[144:145], v[144:145], v[146:147]
	v_pk_add_f32 v[56:57], v[140:141], v[142:143]
	v_mov_b32_dpp v150, v148 quad_perm:[1,0,3,2] row_mask:0xf bank_mask:0xf bound_ctrl:1
	v_mov_b32_dpp v146, v144 quad_perm:[1,0,3,2] row_mask:0xf bank_mask:0xf bound_ctrl:1
	v_mov_b32_dpp v147, v145 quad_perm:[1,0,3,2] row_mask:0xf bank_mask:0xf bound_ctrl:1
	v_pk_fma_f32 v[144:145], v[94:95], v[144:145], v[146:147]
	v_pk_add_f32 v[140:141], v[54:55], v[56:57] neg_lo:[0,1] neg_hi:[0,1]
	v_pk_add_f32 v[54:55], v[54:55], v[56:57]
	v_mov_b32_dpp v146, v144 quad_perm:[2,3,0,1] row_mask:0xf bank_mask:0xf bound_ctrl:1
	v_mov_b32_dpp v147, v145 quad_perm:[2,3,0,1] row_mask:0xf bank_mask:0xf bound_ctrl:1
	v_pk_fma_f32 v[144:145], v[92:93], v[144:145], v[146:147]
	ds_swizzle_b32 v146, v144 offset:swizzle(SWAP,4)
	ds_swizzle_b32 v147, v145 offset:swizzle(SWAP,4)
	v_mov_b32_dpp v56, v54 quad_perm:[1,0,3,2] row_mask:0xf bank_mask:0xf bound_ctrl:1
	v_mov_b32_dpp v57, v55 quad_perm:[1,0,3,2] row_mask:0xf bank_mask:0xf bound_ctrl:1
	v_mov_b32_dpp v151, v149 quad_perm:[1,0,3,2] row_mask:0xf bank_mask:0xf bound_ctrl:1
	v_mov_b32_dpp v142, v140 quad_perm:[1,0,3,2] row_mask:0xf bank_mask:0xf bound_ctrl:1
	v_mov_b32_dpp v143, v141 quad_perm:[1,0,3,2] row_mask:0xf bank_mask:0xf bound_ctrl:1
	v_pk_fma_f32 v[54:55], v[94:95], v[54:55], v[56:57]
	v_pk_fma_f32 v[148:149], v[94:95], v[148:149], v[150:151]
	v_pk_fma_f32 v[140:141], v[94:95], v[140:141], v[142:143]
	v_mov_b32_dpp v56, v54 quad_perm:[2,3,0,1] row_mask:0xf bank_mask:0xf bound_ctrl:1
	v_mov_b32_dpp v57, v55 quad_perm:[2,3,0,1] row_mask:0xf bank_mask:0xf bound_ctrl:1
	v_mov_b32_dpp v150, v148 quad_perm:[2,3,0,1] row_mask:0xf bank_mask:0xf bound_ctrl:1
	v_mov_b32_dpp v151, v149 quad_perm:[2,3,0,1] row_mask:0xf bank_mask:0xf bound_ctrl:1
	v_mov_b32_dpp v142, v140 quad_perm:[2,3,0,1] row_mask:0xf bank_mask:0xf bound_ctrl:1
	v_mov_b32_dpp v143, v141 quad_perm:[2,3,0,1] row_mask:0xf bank_mask:0xf bound_ctrl:1
	v_pk_fma_f32 v[54:55], v[92:93], v[54:55], v[56:57]
	v_pk_fma_f32 v[148:149], v[92:93], v[148:149], v[150:151]
	v_pk_fma_f32 v[140:141], v[92:93], v[140:141], v[142:143]
	ds_swizzle_b32 v56, v54 offset:swizzle(SWAP,4)
	ds_swizzle_b32 v57, v55 offset:swizzle(SWAP,4)
	s_waitcnt lgkmcnt(2)
	v_pk_fma_f32 v[144:145], v[90:91], v[144:145], v[146:147]
	ds_swizzle_b32 v142, v140 offset:swizzle(SWAP,4)
	ds_swizzle_b32 v143, v141 offset:swizzle(SWAP,4)
	ds_swizzle_b32 v146, v148 offset:swizzle(SWAP,4)
	ds_swizzle_b32 v147, v149 offset:swizzle(SWAP,4)
	s_waitcnt lgkmcnt(4)
	v_pk_fma_f32 v[54:55], v[90:91], v[54:55], v[56:57]
	v_pk_mul_f32 v[144:145], v[144:145], s[40:41] op_sel_hi:[1,0]
	v_pk_mul_f32 v[54:55], v[54:55], s[40:41] op_sel_hi:[1,0]
	s_waitcnt lgkmcnt(2)
	v_pk_fma_f32 v[56:57], v[90:91], v[140:141], v[142:143]
	s_waitcnt lgkmcnt(0)
	v_pk_fma_f32 v[140:141], v[90:91], v[148:149], v[146:147]
	v_pk_mul_f32 v[56:57], v[56:57], s[40:41] op_sel_hi:[1,0]
	v_pk_mul_f32 v[140:141], v[140:141], s[40:41] op_sel_hi:[1,0]
	v_cvt_pk_bf16_f32 v54, v54, v55
	v_cvt_pk_bf16_f32 v56, v56, v57
	v_cvt_pk_bf16_f32 v57, v140, v141
	v_lshlrev_b32_e32 v139, 16, v54
	v_and_b32_e32 v140, 0xffff0000, v54
	v_cvt_pk_bf16_f32 v55, v144, v145
	v_and_b32_e32 v54, 0x7fffffff, v140
	v_max_f32_e64 v141, |v139|, |v139|
	v_max_f32_e32 v143, v141, v54
	v_lshlrev_b32_e32 v141, 16, v55
	v_and_b32_e32 v142, 0xffff0000, v55
	v_and_b32_e32 v54, 0x7fffffff, v142
	v_max_f32_e64 v55, |v141|, |v141|
	v_max_f32_e32 v144, v55, v54
	v_lshlrev_b32_e32 v54, 16, v56
	v_and_b32_e32 v55, 0xffff0000, v56
	v_lshlrev_b32_e32 v56, 16, v57
	v_and_b32_e32 v57, 0xffff0000, v57
	v_and_b32_e32 v145, 0x7fffffff, v57
	v_max_f32_e64 v146, |v56|, |v56|
	v_max_f32_e32 v145, v146, v145
	v_max3_f32 v145, |v54|, |v55|, v145
	v_max3_f32 v157, v143, v144, v145
	s_nop 0
	v_lshlrev_b32_e32 v143, 16, v50
	v_and_b32_e32 v144, 0xffff0000, v50
	v_lshlrev_b32_e32 v145, 16, v51
	v_and_b32_e32 v146, 0xffff0000, v51
	v_lshlrev_b32_e32 v147, 16, v52
	v_and_b32_e32 v148, 0xffff0000, v52
	v_lshlrev_b32_e32 v149, 16, v53
	v_and_b32_e32 v150, 0xffff0000, v53
	v_add_f32_e32 v50, v143, v144
	v_sub_f32_e32 v51, v143, v144
	v_add_f32_e32 v52, v145, v146
	v_sub_f32_e32 v53, v145, v146
	v_add_f32_e32 v144, v147, v148
	v_sub_f32_e32 v145, v147, v148
	v_add_f32_e32 v146, v149, v150
	v_sub_f32_e32 v147, v149, v150
	v_pk_add_f32 v[148:149], v[50:51], v[52:53] neg_lo:[0,1] neg_hi:[0,1]
	v_pk_add_f32 v[150:151], v[144:145], v[146:147] neg_lo:[0,1] neg_hi:[0,1]
	v_pk_add_f32 v[50:51], v[50:51], v[52:53]
	v_pk_add_f32 v[152:153], v[148:149], v[150:151] neg_lo:[0,1] neg_hi:[0,1]
	v_pk_add_f32 v[148:149], v[148:149], v[150:151]
	v_pk_add_f32 v[52:53], v[144:145], v[146:147]
	v_mov_b32_dpp v154, v152 quad_perm:[1,0,3,2] row_mask:0xf bank_mask:0xf bound_ctrl:1
	v_mov_b32_dpp v150, v148 quad_perm:[1,0,3,2] row_mask:0xf bank_mask:0xf bound_ctrl:1
	v_mov_b32_dpp v151, v149 quad_perm:[1,0,3,2] row_mask:0xf bank_mask:0xf bound_ctrl:1
	v_pk_fma_f32 v[148:149], v[94:95], v[148:149], v[150:151]
	v_pk_add_f32 v[144:145], v[50:51], v[52:53] neg_lo:[0,1] neg_hi:[0,1]
	v_pk_add_f32 v[50:51], v[50:51], v[52:53]
	v_mov_b32_dpp v150, v148 quad_perm:[2,3,0,1] row_mask:0xf bank_mask:0xf bound_ctrl:1
	v_mov_b32_dpp v151, v149 quad_perm:[2,3,0,1] row_mask:0xf bank_mask:0xf bound_ctrl:1
	v_pk_fma_f32 v[148:149], v[92:93], v[148:149], v[150:151]
	ds_swizzle_b32 v150, v148 offset:swizzle(SWAP,4)
	ds_swizzle_b32 v151, v149 offset:swizzle(SWAP,4)
	v_mov_b32_dpp v52, v50 quad_perm:[1,0,3,2] row_mask:0xf bank_mask:0xf bound_ctrl:1
	v_mov_b32_dpp v53, v51 quad_perm:[1,0,3,2] row_mask:0xf bank_mask:0xf bound_ctrl:1
	v_mov_b32_dpp v155, v153 quad_perm:[1,0,3,2] row_mask:0xf bank_mask:0xf bound_ctrl:1
	v_mov_b32_dpp v146, v144 quad_perm:[1,0,3,2] row_mask:0xf bank_mask:0xf bound_ctrl:1
	v_mov_b32_dpp v147, v145 quad_perm:[1,0,3,2] row_mask:0xf bank_mask:0xf bound_ctrl:1
	v_pk_fma_f32 v[50:51], v[94:95], v[50:51], v[52:53]
	v_pk_fma_f32 v[152:153], v[94:95], v[152:153], v[154:155]
	v_pk_fma_f32 v[144:145], v[94:95], v[144:145], v[146:147]
	v_mov_b32_dpp v52, v50 quad_perm:[2,3,0,1] row_mask:0xf bank_mask:0xf bound_ctrl:1
	v_mov_b32_dpp v53, v51 quad_perm:[2,3,0,1] row_mask:0xf bank_mask:0xf bound_ctrl:1
	v_mov_b32_dpp v154, v152 quad_perm:[2,3,0,1] row_mask:0xf bank_mask:0xf bound_ctrl:1
	v_mov_b32_dpp v155, v153 quad_perm:[2,3,0,1] row_mask:0xf bank_mask:0xf bound_ctrl:1
	v_mov_b32_dpp v146, v144 quad_perm:[2,3,0,1] row_mask:0xf bank_mask:0xf bound_ctrl:1
	v_mov_b32_dpp v147, v145 quad_perm:[2,3,0,1] row_mask:0xf bank_mask:0xf bound_ctrl:1
	v_pk_fma_f32 v[50:51], v[92:93], v[50:51], v[52:53]
	v_pk_fma_f32 v[152:153], v[92:93], v[152:153], v[154:155]
	v_pk_fma_f32 v[144:145], v[92:93], v[144:145], v[146:147]
	ds_swizzle_b32 v52, v50 offset:swizzle(SWAP,4)
	ds_swizzle_b32 v53, v51 offset:swizzle(SWAP,4)
	s_waitcnt lgkmcnt(2)
	v_pk_fma_f32 v[148:149], v[90:91], v[148:149], v[150:151]
	ds_swizzle_b32 v146, v144 offset:swizzle(SWAP,4)
	ds_swizzle_b32 v147, v145 offset:swizzle(SWAP,4)
	ds_swizzle_b32 v150, v152 offset:swizzle(SWAP,4)
	ds_swizzle_b32 v151, v153 offset:swizzle(SWAP,4)
	s_waitcnt lgkmcnt(4)
	v_pk_fma_f32 v[50:51], v[90:91], v[50:51], v[52:53]
	v_pk_mul_f32 v[148:149], v[148:149], s[40:41] op_sel_hi:[1,0]
	v_pk_mul_f32 v[50:51], v[50:51], s[40:41] op_sel_hi:[1,0]
	s_waitcnt lgkmcnt(2)
	v_pk_fma_f32 v[52:53], v[90:91], v[144:145], v[146:147]
	s_waitcnt lgkmcnt(0)
	v_pk_fma_f32 v[144:145], v[90:91], v[152:153], v[150:151]
	v_pk_mul_f32 v[52:53], v[52:53], s[40:41] op_sel_hi:[1,0]
	v_pk_mul_f32 v[144:145], v[144:145], s[40:41] op_sel_hi:[1,0]
	v_cvt_pk_bf16_f32 v50, v50, v51
	v_cvt_pk_bf16_f32 v52, v52, v53
	v_cvt_pk_bf16_f32 v53, v144, v145
	v_lshlrev_b32_e32 v143, 16, v50
	v_and_b32_e32 v144, 0xffff0000, v50
	v_cvt_pk_bf16_f32 v51, v148, v149
	v_and_b32_e32 v50, 0x7fffffff, v144
	v_max_f32_e64 v145, |v143|, |v143|
	v_max_f32_e32 v147, v145, v50
	v_lshlrev_b32_e32 v145, 16, v51
	v_and_b32_e32 v146, 0xffff0000, v51
	v_and_b32_e32 v50, 0x7fffffff, v146
	v_max_f32_e64 v51, |v145|, |v145|
	v_max_f32_e32 v148, v51, v50
	v_lshlrev_b32_e32 v50, 16, v52
	v_and_b32_e32 v51, 0xffff0000, v52
	v_lshlrev_b32_e32 v52, 16, v53
	v_and_b32_e32 v53, 0xffff0000, v53
	v_and_b32_e32 v149, 0x7fffffff, v53
	v_max_f32_e64 v150, |v52|, |v52|
	v_max_f32_e32 v149, v150, v149
	v_max3_f32 v149, |v50|, |v51|, v149
	v_max3_f32 v147, v147, v148, v149
	v_max3_f32 v164, v156, v157, v147
	s_nop 0
	v_lshlrev_b32_e32 v147, 16, v46
	v_and_b32_e32 v148, 0xffff0000, v46
	v_lshlrev_b32_e32 v149, 16, v47
	v_and_b32_e32 v150, 0xffff0000, v47
	v_lshlrev_b32_e32 v151, 16, v48
	v_and_b32_e32 v152, 0xffff0000, v48
	v_lshlrev_b32_e32 v153, 16, v49
	v_and_b32_e32 v154, 0xffff0000, v49
	v_add_f32_e32 v46, v147, v148
	v_sub_f32_e32 v47, v147, v148
	v_add_f32_e32 v48, v149, v150
	v_sub_f32_e32 v49, v149, v150
	v_add_f32_e32 v148, v151, v152
	v_sub_f32_e32 v149, v151, v152
	v_add_f32_e32 v150, v153, v154
	v_sub_f32_e32 v151, v153, v154
	v_pk_add_f32 v[152:153], v[46:47], v[48:49] neg_lo:[0,1] neg_hi:[0,1]
	v_pk_add_f32 v[154:155], v[148:149], v[150:151] neg_lo:[0,1] neg_hi:[0,1]
	v_pk_add_f32 v[46:47], v[46:47], v[48:49]
	v_pk_add_f32 v[156:157], v[152:153], v[154:155] neg_lo:[0,1] neg_hi:[0,1]
	v_pk_add_f32 v[152:153], v[152:153], v[154:155]
	v_pk_add_f32 v[48:49], v[148:149], v[150:151]
	v_mov_b32_dpp v158, v156 quad_perm:[1,0,3,2] row_mask:0xf bank_mask:0xf bound_ctrl:1
	v_mov_b32_dpp v154, v152 quad_perm:[1,0,3,2] row_mask:0xf bank_mask:0xf bound_ctrl:1
	v_mov_b32_dpp v155, v153 quad_perm:[1,0,3,2] row_mask:0xf bank_mask:0xf bound_ctrl:1
	v_pk_fma_f32 v[152:153], v[94:95], v[152:153], v[154:155]
	v_pk_add_f32 v[148:149], v[46:47], v[48:49] neg_lo:[0,1] neg_hi:[0,1]
	v_pk_add_f32 v[46:47], v[46:47], v[48:49]
	v_mov_b32_dpp v154, v152 quad_perm:[2,3,0,1] row_mask:0xf bank_mask:0xf bound_ctrl:1
	v_mov_b32_dpp v155, v153 quad_perm:[2,3,0,1] row_mask:0xf bank_mask:0xf bound_ctrl:1
	v_pk_fma_f32 v[152:153], v[92:93], v[152:153], v[154:155]
	ds_swizzle_b32 v154, v152 offset:swizzle(SWAP,4)
	ds_swizzle_b32 v155, v153 offset:swizzle(SWAP,4)
	v_mov_b32_dpp v48, v46 quad_perm:[1,0,3,2] row_mask:0xf bank_mask:0xf bound_ctrl:1
	v_mov_b32_dpp v49, v47 quad_perm:[1,0,3,2] row_mask:0xf bank_mask:0xf bound_ctrl:1
	v_mov_b32_dpp v159, v157 quad_perm:[1,0,3,2] row_mask:0xf bank_mask:0xf bound_ctrl:1
	v_mov_b32_dpp v150, v148 quad_perm:[1,0,3,2] row_mask:0xf bank_mask:0xf bound_ctrl:1
	v_mov_b32_dpp v151, v149 quad_perm:[1,0,3,2] row_mask:0xf bank_mask:0xf bound_ctrl:1
	v_pk_fma_f32 v[46:47], v[94:95], v[46:47], v[48:49]
	v_pk_fma_f32 v[156:157], v[94:95], v[156:157], v[158:159]
	v_pk_fma_f32 v[148:149], v[94:95], v[148:149], v[150:151]
	v_mov_b32_dpp v48, v46 quad_perm:[2,3,0,1] row_mask:0xf bank_mask:0xf bound_ctrl:1
	v_mov_b32_dpp v49, v47 quad_perm:[2,3,0,1] row_mask:0xf bank_mask:0xf bound_ctrl:1
	v_mov_b32_dpp v158, v156 quad_perm:[2,3,0,1] row_mask:0xf bank_mask:0xf bound_ctrl:1
	v_mov_b32_dpp v159, v157 quad_perm:[2,3,0,1] row_mask:0xf bank_mask:0xf bound_ctrl:1
	v_mov_b32_dpp v150, v148 quad_perm:[2,3,0,1] row_mask:0xf bank_mask:0xf bound_ctrl:1
	v_mov_b32_dpp v151, v149 quad_perm:[2,3,0,1] row_mask:0xf bank_mask:0xf bound_ctrl:1
	v_pk_fma_f32 v[46:47], v[92:93], v[46:47], v[48:49]
	v_pk_fma_f32 v[156:157], v[92:93], v[156:157], v[158:159]
	v_pk_fma_f32 v[148:149], v[92:93], v[148:149], v[150:151]
	ds_swizzle_b32 v48, v46 offset:swizzle(SWAP,4)
	ds_swizzle_b32 v49, v47 offset:swizzle(SWAP,4)
	s_waitcnt lgkmcnt(2)
	v_pk_fma_f32 v[152:153], v[90:91], v[152:153], v[154:155]
	ds_swizzle_b32 v150, v148 offset:swizzle(SWAP,4)
	ds_swizzle_b32 v151, v149 offset:swizzle(SWAP,4)
	ds_swizzle_b32 v154, v156 offset:swizzle(SWAP,4)
	ds_swizzle_b32 v155, v157 offset:swizzle(SWAP,4)
	s_waitcnt lgkmcnt(4)
	v_pk_fma_f32 v[46:47], v[90:91], v[46:47], v[48:49]
	v_pk_mul_f32 v[152:153], v[152:153], s[40:41] op_sel_hi:[1,0]
	v_pk_mul_f32 v[46:47], v[46:47], s[40:41] op_sel_hi:[1,0]
	s_waitcnt lgkmcnt(2)
	v_pk_fma_f32 v[48:49], v[90:91], v[148:149], v[150:151]
	s_waitcnt lgkmcnt(0)
	v_pk_fma_f32 v[148:149], v[90:91], v[156:157], v[154:155]
	v_pk_mul_f32 v[48:49], v[48:49], s[40:41] op_sel_hi:[1,0]
	v_pk_mul_f32 v[148:149], v[148:149], s[40:41] op_sel_hi:[1,0]
	v_cvt_pk_bf16_f32 v46, v46, v47
	v_cvt_pk_bf16_f32 v48, v48, v49
	v_cvt_pk_bf16_f32 v49, v148, v149
	v_lshlrev_b32_e32 v147, 16, v46
	v_and_b32_e32 v148, 0xffff0000, v46
	v_cvt_pk_bf16_f32 v47, v152, v153
	v_and_b32_e32 v46, 0x7fffffff, v148
	v_max_f32_e64 v149, |v147|, |v147|
	v_max_f32_e32 v151, v149, v46
	v_lshlrev_b32_e32 v149, 16, v47
	v_and_b32_e32 v150, 0xffff0000, v47
	v_and_b32_e32 v46, 0x7fffffff, v150
	v_max_f32_e64 v47, |v149|, |v149|
	v_max_f32_e32 v152, v47, v46
	v_lshlrev_b32_e32 v46, 16, v48
	v_and_b32_e32 v47, 0xffff0000, v48
	v_lshlrev_b32_e32 v48, 16, v49
	v_and_b32_e32 v49, 0xffff0000, v49
	v_and_b32_e32 v153, 0x7fffffff, v49
	v_max_f32_e64 v154, |v48|, |v48|
	v_max_f32_e32 v153, v154, v153
	v_max3_f32 v153, |v46|, |v47|, v153
	v_max3_f32 v165, v151, v152, v153
	s_waitcnt vmcnt(9)
	v_lshlrev_b32_e32 v151, 16, v42
	v_and_b32_e32 v152, 0xffff0000, v42
	v_lshlrev_b32_e32 v153, 16, v43
	v_and_b32_e32 v154, 0xffff0000, v43
	v_lshlrev_b32_e32 v155, 16, v44
	v_and_b32_e32 v156, 0xffff0000, v44
	v_lshlrev_b32_e32 v157, 16, v45
	v_and_b32_e32 v158, 0xffff0000, v45
	v_add_f32_e32 v42, v151, v152
	v_sub_f32_e32 v43, v151, v152
	v_add_f32_e32 v44, v153, v154
	v_sub_f32_e32 v45, v153, v154
	v_add_f32_e32 v152, v155, v156
	v_sub_f32_e32 v153, v155, v156
	v_add_f32_e32 v154, v157, v158
	v_sub_f32_e32 v155, v157, v158
	v_pk_add_f32 v[156:157], v[42:43], v[44:45] neg_lo:[0,1] neg_hi:[0,1]
	v_pk_add_f32 v[158:159], v[152:153], v[154:155] neg_lo:[0,1] neg_hi:[0,1]
	v_pk_add_f32 v[42:43], v[42:43], v[44:45]
	v_pk_add_f32 v[160:161], v[156:157], v[158:159] neg_lo:[0,1] neg_hi:[0,1]
	v_pk_add_f32 v[156:157], v[156:157], v[158:159]
	v_pk_add_f32 v[44:45], v[152:153], v[154:155]
	v_mov_b32_dpp v162, v160 quad_perm:[1,0,3,2] row_mask:0xf bank_mask:0xf bound_ctrl:1
	v_mov_b32_dpp v158, v156 quad_perm:[1,0,3,2] row_mask:0xf bank_mask:0xf bound_ctrl:1
	v_mov_b32_dpp v159, v157 quad_perm:[1,0,3,2] row_mask:0xf bank_mask:0xf bound_ctrl:1
	v_pk_fma_f32 v[156:157], v[94:95], v[156:157], v[158:159]
	v_pk_add_f32 v[152:153], v[42:43], v[44:45] neg_lo:[0,1] neg_hi:[0,1]
	v_pk_add_f32 v[42:43], v[42:43], v[44:45]
	v_mov_b32_dpp v158, v156 quad_perm:[2,3,0,1] row_mask:0xf bank_mask:0xf bound_ctrl:1
	v_mov_b32_dpp v159, v157 quad_perm:[2,3,0,1] row_mask:0xf bank_mask:0xf bound_ctrl:1
	v_pk_fma_f32 v[156:157], v[92:93], v[156:157], v[158:159]
	ds_swizzle_b32 v158, v156 offset:swizzle(SWAP,4)
	ds_swizzle_b32 v159, v157 offset:swizzle(SWAP,4)
	v_mov_b32_dpp v44, v42 quad_perm:[1,0,3,2] row_mask:0xf bank_mask:0xf bound_ctrl:1
	v_mov_b32_dpp v45, v43 quad_perm:[1,0,3,2] row_mask:0xf bank_mask:0xf bound_ctrl:1
	v_mov_b32_dpp v163, v161 quad_perm:[1,0,3,2] row_mask:0xf bank_mask:0xf bound_ctrl:1
	v_mov_b32_dpp v154, v152 quad_perm:[1,0,3,2] row_mask:0xf bank_mask:0xf bound_ctrl:1
	v_mov_b32_dpp v155, v153 quad_perm:[1,0,3,2] row_mask:0xf bank_mask:0xf bound_ctrl:1
	v_pk_fma_f32 v[42:43], v[94:95], v[42:43], v[44:45]
	v_pk_fma_f32 v[160:161], v[94:95], v[160:161], v[162:163]
	v_pk_fma_f32 v[152:153], v[94:95], v[152:153], v[154:155]
	v_mov_b32_dpp v44, v42 quad_perm:[2,3,0,1] row_mask:0xf bank_mask:0xf bound_ctrl:1
	v_mov_b32_dpp v45, v43 quad_perm:[2,3,0,1] row_mask:0xf bank_mask:0xf bound_ctrl:1
	v_mov_b32_dpp v162, v160 quad_perm:[2,3,0,1] row_mask:0xf bank_mask:0xf bound_ctrl:1
	v_mov_b32_dpp v163, v161 quad_perm:[2,3,0,1] row_mask:0xf bank_mask:0xf bound_ctrl:1
	v_mov_b32_dpp v154, v152 quad_perm:[2,3,0,1] row_mask:0xf bank_mask:0xf bound_ctrl:1
	v_mov_b32_dpp v155, v153 quad_perm:[2,3,0,1] row_mask:0xf bank_mask:0xf bound_ctrl:1
	v_pk_fma_f32 v[42:43], v[92:93], v[42:43], v[44:45]
	v_pk_fma_f32 v[160:161], v[92:93], v[160:161], v[162:163]
	v_pk_fma_f32 v[152:153], v[92:93], v[152:153], v[154:155]
	ds_swizzle_b32 v44, v42 offset:swizzle(SWAP,4)
	ds_swizzle_b32 v45, v43 offset:swizzle(SWAP,4)
	s_waitcnt lgkmcnt(2)
	v_pk_fma_f32 v[156:157], v[90:91], v[156:157], v[158:159]
	ds_swizzle_b32 v154, v152 offset:swizzle(SWAP,4)
	ds_swizzle_b32 v155, v153 offset:swizzle(SWAP,4)
	ds_swizzle_b32 v158, v160 offset:swizzle(SWAP,4)
	ds_swizzle_b32 v159, v161 offset:swizzle(SWAP,4)
	s_waitcnt lgkmcnt(4)
	v_pk_fma_f32 v[42:43], v[90:91], v[42:43], v[44:45]
	v_pk_mul_f32 v[156:157], v[156:157], s[40:41] op_sel_hi:[1,0]
	v_pk_mul_f32 v[42:43], v[42:43], s[40:41] op_sel_hi:[1,0]
	s_waitcnt lgkmcnt(2)
	v_pk_fma_f32 v[44:45], v[90:91], v[152:153], v[154:155]
	s_waitcnt lgkmcnt(0)
	v_pk_fma_f32 v[152:153], v[90:91], v[160:161], v[158:159]
	v_pk_mul_f32 v[44:45], v[44:45], s[40:41] op_sel_hi:[1,0]
	v_pk_mul_f32 v[152:153], v[152:153], s[40:41] op_sel_hi:[1,0]
	v_cvt_pk_bf16_f32 v42, v42, v43
	v_cvt_pk_bf16_f32 v44, v44, v45
	v_cvt_pk_bf16_f32 v45, v152, v153
	v_lshlrev_b32_e32 v151, 16, v42
	v_and_b32_e32 v152, 0xffff0000, v42
	v_cvt_pk_bf16_f32 v43, v156, v157
	v_and_b32_e32 v42, 0x7fffffff, v152
	v_max_f32_e64 v153, |v151|, |v151|
	v_max_f32_e32 v155, v153, v42
	v_lshlrev_b32_e32 v153, 16, v43
	v_and_b32_e32 v154, 0xffff0000, v43
	v_and_b32_e32 v42, 0x7fffffff, v154
	v_max_f32_e64 v43, |v153|, |v153|
	v_max_f32_e32 v156, v43, v42
	v_lshlrev_b32_e32 v42, 16, v44
	v_and_b32_e32 v43, 0xffff0000, v44
	v_lshlrev_b32_e32 v44, 16, v45
	v_and_b32_e32 v45, 0xffff0000, v45
	v_and_b32_e32 v157, 0x7fffffff, v45
	v_max_f32_e64 v158, |v44|, |v44|
	v_max_f32_e32 v157, v158, v157
	v_max3_f32 v157, |v42|, |v43|, v157
	v_max3_f32 v155, v155, v156, v157
	v_max3_f32 v172, v164, v165, v155
	s_waitcnt vmcnt(8)
	v_lshlrev_b32_e32 v155, 16, v38
	v_and_b32_e32 v156, 0xffff0000, v38
	v_lshlrev_b32_e32 v157, 16, v39
	v_and_b32_e32 v158, 0xffff0000, v39
	v_lshlrev_b32_e32 v159, 16, v40
	v_and_b32_e32 v160, 0xffff0000, v40
	v_lshlrev_b32_e32 v161, 16, v41
	v_and_b32_e32 v162, 0xffff0000, v41
	v_add_f32_e32 v38, v155, v156
	v_sub_f32_e32 v39, v155, v156
	v_add_f32_e32 v40, v157, v158
	v_sub_f32_e32 v41, v157, v158
	v_add_f32_e32 v156, v159, v160
	v_sub_f32_e32 v157, v159, v160
	v_add_f32_e32 v158, v161, v162
	v_sub_f32_e32 v159, v161, v162
	v_pk_add_f32 v[160:161], v[38:39], v[40:41] neg_lo:[0,1] neg_hi:[0,1]
	v_pk_add_f32 v[162:163], v[156:157], v[158:159] neg_lo:[0,1] neg_hi:[0,1]
	v_pk_add_f32 v[38:39], v[38:39], v[40:41]
	v_pk_add_f32 v[164:165], v[160:161], v[162:163] neg_lo:[0,1] neg_hi:[0,1]
	v_pk_add_f32 v[160:161], v[160:161], v[162:163]
	v_pk_add_f32 v[40:41], v[156:157], v[158:159]
	v_mov_b32_dpp v166, v164 quad_perm:[1,0,3,2] row_mask:0xf bank_mask:0xf bound_ctrl:1
	v_mov_b32_dpp v162, v160 quad_perm:[1,0,3,2] row_mask:0xf bank_mask:0xf bound_ctrl:1
	v_mov_b32_dpp v163, v161 quad_perm:[1,0,3,2] row_mask:0xf bank_mask:0xf bound_ctrl:1
	v_pk_fma_f32 v[160:161], v[94:95], v[160:161], v[162:163]
	v_pk_add_f32 v[156:157], v[38:39], v[40:41] neg_lo:[0,1] neg_hi:[0,1]
	v_pk_add_f32 v[38:39], v[38:39], v[40:41]
	v_mov_b32_dpp v162, v160 quad_perm:[2,3,0,1] row_mask:0xf bank_mask:0xf bound_ctrl:1
	v_mov_b32_dpp v163, v161 quad_perm:[2,3,0,1] row_mask:0xf bank_mask:0xf bound_ctrl:1
	v_pk_fma_f32 v[160:161], v[92:93], v[160:161], v[162:163]
	ds_swizzle_b32 v162, v160 offset:swizzle(SWAP,4)
	ds_swizzle_b32 v163, v161 offset:swizzle(SWAP,4)
	v_mov_b32_dpp v40, v38 quad_perm:[1,0,3,2] row_mask:0xf bank_mask:0xf bound_ctrl:1
	v_mov_b32_dpp v41, v39 quad_perm:[1,0,3,2] row_mask:0xf bank_mask:0xf bound_ctrl:1
	v_mov_b32_dpp v167, v165 quad_perm:[1,0,3,2] row_mask:0xf bank_mask:0xf bound_ctrl:1
	v_mov_b32_dpp v158, v156 quad_perm:[1,0,3,2] row_mask:0xf bank_mask:0xf bound_ctrl:1
	v_mov_b32_dpp v159, v157 quad_perm:[1,0,3,2] row_mask:0xf bank_mask:0xf bound_ctrl:1
	v_pk_fma_f32 v[38:39], v[94:95], v[38:39], v[40:41]
	v_pk_fma_f32 v[164:165], v[94:95], v[164:165], v[166:167]
	v_pk_fma_f32 v[156:157], v[94:95], v[156:157], v[158:159]
	v_mov_b32_dpp v40, v38 quad_perm:[2,3,0,1] row_mask:0xf bank_mask:0xf bound_ctrl:1
	v_mov_b32_dpp v41, v39 quad_perm:[2,3,0,1] row_mask:0xf bank_mask:0xf bound_ctrl:1
	v_mov_b32_dpp v166, v164 quad_perm:[2,3,0,1] row_mask:0xf bank_mask:0xf bound_ctrl:1
	v_mov_b32_dpp v167, v165 quad_perm:[2,3,0,1] row_mask:0xf bank_mask:0xf bound_ctrl:1
	v_mov_b32_dpp v158, v156 quad_perm:[2,3,0,1] row_mask:0xf bank_mask:0xf bound_ctrl:1
	v_mov_b32_dpp v159, v157 quad_perm:[2,3,0,1] row_mask:0xf bank_mask:0xf bound_ctrl:1
	v_pk_fma_f32 v[38:39], v[92:93], v[38:39], v[40:41]
	v_pk_fma_f32 v[164:165], v[92:93], v[164:165], v[166:167]
	v_pk_fma_f32 v[156:157], v[92:93], v[156:157], v[158:159]
	ds_swizzle_b32 v40, v38 offset:swizzle(SWAP,4)
	ds_swizzle_b32 v41, v39 offset:swizzle(SWAP,4)
	s_waitcnt lgkmcnt(2)
	v_pk_fma_f32 v[160:161], v[90:91], v[160:161], v[162:163]
	ds_swizzle_b32 v158, v156 offset:swizzle(SWAP,4)
	ds_swizzle_b32 v159, v157 offset:swizzle(SWAP,4)
	ds_swizzle_b32 v162, v164 offset:swizzle(SWAP,4)
	ds_swizzle_b32 v163, v165 offset:swizzle(SWAP,4)
	s_waitcnt lgkmcnt(4)
	v_pk_fma_f32 v[38:39], v[90:91], v[38:39], v[40:41]
	v_pk_mul_f32 v[160:161], v[160:161], s[40:41] op_sel_hi:[1,0]
	v_pk_mul_f32 v[38:39], v[38:39], s[40:41] op_sel_hi:[1,0]
	s_waitcnt lgkmcnt(2)
	v_pk_fma_f32 v[40:41], v[90:91], v[156:157], v[158:159]
	s_waitcnt lgkmcnt(0)
	v_pk_fma_f32 v[156:157], v[90:91], v[164:165], v[162:163]
	v_pk_mul_f32 v[40:41], v[40:41], s[40:41] op_sel_hi:[1,0]
	v_pk_mul_f32 v[156:157], v[156:157], s[40:41] op_sel_hi:[1,0]
	v_cvt_pk_bf16_f32 v38, v38, v39
	v_cvt_pk_bf16_f32 v40, v40, v41
	v_cvt_pk_bf16_f32 v41, v156, v157
	v_lshlrev_b32_e32 v155, 16, v38
	v_and_b32_e32 v156, 0xffff0000, v38
	v_cvt_pk_bf16_f32 v39, v160, v161
	v_and_b32_e32 v38, 0x7fffffff, v156
	v_max_f32_e64 v157, |v155|, |v155|
	v_max_f32_e32 v159, v157, v38
	v_lshlrev_b32_e32 v157, 16, v39
	v_and_b32_e32 v158, 0xffff0000, v39
	v_and_b32_e32 v38, 0x7fffffff, v158
	v_max_f32_e64 v39, |v157|, |v157|
	v_max_f32_e32 v160, v39, v38
	v_lshlrev_b32_e32 v38, 16, v40
	v_and_b32_e32 v39, 0xffff0000, v40
	v_lshlrev_b32_e32 v40, 16, v41
	v_and_b32_e32 v41, 0xffff0000, v41
	v_and_b32_e32 v161, 0x7fffffff, v41
	v_max_f32_e64 v162, |v40|, |v40|
	v_max_f32_e32 v161, v162, v161
	v_max3_f32 v161, |v38|, |v39|, v161
	v_max3_f32 v173, v159, v160, v161
	s_waitcnt vmcnt(7)
	v_lshlrev_b32_e32 v159, 16, v34
	v_and_b32_e32 v160, 0xffff0000, v34
	v_lshlrev_b32_e32 v161, 16, v35
	v_and_b32_e32 v162, 0xffff0000, v35
	v_lshlrev_b32_e32 v163, 16, v36
	v_and_b32_e32 v164, 0xffff0000, v36
	v_lshlrev_b32_e32 v165, 16, v37
	v_and_b32_e32 v166, 0xffff0000, v37
	v_add_f32_e32 v34, v159, v160
	v_sub_f32_e32 v35, v159, v160
	v_add_f32_e32 v36, v161, v162
	v_sub_f32_e32 v37, v161, v162
	v_add_f32_e32 v160, v163, v164
	v_sub_f32_e32 v161, v163, v164
	v_add_f32_e32 v162, v165, v166
	v_sub_f32_e32 v163, v165, v166
	v_pk_add_f32 v[164:165], v[34:35], v[36:37] neg_lo:[0,1] neg_hi:[0,1]
	v_pk_add_f32 v[166:167], v[160:161], v[162:163] neg_lo:[0,1] neg_hi:[0,1]
	v_pk_add_f32 v[34:35], v[34:35], v[36:37]
	v_pk_add_f32 v[168:169], v[164:165], v[166:167] neg_lo:[0,1] neg_hi:[0,1]
	v_pk_add_f32 v[164:165], v[164:165], v[166:167]
	v_pk_add_f32 v[36:37], v[160:161], v[162:163]
	v_mov_b32_dpp v170, v168 quad_perm:[1,0,3,2] row_mask:0xf bank_mask:0xf bound_ctrl:1
	v_mov_b32_dpp v166, v164 quad_perm:[1,0,3,2] row_mask:0xf bank_mask:0xf bound_ctrl:1
	v_mov_b32_dpp v167, v165 quad_perm:[1,0,3,2] row_mask:0xf bank_mask:0xf bound_ctrl:1
	v_pk_fma_f32 v[164:165], v[94:95], v[164:165], v[166:167]
	v_pk_add_f32 v[160:161], v[34:35], v[36:37] neg_lo:[0,1] neg_hi:[0,1]
	v_pk_add_f32 v[34:35], v[34:35], v[36:37]
	v_mov_b32_dpp v166, v164 quad_perm:[2,3,0,1] row_mask:0xf bank_mask:0xf bound_ctrl:1
	v_mov_b32_dpp v167, v165 quad_perm:[2,3,0,1] row_mask:0xf bank_mask:0xf bound_ctrl:1
	v_pk_fma_f32 v[164:165], v[92:93], v[164:165], v[166:167]
	ds_swizzle_b32 v166, v164 offset:swizzle(SWAP,4)
	ds_swizzle_b32 v167, v165 offset:swizzle(SWAP,4)
	v_mov_b32_dpp v36, v34 quad_perm:[1,0,3,2] row_mask:0xf bank_mask:0xf bound_ctrl:1
	v_mov_b32_dpp v37, v35 quad_perm:[1,0,3,2] row_mask:0xf bank_mask:0xf bound_ctrl:1
	v_mov_b32_dpp v171, v169 quad_perm:[1,0,3,2] row_mask:0xf bank_mask:0xf bound_ctrl:1
	v_mov_b32_dpp v162, v160 quad_perm:[1,0,3,2] row_mask:0xf bank_mask:0xf bound_ctrl:1
	v_mov_b32_dpp v163, v161 quad_perm:[1,0,3,2] row_mask:0xf bank_mask:0xf bound_ctrl:1
	v_pk_fma_f32 v[34:35], v[94:95], v[34:35], v[36:37]
	v_pk_fma_f32 v[168:169], v[94:95], v[168:169], v[170:171]
	v_pk_fma_f32 v[160:161], v[94:95], v[160:161], v[162:163]
	v_mov_b32_dpp v36, v34 quad_perm:[2,3,0,1] row_mask:0xf bank_mask:0xf bound_ctrl:1
	v_mov_b32_dpp v37, v35 quad_perm:[2,3,0,1] row_mask:0xf bank_mask:0xf bound_ctrl:1
	v_mov_b32_dpp v170, v168 quad_perm:[2,3,0,1] row_mask:0xf bank_mask:0xf bound_ctrl:1
	v_mov_b32_dpp v171, v169 quad_perm:[2,3,0,1] row_mask:0xf bank_mask:0xf bound_ctrl:1
	v_mov_b32_dpp v162, v160 quad_perm:[2,3,0,1] row_mask:0xf bank_mask:0xf bound_ctrl:1
	v_mov_b32_dpp v163, v161 quad_perm:[2,3,0,1] row_mask:0xf bank_mask:0xf bound_ctrl:1
	v_pk_fma_f32 v[34:35], v[92:93], v[34:35], v[36:37]
	v_pk_fma_f32 v[168:169], v[92:93], v[168:169], v[170:171]
	v_pk_fma_f32 v[160:161], v[92:93], v[160:161], v[162:163]
	ds_swizzle_b32 v36, v34 offset:swizzle(SWAP,4)
	ds_swizzle_b32 v37, v35 offset:swizzle(SWAP,4)
	s_waitcnt lgkmcnt(2)
	v_pk_fma_f32 v[164:165], v[90:91], v[164:165], v[166:167]
	ds_swizzle_b32 v162, v160 offset:swizzle(SWAP,4)
	ds_swizzle_b32 v163, v161 offset:swizzle(SWAP,4)
	ds_swizzle_b32 v166, v168 offset:swizzle(SWAP,4)
	ds_swizzle_b32 v167, v169 offset:swizzle(SWAP,4)
	s_waitcnt lgkmcnt(4)
	v_pk_fma_f32 v[34:35], v[90:91], v[34:35], v[36:37]
	v_pk_mul_f32 v[164:165], v[164:165], s[40:41] op_sel_hi:[1,0]
	v_pk_mul_f32 v[34:35], v[34:35], s[40:41] op_sel_hi:[1,0]
	s_waitcnt lgkmcnt(2)
	v_pk_fma_f32 v[36:37], v[90:91], v[160:161], v[162:163]
	s_waitcnt lgkmcnt(0)
	v_pk_fma_f32 v[160:161], v[90:91], v[168:169], v[166:167]
	v_pk_mul_f32 v[36:37], v[36:37], s[40:41] op_sel_hi:[1,0]
	v_pk_mul_f32 v[160:161], v[160:161], s[40:41] op_sel_hi:[1,0]
	v_cvt_pk_bf16_f32 v34, v34, v35
	v_cvt_pk_bf16_f32 v36, v36, v37
	v_cvt_pk_bf16_f32 v37, v160, v161
	v_lshlrev_b32_e32 v159, 16, v34
	v_and_b32_e32 v160, 0xffff0000, v34
	v_cvt_pk_bf16_f32 v35, v164, v165
	v_and_b32_e32 v34, 0x7fffffff, v160
	v_max_f32_e64 v161, |v159|, |v159|
	v_max_f32_e32 v163, v161, v34
	v_lshlrev_b32_e32 v161, 16, v35
	v_and_b32_e32 v162, 0xffff0000, v35
	v_and_b32_e32 v34, 0x7fffffff, v162
	v_max_f32_e64 v35, |v161|, |v161|
	v_max_f32_e32 v164, v35, v34
	v_lshlrev_b32_e32 v34, 16, v36
	v_and_b32_e32 v35, 0xffff0000, v36
	v_lshlrev_b32_e32 v36, 16, v37
	v_and_b32_e32 v37, 0xffff0000, v37
	v_and_b32_e32 v165, 0x7fffffff, v37
	v_max_f32_e64 v166, |v36|, |v36|
	v_max_f32_e32 v165, v166, v165
	v_max3_f32 v165, |v34|, |v35|, v165
	v_max3_f32 v163, v163, v164, v165
	v_max3_f32 v180, v172, v173, v163
	s_waitcnt vmcnt(6)
	v_lshlrev_b32_e32 v163, 16, v30
	v_and_b32_e32 v164, 0xffff0000, v30
	v_lshlrev_b32_e32 v165, 16, v31
	v_and_b32_e32 v166, 0xffff0000, v31
	v_lshlrev_b32_e32 v167, 16, v32
	v_and_b32_e32 v168, 0xffff0000, v32
	v_lshlrev_b32_e32 v169, 16, v33
	v_and_b32_e32 v170, 0xffff0000, v33
	v_add_f32_e32 v30, v163, v164
	v_sub_f32_e32 v31, v163, v164
	v_add_f32_e32 v32, v165, v166
	v_sub_f32_e32 v33, v165, v166
	v_add_f32_e32 v164, v167, v168
	v_sub_f32_e32 v165, v167, v168
	v_add_f32_e32 v166, v169, v170
	v_sub_f32_e32 v167, v169, v170
	v_pk_add_f32 v[168:169], v[30:31], v[32:33] neg_lo:[0,1] neg_hi:[0,1]
	v_pk_add_f32 v[170:171], v[164:165], v[166:167] neg_lo:[0,1] neg_hi:[0,1]
	v_pk_add_f32 v[30:31], v[30:31], v[32:33]
	v_pk_add_f32 v[172:173], v[168:169], v[170:171] neg_lo:[0,1] neg_hi:[0,1]
	v_pk_add_f32 v[168:169], v[168:169], v[170:171]
	v_pk_add_f32 v[32:33], v[164:165], v[166:167]
	v_mov_b32_dpp v174, v172 quad_perm:[1,0,3,2] row_mask:0xf bank_mask:0xf bound_ctrl:1
	v_mov_b32_dpp v170, v168 quad_perm:[1,0,3,2] row_mask:0xf bank_mask:0xf bound_ctrl:1
	v_mov_b32_dpp v171, v169 quad_perm:[1,0,3,2] row_mask:0xf bank_mask:0xf bound_ctrl:1
	v_pk_fma_f32 v[168:169], v[94:95], v[168:169], v[170:171]
	v_pk_add_f32 v[164:165], v[30:31], v[32:33] neg_lo:[0,1] neg_hi:[0,1]
	v_pk_add_f32 v[30:31], v[30:31], v[32:33]
	v_mov_b32_dpp v170, v168 quad_perm:[2,3,0,1] row_mask:0xf bank_mask:0xf bound_ctrl:1
	v_mov_b32_dpp v171, v169 quad_perm:[2,3,0,1] row_mask:0xf bank_mask:0xf bound_ctrl:1
	v_pk_fma_f32 v[168:169], v[92:93], v[168:169], v[170:171]
	ds_swizzle_b32 v170, v168 offset:swizzle(SWAP,4)
	ds_swizzle_b32 v171, v169 offset:swizzle(SWAP,4)
	v_mov_b32_dpp v32, v30 quad_perm:[1,0,3,2] row_mask:0xf bank_mask:0xf bound_ctrl:1
	v_mov_b32_dpp v33, v31 quad_perm:[1,0,3,2] row_mask:0xf bank_mask:0xf bound_ctrl:1
	v_mov_b32_dpp v175, v173 quad_perm:[1,0,3,2] row_mask:0xf bank_mask:0xf bound_ctrl:1
	v_mov_b32_dpp v166, v164 quad_perm:[1,0,3,2] row_mask:0xf bank_mask:0xf bound_ctrl:1
	v_mov_b32_dpp v167, v165 quad_perm:[1,0,3,2] row_mask:0xf bank_mask:0xf bound_ctrl:1
	v_pk_fma_f32 v[30:31], v[94:95], v[30:31], v[32:33]
	v_pk_fma_f32 v[172:173], v[94:95], v[172:173], v[174:175]
	v_pk_fma_f32 v[164:165], v[94:95], v[164:165], v[166:167]
	v_mov_b32_dpp v32, v30 quad_perm:[2,3,0,1] row_mask:0xf bank_mask:0xf bound_ctrl:1
	v_mov_b32_dpp v33, v31 quad_perm:[2,3,0,1] row_mask:0xf bank_mask:0xf bound_ctrl:1
	v_mov_b32_dpp v174, v172 quad_perm:[2,3,0,1] row_mask:0xf bank_mask:0xf bound_ctrl:1
	v_mov_b32_dpp v175, v173 quad_perm:[2,3,0,1] row_mask:0xf bank_mask:0xf bound_ctrl:1
	v_mov_b32_dpp v166, v164 quad_perm:[2,3,0,1] row_mask:0xf bank_mask:0xf bound_ctrl:1
	v_mov_b32_dpp v167, v165 quad_perm:[2,3,0,1] row_mask:0xf bank_mask:0xf bound_ctrl:1
	v_pk_fma_f32 v[30:31], v[92:93], v[30:31], v[32:33]
	v_pk_fma_f32 v[172:173], v[92:93], v[172:173], v[174:175]
	v_pk_fma_f32 v[164:165], v[92:93], v[164:165], v[166:167]
	ds_swizzle_b32 v32, v30 offset:swizzle(SWAP,4)
	ds_swizzle_b32 v33, v31 offset:swizzle(SWAP,4)
	s_waitcnt lgkmcnt(2)
	v_pk_fma_f32 v[168:169], v[90:91], v[168:169], v[170:171]
	ds_swizzle_b32 v166, v164 offset:swizzle(SWAP,4)
	ds_swizzle_b32 v167, v165 offset:swizzle(SWAP,4)
	ds_swizzle_b32 v170, v172 offset:swizzle(SWAP,4)
	ds_swizzle_b32 v171, v173 offset:swizzle(SWAP,4)
	s_waitcnt lgkmcnt(4)
	v_pk_fma_f32 v[30:31], v[90:91], v[30:31], v[32:33]
	v_pk_mul_f32 v[168:169], v[168:169], s[40:41] op_sel_hi:[1,0]
	v_pk_mul_f32 v[30:31], v[30:31], s[40:41] op_sel_hi:[1,0]
	s_waitcnt lgkmcnt(2)
	v_pk_fma_f32 v[32:33], v[90:91], v[164:165], v[166:167]
	s_waitcnt lgkmcnt(0)
	v_pk_fma_f32 v[164:165], v[90:91], v[172:173], v[170:171]
	v_pk_mul_f32 v[32:33], v[32:33], s[40:41] op_sel_hi:[1,0]
	v_pk_mul_f32 v[164:165], v[164:165], s[40:41] op_sel_hi:[1,0]
	v_cvt_pk_bf16_f32 v30, v30, v31
	v_cvt_pk_bf16_f32 v32, v32, v33
	v_cvt_pk_bf16_f32 v33, v164, v165
	v_lshlrev_b32_e32 v163, 16, v30
	v_and_b32_e32 v164, 0xffff0000, v30
	v_cvt_pk_bf16_f32 v31, v168, v169
	v_and_b32_e32 v30, 0x7fffffff, v164
	v_max_f32_e64 v165, |v163|, |v163|
	v_max_f32_e32 v167, v165, v30
	v_lshlrev_b32_e32 v165, 16, v31
	v_and_b32_e32 v166, 0xffff0000, v31
	v_and_b32_e32 v30, 0x7fffffff, v166
	v_max_f32_e64 v31, |v165|, |v165|
	v_max_f32_e32 v168, v31, v30
	v_lshlrev_b32_e32 v30, 16, v32
	v_and_b32_e32 v31, 0xffff0000, v32
	v_lshlrev_b32_e32 v32, 16, v33
	v_and_b32_e32 v33, 0xffff0000, v33
	v_and_b32_e32 v169, 0x7fffffff, v33
	v_max_f32_e64 v170, |v32|, |v32|
	v_max_f32_e32 v169, v170, v169
	v_max3_f32 v169, |v30|, |v31|, v169
	v_max3_f32 v181, v167, v168, v169
	s_waitcnt vmcnt(5)
	v_lshlrev_b32_e32 v167, 16, v26
	v_and_b32_e32 v168, 0xffff0000, v26
	v_lshlrev_b32_e32 v169, 16, v27
	v_and_b32_e32 v170, 0xffff0000, v27
	v_lshlrev_b32_e32 v171, 16, v28
	v_and_b32_e32 v172, 0xffff0000, v28
	v_lshlrev_b32_e32 v173, 16, v29
	v_and_b32_e32 v174, 0xffff0000, v29
	v_add_f32_e32 v26, v167, v168
	v_sub_f32_e32 v27, v167, v168
	v_add_f32_e32 v28, v169, v170
	v_sub_f32_e32 v29, v169, v170
	v_add_f32_e32 v168, v171, v172
	v_sub_f32_e32 v169, v171, v172
	v_add_f32_e32 v170, v173, v174
	v_sub_f32_e32 v171, v173, v174
	v_pk_add_f32 v[172:173], v[26:27], v[28:29] neg_lo:[0,1] neg_hi:[0,1]
	v_pk_add_f32 v[174:175], v[168:169], v[170:171] neg_lo:[0,1] neg_hi:[0,1]
	v_pk_add_f32 v[26:27], v[26:27], v[28:29]
	v_pk_add_f32 v[176:177], v[172:173], v[174:175] neg_lo:[0,1] neg_hi:[0,1]
	v_pk_add_f32 v[172:173], v[172:173], v[174:175]
	v_pk_add_f32 v[28:29], v[168:169], v[170:171]
	v_mov_b32_dpp v178, v176 quad_perm:[1,0,3,2] row_mask:0xf bank_mask:0xf bound_ctrl:1
	v_mov_b32_dpp v174, v172 quad_perm:[1,0,3,2] row_mask:0xf bank_mask:0xf bound_ctrl:1
	v_mov_b32_dpp v175, v173 quad_perm:[1,0,3,2] row_mask:0xf bank_mask:0xf bound_ctrl:1
	v_pk_fma_f32 v[172:173], v[94:95], v[172:173], v[174:175]
	v_pk_add_f32 v[168:169], v[26:27], v[28:29] neg_lo:[0,1] neg_hi:[0,1]
	v_pk_add_f32 v[26:27], v[26:27], v[28:29]
	v_mov_b32_dpp v174, v172 quad_perm:[2,3,0,1] row_mask:0xf bank_mask:0xf bound_ctrl:1
	v_mov_b32_dpp v175, v173 quad_perm:[2,3,0,1] row_mask:0xf bank_mask:0xf bound_ctrl:1
	v_pk_fma_f32 v[172:173], v[92:93], v[172:173], v[174:175]
	ds_swizzle_b32 v174, v172 offset:swizzle(SWAP,4)
	ds_swizzle_b32 v175, v173 offset:swizzle(SWAP,4)
	v_mov_b32_dpp v28, v26 quad_perm:[1,0,3,2] row_mask:0xf bank_mask:0xf bound_ctrl:1
	v_mov_b32_dpp v29, v27 quad_perm:[1,0,3,2] row_mask:0xf bank_mask:0xf bound_ctrl:1
	v_mov_b32_dpp v179, v177 quad_perm:[1,0,3,2] row_mask:0xf bank_mask:0xf bound_ctrl:1
	v_mov_b32_dpp v170, v168 quad_perm:[1,0,3,2] row_mask:0xf bank_mask:0xf bound_ctrl:1
	v_mov_b32_dpp v171, v169 quad_perm:[1,0,3,2] row_mask:0xf bank_mask:0xf bound_ctrl:1
	v_pk_fma_f32 v[26:27], v[94:95], v[26:27], v[28:29]
	v_pk_fma_f32 v[176:177], v[94:95], v[176:177], v[178:179]
	v_pk_fma_f32 v[168:169], v[94:95], v[168:169], v[170:171]
	v_mov_b32_dpp v28, v26 quad_perm:[2,3,0,1] row_mask:0xf bank_mask:0xf bound_ctrl:1
	v_mov_b32_dpp v29, v27 quad_perm:[2,3,0,1] row_mask:0xf bank_mask:0xf bound_ctrl:1
	v_mov_b32_dpp v178, v176 quad_perm:[2,3,0,1] row_mask:0xf bank_mask:0xf bound_ctrl:1
	v_mov_b32_dpp v179, v177 quad_perm:[2,3,0,1] row_mask:0xf bank_mask:0xf bound_ctrl:1
	v_mov_b32_dpp v170, v168 quad_perm:[2,3,0,1] row_mask:0xf bank_mask:0xf bound_ctrl:1
	v_mov_b32_dpp v171, v169 quad_perm:[2,3,0,1] row_mask:0xf bank_mask:0xf bound_ctrl:1
	v_pk_fma_f32 v[26:27], v[92:93], v[26:27], v[28:29]
	v_pk_fma_f32 v[176:177], v[92:93], v[176:177], v[178:179]
	v_pk_fma_f32 v[168:169], v[92:93], v[168:169], v[170:171]
	ds_swizzle_b32 v28, v26 offset:swizzle(SWAP,4)
	ds_swizzle_b32 v29, v27 offset:swizzle(SWAP,4)
	s_waitcnt lgkmcnt(2)
	v_pk_fma_f32 v[172:173], v[90:91], v[172:173], v[174:175]
	ds_swizzle_b32 v170, v168 offset:swizzle(SWAP,4)
	ds_swizzle_b32 v171, v169 offset:swizzle(SWAP,4)
	ds_swizzle_b32 v174, v176 offset:swizzle(SWAP,4)
	ds_swizzle_b32 v175, v177 offset:swizzle(SWAP,4)
	s_waitcnt lgkmcnt(4)
	v_pk_fma_f32 v[26:27], v[90:91], v[26:27], v[28:29]
	v_pk_mul_f32 v[172:173], v[172:173], s[40:41] op_sel_hi:[1,0]
	v_pk_mul_f32 v[26:27], v[26:27], s[40:41] op_sel_hi:[1,0]
	s_waitcnt lgkmcnt(2)
	v_pk_fma_f32 v[28:29], v[90:91], v[168:169], v[170:171]
	s_waitcnt lgkmcnt(0)
	v_pk_fma_f32 v[168:169], v[90:91], v[176:177], v[174:175]
	v_pk_mul_f32 v[28:29], v[28:29], s[40:41] op_sel_hi:[1,0]
	v_pk_mul_f32 v[168:169], v[168:169], s[40:41] op_sel_hi:[1,0]
	v_cvt_pk_bf16_f32 v26, v26, v27
	v_cvt_pk_bf16_f32 v28, v28, v29
	v_cvt_pk_bf16_f32 v29, v168, v169
	v_lshlrev_b32_e32 v167, 16, v26
	v_and_b32_e32 v168, 0xffff0000, v26
	v_cvt_pk_bf16_f32 v27, v172, v173
	v_and_b32_e32 v26, 0x7fffffff, v168
	v_max_f32_e64 v169, |v167|, |v167|
	v_max_f32_e32 v171, v169, v26
	v_lshlrev_b32_e32 v169, 16, v27
	v_and_b32_e32 v170, 0xffff0000, v27
	v_and_b32_e32 v26, 0x7fffffff, v170
	v_max_f32_e64 v27, |v169|, |v169|
	v_max_f32_e32 v172, v27, v26
	v_lshlrev_b32_e32 v26, 16, v28
	v_and_b32_e32 v27, 0xffff0000, v28
	v_lshlrev_b32_e32 v28, 16, v29
	v_and_b32_e32 v29, 0xffff0000, v29
	v_and_b32_e32 v173, 0x7fffffff, v29
	v_max_f32_e64 v174, |v28|, |v28|
	v_max_f32_e32 v173, v174, v173
	v_max3_f32 v173, |v26|, |v27|, v173
	v_max3_f32 v171, v171, v172, v173
	v_max3_f32 v188, v180, v181, v171
	s_waitcnt vmcnt(4)
	v_lshlrev_b32_e32 v171, 16, v22
	v_and_b32_e32 v172, 0xffff0000, v22
	v_lshlrev_b32_e32 v173, 16, v23
	v_and_b32_e32 v174, 0xffff0000, v23
	v_lshlrev_b32_e32 v175, 16, v24
	v_and_b32_e32 v176, 0xffff0000, v24
	v_lshlrev_b32_e32 v177, 16, v25
	v_and_b32_e32 v178, 0xffff0000, v25
	v_add_f32_e32 v22, v171, v172
	v_sub_f32_e32 v23, v171, v172
	v_add_f32_e32 v24, v173, v174
	v_sub_f32_e32 v25, v173, v174
	v_add_f32_e32 v172, v175, v176
	v_sub_f32_e32 v173, v175, v176
	v_add_f32_e32 v174, v177, v178
	v_sub_f32_e32 v175, v177, v178
	v_pk_add_f32 v[176:177], v[22:23], v[24:25] neg_lo:[0,1] neg_hi:[0,1]
	v_pk_add_f32 v[178:179], v[172:173], v[174:175] neg_lo:[0,1] neg_hi:[0,1]
	v_pk_add_f32 v[22:23], v[22:23], v[24:25]
	v_pk_add_f32 v[180:181], v[176:177], v[178:179] neg_lo:[0,1] neg_hi:[0,1]
	v_pk_add_f32 v[176:177], v[176:177], v[178:179]
	v_pk_add_f32 v[24:25], v[172:173], v[174:175]
	v_mov_b32_dpp v182, v180 quad_perm:[1,0,3,2] row_mask:0xf bank_mask:0xf bound_ctrl:1
	v_mov_b32_dpp v178, v176 quad_perm:[1,0,3,2] row_mask:0xf bank_mask:0xf bound_ctrl:1
	v_mov_b32_dpp v179, v177 quad_perm:[1,0,3,2] row_mask:0xf bank_mask:0xf bound_ctrl:1
	v_pk_fma_f32 v[176:177], v[94:95], v[176:177], v[178:179]
	v_pk_add_f32 v[172:173], v[22:23], v[24:25] neg_lo:[0,1] neg_hi:[0,1]
	v_pk_add_f32 v[22:23], v[22:23], v[24:25]
	v_mov_b32_dpp v178, v176 quad_perm:[2,3,0,1] row_mask:0xf bank_mask:0xf bound_ctrl:1
	v_mov_b32_dpp v179, v177 quad_perm:[2,3,0,1] row_mask:0xf bank_mask:0xf bound_ctrl:1
	v_pk_fma_f32 v[176:177], v[92:93], v[176:177], v[178:179]
	ds_swizzle_b32 v178, v176 offset:swizzle(SWAP,4)
	ds_swizzle_b32 v179, v177 offset:swizzle(SWAP,4)
	v_mov_b32_dpp v24, v22 quad_perm:[1,0,3,2] row_mask:0xf bank_mask:0xf bound_ctrl:1
	v_mov_b32_dpp v25, v23 quad_perm:[1,0,3,2] row_mask:0xf bank_mask:0xf bound_ctrl:1
	v_mov_b32_dpp v183, v181 quad_perm:[1,0,3,2] row_mask:0xf bank_mask:0xf bound_ctrl:1
	v_mov_b32_dpp v174, v172 quad_perm:[1,0,3,2] row_mask:0xf bank_mask:0xf bound_ctrl:1
	v_mov_b32_dpp v175, v173 quad_perm:[1,0,3,2] row_mask:0xf bank_mask:0xf bound_ctrl:1
	v_pk_fma_f32 v[22:23], v[94:95], v[22:23], v[24:25]
	v_pk_fma_f32 v[180:181], v[94:95], v[180:181], v[182:183]
	v_pk_fma_f32 v[172:173], v[94:95], v[172:173], v[174:175]
	v_mov_b32_dpp v24, v22 quad_perm:[2,3,0,1] row_mask:0xf bank_mask:0xf bound_ctrl:1
	v_mov_b32_dpp v25, v23 quad_perm:[2,3,0,1] row_mask:0xf bank_mask:0xf bound_ctrl:1
	v_mov_b32_dpp v182, v180 quad_perm:[2,3,0,1] row_mask:0xf bank_mask:0xf bound_ctrl:1
	v_mov_b32_dpp v183, v181 quad_perm:[2,3,0,1] row_mask:0xf bank_mask:0xf bound_ctrl:1
	v_mov_b32_dpp v174, v172 quad_perm:[2,3,0,1] row_mask:0xf bank_mask:0xf bound_ctrl:1
	v_mov_b32_dpp v175, v173 quad_perm:[2,3,0,1] row_mask:0xf bank_mask:0xf bound_ctrl:1
	v_pk_fma_f32 v[22:23], v[92:93], v[22:23], v[24:25]
	v_pk_fma_f32 v[180:181], v[92:93], v[180:181], v[182:183]
	v_pk_fma_f32 v[172:173], v[92:93], v[172:173], v[174:175]
	ds_swizzle_b32 v24, v22 offset:swizzle(SWAP,4)
	ds_swizzle_b32 v25, v23 offset:swizzle(SWAP,4)
	s_waitcnt lgkmcnt(2)
	v_pk_fma_f32 v[176:177], v[90:91], v[176:177], v[178:179]
	ds_swizzle_b32 v174, v172 offset:swizzle(SWAP,4)
	ds_swizzle_b32 v175, v173 offset:swizzle(SWAP,4)
	ds_swizzle_b32 v178, v180 offset:swizzle(SWAP,4)
	ds_swizzle_b32 v179, v181 offset:swizzle(SWAP,4)
	s_waitcnt lgkmcnt(4)
	v_pk_fma_f32 v[22:23], v[90:91], v[22:23], v[24:25]
	v_pk_mul_f32 v[176:177], v[176:177], s[40:41] op_sel_hi:[1,0]
	v_pk_mul_f32 v[22:23], v[22:23], s[40:41] op_sel_hi:[1,0]
	s_waitcnt lgkmcnt(2)
	v_pk_fma_f32 v[24:25], v[90:91], v[172:173], v[174:175]
	s_waitcnt lgkmcnt(0)
	v_pk_fma_f32 v[172:173], v[90:91], v[180:181], v[178:179]
	v_pk_mul_f32 v[24:25], v[24:25], s[40:41] op_sel_hi:[1,0]
	v_pk_mul_f32 v[172:173], v[172:173], s[40:41] op_sel_hi:[1,0]
	v_cvt_pk_bf16_f32 v22, v22, v23
	v_cvt_pk_bf16_f32 v24, v24, v25
	v_cvt_pk_bf16_f32 v25, v172, v173
	v_lshlrev_b32_e32 v171, 16, v22
	v_and_b32_e32 v172, 0xffff0000, v22
	v_cvt_pk_bf16_f32 v23, v176, v177
	v_and_b32_e32 v22, 0x7fffffff, v172
	v_max_f32_e64 v173, |v171|, |v171|
	v_max_f32_e32 v175, v173, v22
	v_lshlrev_b32_e32 v173, 16, v23
	v_and_b32_e32 v174, 0xffff0000, v23
	v_and_b32_e32 v22, 0x7fffffff, v174
	v_max_f32_e64 v23, |v173|, |v173|
	v_max_f32_e32 v176, v23, v22
	v_lshlrev_b32_e32 v22, 16, v24
	v_and_b32_e32 v23, 0xffff0000, v24
	v_lshlrev_b32_e32 v24, 16, v25
	v_and_b32_e32 v25, 0xffff0000, v25
	v_and_b32_e32 v177, 0x7fffffff, v25
	v_max_f32_e64 v178, |v24|, |v24|
	v_max_f32_e32 v177, v178, v177
	v_max3_f32 v177, |v22|, |v23|, v177
	v_max3_f32 v189, v175, v176, v177
	s_waitcnt vmcnt(3)
	v_lshlrev_b32_e32 v175, 16, v18
	v_and_b32_e32 v176, 0xffff0000, v18
	v_lshlrev_b32_e32 v177, 16, v19
	v_and_b32_e32 v178, 0xffff0000, v19
	v_lshlrev_b32_e32 v179, 16, v20
	v_and_b32_e32 v180, 0xffff0000, v20
	v_lshlrev_b32_e32 v181, 16, v21
	v_and_b32_e32 v182, 0xffff0000, v21
	v_add_f32_e32 v18, v175, v176
	v_sub_f32_e32 v19, v175, v176
	v_add_f32_e32 v20, v177, v178
	v_sub_f32_e32 v21, v177, v178
	v_add_f32_e32 v176, v179, v180
	v_sub_f32_e32 v177, v179, v180
	v_add_f32_e32 v178, v181, v182
	v_sub_f32_e32 v179, v181, v182
	v_pk_add_f32 v[180:181], v[18:19], v[20:21] neg_lo:[0,1] neg_hi:[0,1]
	v_pk_add_f32 v[182:183], v[176:177], v[178:179] neg_lo:[0,1] neg_hi:[0,1]
	v_pk_add_f32 v[18:19], v[18:19], v[20:21]
	v_pk_add_f32 v[184:185], v[180:181], v[182:183] neg_lo:[0,1] neg_hi:[0,1]
	v_pk_add_f32 v[180:181], v[180:181], v[182:183]
	v_pk_add_f32 v[20:21], v[176:177], v[178:179]
	v_mov_b32_dpp v186, v184 quad_perm:[1,0,3,2] row_mask:0xf bank_mask:0xf bound_ctrl:1
	v_mov_b32_dpp v182, v180 quad_perm:[1,0,3,2] row_mask:0xf bank_mask:0xf bound_ctrl:1
	v_mov_b32_dpp v183, v181 quad_perm:[1,0,3,2] row_mask:0xf bank_mask:0xf bound_ctrl:1
	v_pk_fma_f32 v[180:181], v[94:95], v[180:181], v[182:183]
	v_pk_add_f32 v[176:177], v[18:19], v[20:21] neg_lo:[0,1] neg_hi:[0,1]
	v_pk_add_f32 v[18:19], v[18:19], v[20:21]
	v_mov_b32_dpp v182, v180 quad_perm:[2,3,0,1] row_mask:0xf bank_mask:0xf bound_ctrl:1
	v_mov_b32_dpp v183, v181 quad_perm:[2,3,0,1] row_mask:0xf bank_mask:0xf bound_ctrl:1
	v_pk_fma_f32 v[180:181], v[92:93], v[180:181], v[182:183]
	ds_swizzle_b32 v182, v180 offset:swizzle(SWAP,4)
	ds_swizzle_b32 v183, v181 offset:swizzle(SWAP,4)
	v_mov_b32_dpp v20, v18 quad_perm:[1,0,3,2] row_mask:0xf bank_mask:0xf bound_ctrl:1
	v_mov_b32_dpp v21, v19 quad_perm:[1,0,3,2] row_mask:0xf bank_mask:0xf bound_ctrl:1
	v_mov_b32_dpp v187, v185 quad_perm:[1,0,3,2] row_mask:0xf bank_mask:0xf bound_ctrl:1
	v_mov_b32_dpp v178, v176 quad_perm:[1,0,3,2] row_mask:0xf bank_mask:0xf bound_ctrl:1
	v_mov_b32_dpp v179, v177 quad_perm:[1,0,3,2] row_mask:0xf bank_mask:0xf bound_ctrl:1
	v_pk_fma_f32 v[18:19], v[94:95], v[18:19], v[20:21]
	v_pk_fma_f32 v[184:185], v[94:95], v[184:185], v[186:187]
	v_pk_fma_f32 v[176:177], v[94:95], v[176:177], v[178:179]
	v_mov_b32_dpp v20, v18 quad_perm:[2,3,0,1] row_mask:0xf bank_mask:0xf bound_ctrl:1
	v_mov_b32_dpp v21, v19 quad_perm:[2,3,0,1] row_mask:0xf bank_mask:0xf bound_ctrl:1
	v_mov_b32_dpp v186, v184 quad_perm:[2,3,0,1] row_mask:0xf bank_mask:0xf bound_ctrl:1
	v_mov_b32_dpp v187, v185 quad_perm:[2,3,0,1] row_mask:0xf bank_mask:0xf bound_ctrl:1
	v_mov_b32_dpp v178, v176 quad_perm:[2,3,0,1] row_mask:0xf bank_mask:0xf bound_ctrl:1
	v_mov_b32_dpp v179, v177 quad_perm:[2,3,0,1] row_mask:0xf bank_mask:0xf bound_ctrl:1
	v_pk_fma_f32 v[18:19], v[92:93], v[18:19], v[20:21]
	v_pk_fma_f32 v[184:185], v[92:93], v[184:185], v[186:187]
	v_pk_fma_f32 v[176:177], v[92:93], v[176:177], v[178:179]
	ds_swizzle_b32 v20, v18 offset:swizzle(SWAP,4)
	ds_swizzle_b32 v21, v19 offset:swizzle(SWAP,4)
	s_waitcnt lgkmcnt(2)
	v_pk_fma_f32 v[180:181], v[90:91], v[180:181], v[182:183]
	ds_swizzle_b32 v178, v176 offset:swizzle(SWAP,4)
	ds_swizzle_b32 v179, v177 offset:swizzle(SWAP,4)
	ds_swizzle_b32 v182, v184 offset:swizzle(SWAP,4)
	ds_swizzle_b32 v183, v185 offset:swizzle(SWAP,4)
	s_waitcnt lgkmcnt(4)
	v_pk_fma_f32 v[18:19], v[90:91], v[18:19], v[20:21]
	v_pk_mul_f32 v[180:181], v[180:181], s[40:41] op_sel_hi:[1,0]
	v_pk_mul_f32 v[18:19], v[18:19], s[40:41] op_sel_hi:[1,0]
	s_waitcnt lgkmcnt(2)
	v_pk_fma_f32 v[20:21], v[90:91], v[176:177], v[178:179]
	s_waitcnt lgkmcnt(0)
	v_pk_fma_f32 v[176:177], v[90:91], v[184:185], v[182:183]
	v_pk_mul_f32 v[20:21], v[20:21], s[40:41] op_sel_hi:[1,0]
	v_pk_mul_f32 v[176:177], v[176:177], s[40:41] op_sel_hi:[1,0]
	v_cvt_pk_bf16_f32 v18, v18, v19
	v_cvt_pk_bf16_f32 v20, v20, v21
	v_cvt_pk_bf16_f32 v21, v176, v177
	v_lshlrev_b32_e32 v175, 16, v18
	v_and_b32_e32 v176, 0xffff0000, v18
	v_cvt_pk_bf16_f32 v19, v180, v181
	v_and_b32_e32 v18, 0x7fffffff, v176
	v_max_f32_e64 v177, |v175|, |v175|
	v_max_f32_e32 v179, v177, v18
	v_lshlrev_b32_e32 v177, 16, v19
	v_and_b32_e32 v178, 0xffff0000, v19
	v_and_b32_e32 v18, 0x7fffffff, v178
	v_max_f32_e64 v19, |v177|, |v177|
	v_max_f32_e32 v180, v19, v18
	v_lshlrev_b32_e32 v18, 16, v20
	v_and_b32_e32 v19, 0xffff0000, v20
	v_lshlrev_b32_e32 v20, 16, v21
	v_and_b32_e32 v21, 0xffff0000, v21
	v_and_b32_e32 v181, 0x7fffffff, v21
	v_max_f32_e64 v182, |v20|, |v20|
	v_max_f32_e32 v181, v182, v181
	v_max3_f32 v181, |v18|, |v19|, v181
	v_max3_f32 v179, v179, v180, v181
	v_max3_f32 v196, v188, v189, v179
	s_waitcnt vmcnt(2)
	v_lshlrev_b32_e32 v179, 16, v14
	v_and_b32_e32 v180, 0xffff0000, v14
	v_lshlrev_b32_e32 v181, 16, v15
	v_and_b32_e32 v182, 0xffff0000, v15
	v_lshlrev_b32_e32 v183, 16, v16
	v_and_b32_e32 v184, 0xffff0000, v16
	v_lshlrev_b32_e32 v185, 16, v17
	v_and_b32_e32 v186, 0xffff0000, v17
	v_add_f32_e32 v14, v179, v180
	v_sub_f32_e32 v15, v179, v180
	v_add_f32_e32 v16, v181, v182
	v_sub_f32_e32 v17, v181, v182
	v_add_f32_e32 v180, v183, v184
	v_sub_f32_e32 v181, v183, v184
	v_add_f32_e32 v182, v185, v186
	v_sub_f32_e32 v183, v185, v186
	v_pk_add_f32 v[184:185], v[14:15], v[16:17] neg_lo:[0,1] neg_hi:[0,1]
	v_pk_add_f32 v[186:187], v[180:181], v[182:183] neg_lo:[0,1] neg_hi:[0,1]
	v_pk_add_f32 v[14:15], v[14:15], v[16:17]
	v_pk_add_f32 v[188:189], v[184:185], v[186:187] neg_lo:[0,1] neg_hi:[0,1]
	v_pk_add_f32 v[184:185], v[184:185], v[186:187]
	v_pk_add_f32 v[16:17], v[180:181], v[182:183]
	v_mov_b32_dpp v190, v188 quad_perm:[1,0,3,2] row_mask:0xf bank_mask:0xf bound_ctrl:1
	v_mov_b32_dpp v186, v184 quad_perm:[1,0,3,2] row_mask:0xf bank_mask:0xf bound_ctrl:1
	v_mov_b32_dpp v187, v185 quad_perm:[1,0,3,2] row_mask:0xf bank_mask:0xf bound_ctrl:1
	v_pk_fma_f32 v[184:185], v[94:95], v[184:185], v[186:187]
	v_pk_add_f32 v[180:181], v[14:15], v[16:17] neg_lo:[0,1] neg_hi:[0,1]
	v_pk_add_f32 v[14:15], v[14:15], v[16:17]
	v_mov_b32_dpp v186, v184 quad_perm:[2,3,0,1] row_mask:0xf bank_mask:0xf bound_ctrl:1
	v_mov_b32_dpp v187, v185 quad_perm:[2,3,0,1] row_mask:0xf bank_mask:0xf bound_ctrl:1
	v_pk_fma_f32 v[184:185], v[92:93], v[184:185], v[186:187]
	ds_swizzle_b32 v186, v184 offset:swizzle(SWAP,4)
	ds_swizzle_b32 v187, v185 offset:swizzle(SWAP,4)
	v_mov_b32_dpp v16, v14 quad_perm:[1,0,3,2] row_mask:0xf bank_mask:0xf bound_ctrl:1
	v_mov_b32_dpp v17, v15 quad_perm:[1,0,3,2] row_mask:0xf bank_mask:0xf bound_ctrl:1
	v_mov_b32_dpp v191, v189 quad_perm:[1,0,3,2] row_mask:0xf bank_mask:0xf bound_ctrl:1
	v_mov_b32_dpp v182, v180 quad_perm:[1,0,3,2] row_mask:0xf bank_mask:0xf bound_ctrl:1
	v_mov_b32_dpp v183, v181 quad_perm:[1,0,3,2] row_mask:0xf bank_mask:0xf bound_ctrl:1
	v_pk_fma_f32 v[14:15], v[94:95], v[14:15], v[16:17]
	v_pk_fma_f32 v[188:189], v[94:95], v[188:189], v[190:191]
	v_pk_fma_f32 v[180:181], v[94:95], v[180:181], v[182:183]
	v_mov_b32_dpp v16, v14 quad_perm:[2,3,0,1] row_mask:0xf bank_mask:0xf bound_ctrl:1
	v_mov_b32_dpp v17, v15 quad_perm:[2,3,0,1] row_mask:0xf bank_mask:0xf bound_ctrl:1
	v_mov_b32_dpp v190, v188 quad_perm:[2,3,0,1] row_mask:0xf bank_mask:0xf bound_ctrl:1
	v_mov_b32_dpp v191, v189 quad_perm:[2,3,0,1] row_mask:0xf bank_mask:0xf bound_ctrl:1
	v_mov_b32_dpp v182, v180 quad_perm:[2,3,0,1] row_mask:0xf bank_mask:0xf bound_ctrl:1
	v_mov_b32_dpp v183, v181 quad_perm:[2,3,0,1] row_mask:0xf bank_mask:0xf bound_ctrl:1
	v_pk_fma_f32 v[14:15], v[92:93], v[14:15], v[16:17]
	v_pk_fma_f32 v[188:189], v[92:93], v[188:189], v[190:191]
	v_pk_fma_f32 v[180:181], v[92:93], v[180:181], v[182:183]
	ds_swizzle_b32 v16, v14 offset:swizzle(SWAP,4)
	ds_swizzle_b32 v17, v15 offset:swizzle(SWAP,4)
	s_waitcnt lgkmcnt(2)
	v_pk_fma_f32 v[184:185], v[90:91], v[184:185], v[186:187]
	ds_swizzle_b32 v182, v180 offset:swizzle(SWAP,4)
	ds_swizzle_b32 v183, v181 offset:swizzle(SWAP,4)
	ds_swizzle_b32 v186, v188 offset:swizzle(SWAP,4)
	ds_swizzle_b32 v187, v189 offset:swizzle(SWAP,4)
	s_waitcnt lgkmcnt(4)
	v_pk_fma_f32 v[14:15], v[90:91], v[14:15], v[16:17]
	v_pk_mul_f32 v[184:185], v[184:185], s[40:41] op_sel_hi:[1,0]
	v_pk_mul_f32 v[14:15], v[14:15], s[40:41] op_sel_hi:[1,0]
	s_waitcnt lgkmcnt(2)
	v_pk_fma_f32 v[16:17], v[90:91], v[180:181], v[182:183]
	s_waitcnt lgkmcnt(0)
	v_pk_fma_f32 v[180:181], v[90:91], v[188:189], v[186:187]
	v_pk_mul_f32 v[16:17], v[16:17], s[40:41] op_sel_hi:[1,0]
	v_pk_mul_f32 v[180:181], v[180:181], s[40:41] op_sel_hi:[1,0]
	v_cvt_pk_bf16_f32 v14, v14, v15
	v_cvt_pk_bf16_f32 v16, v16, v17
	v_cvt_pk_bf16_f32 v17, v180, v181
	v_lshlrev_b32_e32 v179, 16, v14
	v_and_b32_e32 v180, 0xffff0000, v14
	v_cvt_pk_bf16_f32 v15, v184, v185
	v_and_b32_e32 v14, 0x7fffffff, v180
	v_max_f32_e64 v181, |v179|, |v179|
	v_max_f32_e32 v183, v181, v14
	v_lshlrev_b32_e32 v181, 16, v15
	v_and_b32_e32 v182, 0xffff0000, v15
	v_and_b32_e32 v14, 0x7fffffff, v182
	v_max_f32_e64 v15, |v181|, |v181|
	v_max_f32_e32 v184, v15, v14
	v_lshlrev_b32_e32 v14, 16, v16
	v_and_b32_e32 v15, 0xffff0000, v16
	v_lshlrev_b32_e32 v16, 16, v17
	v_and_b32_e32 v17, 0xffff0000, v17
	v_and_b32_e32 v185, 0x7fffffff, v17
	v_max_f32_e64 v186, |v16|, |v16|
	v_max_f32_e32 v185, v186, v185
	v_max3_f32 v185, |v14|, |v15|, v185
	v_max3_f32 v197, v183, v184, v185
	s_waitcnt vmcnt(1)
	v_lshlrev_b32_e32 v183, 16, v10
	v_and_b32_e32 v184, 0xffff0000, v10
	v_lshlrev_b32_e32 v185, 16, v11
	v_and_b32_e32 v186, 0xffff0000, v11
	v_lshlrev_b32_e32 v187, 16, v12
	v_and_b32_e32 v188, 0xffff0000, v12
	v_lshlrev_b32_e32 v189, 16, v13
	v_and_b32_e32 v190, 0xffff0000, v13
	v_add_f32_e32 v10, v183, v184
	v_sub_f32_e32 v11, v183, v184
	v_add_f32_e32 v12, v185, v186
	v_sub_f32_e32 v13, v185, v186
	v_add_f32_e32 v184, v187, v188
	v_sub_f32_e32 v185, v187, v188
	v_add_f32_e32 v186, v189, v190
	v_sub_f32_e32 v187, v189, v190
	v_pk_add_f32 v[188:189], v[10:11], v[12:13] neg_lo:[0,1] neg_hi:[0,1]
	v_pk_add_f32 v[190:191], v[184:185], v[186:187] neg_lo:[0,1] neg_hi:[0,1]
	v_pk_add_f32 v[10:11], v[10:11], v[12:13]
	v_pk_add_f32 v[192:193], v[188:189], v[190:191] neg_lo:[0,1] neg_hi:[0,1]
	v_pk_add_f32 v[188:189], v[188:189], v[190:191]
	v_pk_add_f32 v[12:13], v[184:185], v[186:187]
	v_mov_b32_dpp v194, v192 quad_perm:[1,0,3,2] row_mask:0xf bank_mask:0xf bound_ctrl:1
	v_mov_b32_dpp v190, v188 quad_perm:[1,0,3,2] row_mask:0xf bank_mask:0xf bound_ctrl:1
	v_mov_b32_dpp v191, v189 quad_perm:[1,0,3,2] row_mask:0xf bank_mask:0xf bound_ctrl:1
	v_pk_fma_f32 v[188:189], v[94:95], v[188:189], v[190:191]
	v_pk_add_f32 v[184:185], v[10:11], v[12:13] neg_lo:[0,1] neg_hi:[0,1]
	v_pk_add_f32 v[10:11], v[10:11], v[12:13]
	v_mov_b32_dpp v190, v188 quad_perm:[2,3,0,1] row_mask:0xf bank_mask:0xf bound_ctrl:1
	v_mov_b32_dpp v191, v189 quad_perm:[2,3,0,1] row_mask:0xf bank_mask:0xf bound_ctrl:1
	v_pk_fma_f32 v[188:189], v[92:93], v[188:189], v[190:191]
	ds_swizzle_b32 v190, v188 offset:swizzle(SWAP,4)
	ds_swizzle_b32 v191, v189 offset:swizzle(SWAP,4)
	v_mov_b32_dpp v12, v10 quad_perm:[1,0,3,2] row_mask:0xf bank_mask:0xf bound_ctrl:1
	v_mov_b32_dpp v13, v11 quad_perm:[1,0,3,2] row_mask:0xf bank_mask:0xf bound_ctrl:1
	v_mov_b32_dpp v195, v193 quad_perm:[1,0,3,2] row_mask:0xf bank_mask:0xf bound_ctrl:1
	v_mov_b32_dpp v186, v184 quad_perm:[1,0,3,2] row_mask:0xf bank_mask:0xf bound_ctrl:1
	v_mov_b32_dpp v187, v185 quad_perm:[1,0,3,2] row_mask:0xf bank_mask:0xf bound_ctrl:1
	v_pk_fma_f32 v[10:11], v[94:95], v[10:11], v[12:13]
	v_pk_fma_f32 v[192:193], v[94:95], v[192:193], v[194:195]
	v_pk_fma_f32 v[184:185], v[94:95], v[184:185], v[186:187]
	v_mov_b32_dpp v12, v10 quad_perm:[2,3,0,1] row_mask:0xf bank_mask:0xf bound_ctrl:1
	v_mov_b32_dpp v13, v11 quad_perm:[2,3,0,1] row_mask:0xf bank_mask:0xf bound_ctrl:1
	v_mov_b32_dpp v194, v192 quad_perm:[2,3,0,1] row_mask:0xf bank_mask:0xf bound_ctrl:1
	v_mov_b32_dpp v195, v193 quad_perm:[2,3,0,1] row_mask:0xf bank_mask:0xf bound_ctrl:1
	v_mov_b32_dpp v186, v184 quad_perm:[2,3,0,1] row_mask:0xf bank_mask:0xf bound_ctrl:1
	v_mov_b32_dpp v187, v185 quad_perm:[2,3,0,1] row_mask:0xf bank_mask:0xf bound_ctrl:1
	v_pk_fma_f32 v[10:11], v[92:93], v[10:11], v[12:13]
	v_pk_fma_f32 v[192:193], v[92:93], v[192:193], v[194:195]
	v_pk_fma_f32 v[184:185], v[92:93], v[184:185], v[186:187]
	ds_swizzle_b32 v12, v10 offset:swizzle(SWAP,4)
	ds_swizzle_b32 v13, v11 offset:swizzle(SWAP,4)
	s_waitcnt lgkmcnt(2)
	v_pk_fma_f32 v[188:189], v[90:91], v[188:189], v[190:191]
	ds_swizzle_b32 v186, v184 offset:swizzle(SWAP,4)
	ds_swizzle_b32 v187, v185 offset:swizzle(SWAP,4)
	ds_swizzle_b32 v190, v192 offset:swizzle(SWAP,4)
	ds_swizzle_b32 v191, v193 offset:swizzle(SWAP,4)
	s_waitcnt lgkmcnt(4)
	v_pk_fma_f32 v[10:11], v[90:91], v[10:11], v[12:13]
	v_pk_mul_f32 v[188:189], v[188:189], s[40:41] op_sel_hi:[1,0]
	v_pk_mul_f32 v[10:11], v[10:11], s[40:41] op_sel_hi:[1,0]
	s_waitcnt lgkmcnt(2)
	v_pk_fma_f32 v[12:13], v[90:91], v[184:185], v[186:187]
	s_waitcnt lgkmcnt(0)
	v_pk_fma_f32 v[184:185], v[90:91], v[192:193], v[190:191]
	v_pk_mul_f32 v[12:13], v[12:13], s[40:41] op_sel_hi:[1,0]
	v_pk_mul_f32 v[184:185], v[184:185], s[40:41] op_sel_hi:[1,0]
	v_cvt_pk_bf16_f32 v10, v10, v11
	v_cvt_pk_bf16_f32 v12, v12, v13
	v_cvt_pk_bf16_f32 v13, v184, v185
	v_lshlrev_b32_e32 v183, 16, v10
	v_and_b32_e32 v184, 0xffff0000, v10
	v_cvt_pk_bf16_f32 v11, v188, v189
	v_and_b32_e32 v10, 0x7fffffff, v184
	v_max_f32_e64 v185, |v183|, |v183|
	v_max_f32_e32 v187, v185, v10
	v_lshlrev_b32_e32 v185, 16, v11
	v_and_b32_e32 v186, 0xffff0000, v11
	v_and_b32_e32 v10, 0x7fffffff, v186
	v_max_f32_e64 v11, |v185|, |v185|
	v_max_f32_e32 v188, v11, v10
	v_lshlrev_b32_e32 v10, 16, v12
	v_and_b32_e32 v11, 0xffff0000, v12
	v_lshlrev_b32_e32 v12, 16, v13
	v_and_b32_e32 v13, 0xffff0000, v13
	v_and_b32_e32 v189, 0x7fffffff, v13
	v_max_f32_e64 v190, |v12|, |v12|
	v_max_f32_e32 v189, v190, v189
	v_max3_f32 v189, |v10|, |v11|, v189
	v_max3_f32 v187, v187, v188, v189
	v_max3_f32 v204, v196, v197, v187
	s_waitcnt vmcnt(0)
	v_lshlrev_b32_e32 v187, 16, v6
	v_and_b32_e32 v188, 0xffff0000, v6
	v_lshlrev_b32_e32 v189, 16, v7
	v_and_b32_e32 v190, 0xffff0000, v7
	v_lshlrev_b32_e32 v191, 16, v8
	v_and_b32_e32 v192, 0xffff0000, v8
	v_lshlrev_b32_e32 v193, 16, v9
	v_and_b32_e32 v194, 0xffff0000, v9
	v_add_f32_e32 v6, v187, v188
	v_sub_f32_e32 v7, v187, v188
	v_add_f32_e32 v8, v189, v190
	v_sub_f32_e32 v9, v189, v190
	v_add_f32_e32 v188, v191, v192
	v_sub_f32_e32 v189, v191, v192
	v_add_f32_e32 v190, v193, v194
	v_sub_f32_e32 v191, v193, v194
	v_pk_add_f32 v[192:193], v[6:7], v[8:9] neg_lo:[0,1] neg_hi:[0,1]
	v_pk_add_f32 v[194:195], v[188:189], v[190:191] neg_lo:[0,1] neg_hi:[0,1]
	v_pk_add_f32 v[6:7], v[6:7], v[8:9]
	v_pk_add_f32 v[196:197], v[192:193], v[194:195] neg_lo:[0,1] neg_hi:[0,1]
	v_pk_add_f32 v[192:193], v[192:193], v[194:195]
	v_pk_add_f32 v[8:9], v[188:189], v[190:191]
	v_mov_b32_dpp v198, v196 quad_perm:[1,0,3,2] row_mask:0xf bank_mask:0xf bound_ctrl:1
	v_mov_b32_dpp v194, v192 quad_perm:[1,0,3,2] row_mask:0xf bank_mask:0xf bound_ctrl:1
	v_mov_b32_dpp v195, v193 quad_perm:[1,0,3,2] row_mask:0xf bank_mask:0xf bound_ctrl:1
	v_pk_fma_f32 v[192:193], v[94:95], v[192:193], v[194:195]
	v_pk_add_f32 v[188:189], v[6:7], v[8:9] neg_lo:[0,1] neg_hi:[0,1]
	v_pk_add_f32 v[6:7], v[6:7], v[8:9]
	v_mov_b32_dpp v194, v192 quad_perm:[2,3,0,1] row_mask:0xf bank_mask:0xf bound_ctrl:1
	v_mov_b32_dpp v195, v193 quad_perm:[2,3,0,1] row_mask:0xf bank_mask:0xf bound_ctrl:1
	v_pk_fma_f32 v[192:193], v[92:93], v[192:193], v[194:195]
	ds_swizzle_b32 v194, v192 offset:swizzle(SWAP,4)
	ds_swizzle_b32 v195, v193 offset:swizzle(SWAP,4)
	v_mov_b32_dpp v8, v6 quad_perm:[1,0,3,2] row_mask:0xf bank_mask:0xf bound_ctrl:1
	v_mov_b32_dpp v9, v7 quad_perm:[1,0,3,2] row_mask:0xf bank_mask:0xf bound_ctrl:1
	v_mov_b32_dpp v199, v197 quad_perm:[1,0,3,2] row_mask:0xf bank_mask:0xf bound_ctrl:1
	v_mov_b32_dpp v190, v188 quad_perm:[1,0,3,2] row_mask:0xf bank_mask:0xf bound_ctrl:1
	v_mov_b32_dpp v191, v189 quad_perm:[1,0,3,2] row_mask:0xf bank_mask:0xf bound_ctrl:1
	v_pk_fma_f32 v[6:7], v[94:95], v[6:7], v[8:9]
	v_pk_fma_f32 v[196:197], v[94:95], v[196:197], v[198:199]
	v_pk_fma_f32 v[188:189], v[94:95], v[188:189], v[190:191]
	v_mov_b32_dpp v8, v6 quad_perm:[2,3,0,1] row_mask:0xf bank_mask:0xf bound_ctrl:1
	v_mov_b32_dpp v9, v7 quad_perm:[2,3,0,1] row_mask:0xf bank_mask:0xf bound_ctrl:1
	v_mov_b32_dpp v198, v196 quad_perm:[2,3,0,1] row_mask:0xf bank_mask:0xf bound_ctrl:1
	v_mov_b32_dpp v199, v197 quad_perm:[2,3,0,1] row_mask:0xf bank_mask:0xf bound_ctrl:1
	v_mov_b32_dpp v190, v188 quad_perm:[2,3,0,1] row_mask:0xf bank_mask:0xf bound_ctrl:1
	v_mov_b32_dpp v191, v189 quad_perm:[2,3,0,1] row_mask:0xf bank_mask:0xf bound_ctrl:1
	v_pk_fma_f32 v[6:7], v[92:93], v[6:7], v[8:9]
	v_pk_fma_f32 v[196:197], v[92:93], v[196:197], v[198:199]
	v_pk_fma_f32 v[188:189], v[92:93], v[188:189], v[190:191]
	ds_swizzle_b32 v8, v6 offset:swizzle(SWAP,4)
	ds_swizzle_b32 v9, v7 offset:swizzle(SWAP,4)
	s_waitcnt lgkmcnt(2)
	v_pk_fma_f32 v[192:193], v[90:91], v[192:193], v[194:195]
	ds_swizzle_b32 v190, v188 offset:swizzle(SWAP,4)
	ds_swizzle_b32 v191, v189 offset:swizzle(SWAP,4)
	ds_swizzle_b32 v194, v196 offset:swizzle(SWAP,4)
	ds_swizzle_b32 v195, v197 offset:swizzle(SWAP,4)
	s_waitcnt lgkmcnt(4)
	v_pk_fma_f32 v[6:7], v[90:91], v[6:7], v[8:9]
	v_pk_mul_f32 v[192:193], v[192:193], s[40:41] op_sel_hi:[1,0]
	v_pk_mul_f32 v[6:7], v[6:7], s[40:41] op_sel_hi:[1,0]
	s_waitcnt lgkmcnt(2)
	v_pk_fma_f32 v[8:9], v[90:91], v[188:189], v[190:191]
	s_waitcnt lgkmcnt(0)
	v_pk_fma_f32 v[188:189], v[90:91], v[196:197], v[194:195]
	v_cvt_pk_bf16_f32 v6, v6, v7
	v_pk_mul_f32 v[188:189], v[188:189], s[40:41] op_sel_hi:[1,0]
	v_pk_mul_f32 v[8:9], v[8:9], s[40:41] op_sel_hi:[1,0]
	v_cvt_pk_bf16_f32 v7, v192, v193
	v_cvt_pk_bf16_f32 v188, v188, v189
	v_lshlrev_b32_e32 v189, 16, v6
	v_and_b32_e32 v190, 0xffff0000, v6
	v_cvt_pk_bf16_f32 v9, v8, v9
	v_and_b32_e32 v6, 0x7fffffff, v190
	v_max_f32_e64 v8, |v189|, |v189|
	v_lshlrev_b32_e32 v191, 16, v7
	v_and_b32_e32 v192, 0xffff0000, v7
	v_lshlrev_b32_e32 v187, 16, v188
	v_and_b32_e32 v188, 0xffff0000, v188
	v_max_f32_e32 v6, v8, v6
	v_and_b32_e32 v7, 0x7fffffff, v192
	v_max_f32_e64 v8, |v191|, |v191|
	v_and_b32_e32 v193, 0x7fffffff, v188
	v_max_f32_e64 v194, |v187|, |v187|
	v_max_f32_e32 v7, v8, v7
	v_lshlrev_b32_e32 v8, 16, v9
	v_and_b32_e32 v9, 0xffff0000, v9
	v_max_f32_e32 v193, v194, v193
	v_max3_f32 v193, |v8|, |v9|, v193
	v_max3_f32 v193, v6, v7, v193
	v_lshlrev_b32_e32 v6, 16, v2
	v_and_b32_e32 v7, 0xffff0000, v2
	v_lshlrev_b32_e32 v194, 16, v3
	v_and_b32_e32 v195, 0xffff0000, v3
	v_lshlrev_b32_e32 v196, 16, v4
	v_and_b32_e32 v197, 0xffff0000, v4
	v_lshlrev_b32_e32 v198, 16, v5
	v_and_b32_e32 v199, 0xffff0000, v5
	v_add_f32_e32 v2, v6, v7
	v_sub_f32_e32 v3, v6, v7
	v_add_f32_e32 v4, v194, v195
	v_sub_f32_e32 v5, v194, v195
	v_add_f32_e32 v6, v196, v197
	v_sub_f32_e32 v7, v196, v197
	v_add_f32_e32 v194, v198, v199
	v_sub_f32_e32 v195, v198, v199
	v_pk_add_f32 v[196:197], v[2:3], v[4:5] neg_lo:[0,1] neg_hi:[0,1]
	v_pk_add_f32 v[198:199], v[6:7], v[194:195] neg_lo:[0,1] neg_hi:[0,1]
	v_pk_add_f32 v[2:3], v[2:3], v[4:5]
	v_pk_add_f32 v[200:201], v[196:197], v[198:199] neg_lo:[0,1] neg_hi:[0,1]
	v_pk_add_f32 v[196:197], v[196:197], v[198:199]
	v_pk_add_f32 v[4:5], v[6:7], v[194:195]
	v_mov_b32_dpp v202, v200 quad_perm:[1,0,3,2] row_mask:0xf bank_mask:0xf bound_ctrl:1
	v_mov_b32_dpp v198, v196 quad_perm:[1,0,3,2] row_mask:0xf bank_mask:0xf bound_ctrl:1
	v_mov_b32_dpp v199, v197 quad_perm:[1,0,3,2] row_mask:0xf bank_mask:0xf bound_ctrl:1
	v_pk_fma_f32 v[196:197], v[94:95], v[196:197], v[198:199]
	v_pk_add_f32 v[6:7], v[2:3], v[4:5] neg_lo:[0,1] neg_hi:[0,1]
	v_pk_add_f32 v[2:3], v[2:3], v[4:5]
	v_mov_b32_dpp v198, v196 quad_perm:[2,3,0,1] row_mask:0xf bank_mask:0xf bound_ctrl:1
	v_mov_b32_dpp v199, v197 quad_perm:[2,3,0,1] row_mask:0xf bank_mask:0xf bound_ctrl:1
	v_pk_fma_f32 v[196:197], v[92:93], v[196:197], v[198:199]
	ds_swizzle_b32 v198, v196 offset:swizzle(SWAP,4)
	ds_swizzle_b32 v199, v197 offset:swizzle(SWAP,4)
	v_mov_b32_dpp v203, v201 quad_perm:[1,0,3,2] row_mask:0xf bank_mask:0xf bound_ctrl:1
	v_mov_b32_dpp v194, v6 quad_perm:[1,0,3,2] row_mask:0xf bank_mask:0xf bound_ctrl:1
	v_mov_b32_dpp v195, v7 quad_perm:[1,0,3,2] row_mask:0xf bank_mask:0xf bound_ctrl:1
	v_mov_b32_dpp v4, v2 quad_perm:[1,0,3,2] row_mask:0xf bank_mask:0xf bound_ctrl:1
	v_mov_b32_dpp v5, v3 quad_perm:[1,0,3,2] row_mask:0xf bank_mask:0xf bound_ctrl:1
	v_pk_fma_f32 v[200:201], v[94:95], v[200:201], v[202:203]
	v_pk_fma_f32 v[6:7], v[94:95], v[6:7], v[194:195]
	v_pk_fma_f32 v[2:3], v[94:95], v[2:3], v[4:5]
	v_mov_b32_dpp v202, v200 quad_perm:[2,3,0,1] row_mask:0xf bank_mask:0xf bound_ctrl:1
	v_mov_b32_dpp v203, v201 quad_perm:[2,3,0,1] row_mask:0xf bank_mask:0xf bound_ctrl:1
	v_mov_b32_dpp v194, v6 quad_perm:[2,3,0,1] row_mask:0xf bank_mask:0xf bound_ctrl:1
	v_mov_b32_dpp v195, v7 quad_perm:[2,3,0,1] row_mask:0xf bank_mask:0xf bound_ctrl:1
	v_mov_b32_dpp v4, v2 quad_perm:[2,3,0,1] row_mask:0xf bank_mask:0xf bound_ctrl:1
	v_mov_b32_dpp v5, v3 quad_perm:[2,3,0,1] row_mask:0xf bank_mask:0xf bound_ctrl:1
	v_pk_fma_f32 v[200:201], v[92:93], v[200:201], v[202:203]
	v_pk_fma_f32 v[6:7], v[92:93], v[6:7], v[194:195]
	v_pk_fma_f32 v[2:3], v[92:93], v[2:3], v[4:5]
	s_waitcnt lgkmcnt(0)
	v_pk_fma_f32 v[196:197], v[90:91], v[196:197], v[198:199]
	ds_swizzle_b32 v4, v2 offset:swizzle(SWAP,4)
	ds_swizzle_b32 v5, v3 offset:swizzle(SWAP,4)
	ds_swizzle_b32 v194, v6 offset:swizzle(SWAP,4)
	ds_swizzle_b32 v195, v7 offset:swizzle(SWAP,4)
	ds_swizzle_b32 v198, v200 offset:swizzle(SWAP,4)
	ds_swizzle_b32 v199, v201 offset:swizzle(SWAP,4)
	s_waitcnt lgkmcnt(4)
	v_pk_fma_f32 v[2:3], v[90:91], v[2:3], v[4:5]
	v_pk_mul_f32 v[196:197], v[196:197], s[40:41] op_sel_hi:[1,0]
	s_waitcnt lgkmcnt(2)
	v_pk_fma_f32 v[4:5], v[90:91], v[6:7], v[194:195]
	v_pk_mul_f32 v[2:3], v[2:3], s[40:41] op_sel_hi:[1,0]
	s_waitcnt lgkmcnt(0)
	v_pk_fma_f32 v[6:7], v[90:91], v[200:201], v[198:199]
	v_pk_mul_f32 v[4:5], v[4:5], s[40:41] op_sel_hi:[1,0]
	v_pk_mul_f32 v[6:7], v[6:7], s[40:41] op_sel_hi:[1,0]
	v_cvt_pk_bf16_f32 v2, v2, v3
	v_cvt_pk_bf16_f32 v4, v4, v5
	v_cvt_pk_bf16_f32 v5, v6, v7
	v_cvt_pk_bf16_f32 v3, v196, v197
	v_lshlrev_b32_e32 v198, 16, v2
	v_and_b32_e32 v199, 0xffff0000, v2
	v_lshlrev_b32_e32 v196, 16, v5
	v_and_b32_e32 v197, 0xffff0000, v5
	v_and_b32_e32 v2, 0x7fffffff, v199
	v_max_f32_e64 v6, |v198|, |v198|
	v_lshlrev_b32_e32 v200, 16, v3
	v_and_b32_e32 v201, 0xffff0000, v3
	v_lshlrev_b32_e32 v194, 16, v4
	v_and_b32_e32 v195, 0xffff0000, v4
	v_and_b32_e32 v4, 0x7fffffff, v197
	v_max_f32_e64 v5, |v196|, |v196|
	v_max_f32_e32 v2, v6, v2
	v_and_b32_e32 v3, 0x7fffffff, v201
	v_max_f32_e64 v6, |v200|, |v200|
	v_max_f32_e32 v4, v5, v4
	v_max_f32_e32 v3, v6, v3
	v_max3_f32 v4, |v194|, |v195|, v4
	v_max3_f32 v2, v2, v3, v4
	v_max3_f32 v2, v204, v193, v2
	ds_bpermute_b32 v3, v104, v2
	s_mov_b32 s15, 0xda24260
	s_waitcnt lgkmcnt(0)
	v_max_f32_e32 v3, v3, v3
	v_max_f32_e32 v2, v2, v3
	ds_bpermute_b32 v3, v105, v2
	s_waitcnt lgkmcnt(0)
	v_max_f32_e32 v3, v3, v3
	v_max_f32_e32 v2, v2, v3
	ds_bpermute_b32 v3, v106, v2
	s_waitcnt lgkmcnt(0)
	v_max_f32_e32 v3, v3, v3
	v_max_f32_e32 v2, v2, v3
	ds_bpermute_b32 v3, v107, v2
	s_waitcnt lgkmcnt(0)
	v_max_f32_e32 v3, v3, v3
	v_max_f32_e32 v2, v2, v3
	ds_bpermute_b32 v3, v108, v2
	s_waitcnt lgkmcnt(0)
	v_max_f32_e32 v3, v3, v3
	v_max_f32_e32 v2, v2, v3
	ds_bpermute_b32 v3, v109, v2
	s_waitcnt lgkmcnt(0)
	v_max3_f32 v193, v2, v3, s15
	v_div_scale_f32 v2, s[16:17], v193, v193, s13
	v_rcp_f32_e32 v3, v2
	s_mov_b32 s15, 0x42400000
	v_fma_f32 v4, -v2, v3, 1.0
	v_fmac_f32_e32 v3, v4, v3
	v_div_scale_f32 v4, vcc, s13, v193, s13
	v_mul_f32_e32 v5, v4, v3
	v_fma_f32 v6, -v2, v5, v4
	v_fmac_f32_e32 v5, v6, v3
	v_fma_f32 v2, -v2, v5, v4
	v_div_fmas_f32 v2, v2, v3, v5
	v_div_fixup_f32 v202, v2, v193, s13
	v_mul_f32_e32 v3, v202, v102
	v_mul_f32_e32 v2, v202, v96
	v_mul_f32_e32 v4, v202, v103
	v_mul_f32_e32 v5, v202, v110
	v_rndne_f32_e32 v3, v3
	v_rndne_f32_e32 v2, v2
	v_cvt_i32_f32_e32 v3, v3
	v_rndne_f32_e32 v4, v4
	v_rndne_f32_e32 v5, v5
	v_cvt_i32_f32_e32 v2, v2
	v_cvt_i32_f32_sdwa v4, v4 dst_sel:WORD_1 dst_unused:UNUSED_PAD src0_sel:DWORD
	v_cvt_i32_f32_e32 v5, v5
	v_lshlrev_b32_e32 v3, 8, v3
	v_and_b32_e32 v3, 0xff00, v3
	v_and_b32_e32 v4, 0xff0000, v4
	v_perm_b32 v2, v5, v2, s14
	v_or3_b32 v102, v2, v3, v4
	v_mul_f32_e32 v3, v202, v87
	v_mul_f32_e32 v87, v202, v112
	v_mul_f32_e32 v83, v202, v83
	v_mul_f32_e32 v2, v202, v86
	v_mul_f32_e32 v4, v202, v88
	v_mul_f32_e32 v5, v202, v89
	v_mul_f32_e32 v86, v202, v111
	v_mul_f32_e32 v88, v202, v113
	v_mul_f32_e32 v89, v202, v114
	v_rndne_f32_e32 v87, v87
	v_mul_f32_e32 v82, v202, v82
	v_mul_f32_e32 v84, v202, v84
	v_mul_f32_e32 v85, v202, v85
	v_rndne_f32_e32 v83, v83
	v_rndne_f32_e32 v86, v86
	v_cvt_i32_f32_e32 v87, v87
	v_rndne_f32_e32 v88, v88
	v_rndne_f32_e32 v89, v89
	v_rndne_f32_e32 v82, v82
	v_cvt_i32_f32_e32 v83, v83
	v_rndne_f32_e32 v84, v84
	v_rndne_f32_e32 v85, v85
	v_cvt_i32_f32_e32 v86, v86
	v_cvt_i32_f32_sdwa v88, v88 dst_sel:WORD_1 dst_unused:UNUSED_PAD src0_sel:DWORD
	v_cvt_i32_f32_e32 v89, v89
	v_cvt_i32_f32_e32 v82, v82
	v_cvt_i32_f32_sdwa v84, v84 dst_sel:WORD_1 dst_unused:UNUSED_PAD src0_sel:DWORD
	v_cvt_i32_f32_e32 v85, v85
	v_lshlrev_b32_e32 v87, 8, v87
	v_lshlrev_b32_e32 v83, 8, v83
	v_and_b32_e32 v87, 0xff00, v87
	v_and_b32_e32 v88, 0xff0000, v88
	v_perm_b32 v86, v89, v86, s14
	v_and_b32_e32 v83, 0xff00, v83
	v_and_b32_e32 v84, 0xff0000, v84
	v_perm_b32 v82, v85, v82, s14
	v_or3_b32 v86, v86, v87, v88
	v_or3_b32 v87, v82, v83, v84
	v_mul_f32_e32 v83, v202, v116
	v_mul_f32_e32 v79, v202, v79
	v_mul_f32_e32 v82, v202, v115
	v_mul_f32_e32 v84, v202, v117
	v_mul_f32_e32 v85, v202, v118
	v_rndne_f32_e32 v83, v83
	v_mul_f32_e32 v78, v202, v78
	v_mul_f32_e32 v80, v202, v80
	v_mul_f32_e32 v81, v202, v81
	v_rndne_f32_e32 v79, v79
	v_rndne_f32_e32 v82, v82
	v_cvt_i32_f32_e32 v83, v83
	v_rndne_f32_e32 v84, v84
	v_rndne_f32_e32 v85, v85
	v_rndne_f32_e32 v78, v78
	v_cvt_i32_f32_e32 v79, v79
	v_rndne_f32_e32 v80, v80
	v_rndne_f32_e32 v81, v81
	v_cvt_i32_f32_e32 v82, v82
	v_cvt_i32_f32_sdwa v84, v84 dst_sel:WORD_1 dst_unused:UNUSED_PAD src0_sel:DWORD
	v_cvt_i32_f32_e32 v85, v85
	v_cvt_i32_f32_e32 v78, v78
	v_cvt_i32_f32_sdwa v80, v80 dst_sel:WORD_1 dst_unused:UNUSED_PAD src0_sel:DWORD
	v_cvt_i32_f32_e32 v81, v81
	v_lshlrev_b32_e32 v83, 8, v83
	v_lshlrev_b32_e32 v79, 8, v79
	v_and_b32_e32 v83, 0xff00, v83
	v_and_b32_e32 v84, 0xff0000, v84
	v_perm_b32 v82, v85, v82, s14
	v_and_b32_e32 v79, 0xff00, v79
	v_and_b32_e32 v80, 0xff0000, v80
	v_perm_b32 v78, v81, v78, s14
	v_or3_b32 v82, v82, v83, v84
	v_or3_b32 v83, v78, v79, v80
	v_mul_f32_e32 v79, v202, v120
	v_mul_f32_e32 v75, v202, v75
	v_mul_f32_e32 v78, v202, v119
	v_mul_f32_e32 v80, v202, v121
	v_mul_f32_e32 v81, v202, v122
	v_rndne_f32_e32 v79, v79
	v_mul_f32_e32 v74, v202, v74
	v_mul_f32_e32 v76, v202, v76
	v_mul_f32_e32 v77, v202, v77
	v_rndne_f32_e32 v75, v75
	v_rndne_f32_e32 v78, v78
	v_cvt_i32_f32_e32 v79, v79
	v_rndne_f32_e32 v80, v80
	v_rndne_f32_e32 v81, v81
	v_rndne_f32_e32 v74, v74
	v_cvt_i32_f32_e32 v75, v75
	v_rndne_f32_e32 v76, v76
	v_rndne_f32_e32 v77, v77
	v_cvt_i32_f32_e32 v78, v78
	v_cvt_i32_f32_sdwa v80, v80 dst_sel:WORD_1 dst_unused:UNUSED_PAD src0_sel:DWORD
	v_cvt_i32_f32_e32 v81, v81
	v_cvt_i32_f32_e32 v74, v74
	v_cvt_i32_f32_sdwa v76, v76 dst_sel:WORD_1 dst_unused:UNUSED_PAD src0_sel:DWORD
	v_cvt_i32_f32_e32 v77, v77
	v_lshlrev_b32_e32 v79, 8, v79
	v_lshlrev_b32_e32 v75, 8, v75
	v_and_b32_e32 v79, 0xff00, v79
	v_and_b32_e32 v80, 0xff0000, v80
	v_perm_b32 v78, v81, v78, s14
	v_and_b32_e32 v75, 0xff00, v75
	v_and_b32_e32 v76, 0xff0000, v76
	v_perm_b32 v74, v77, v74, s14
	v_or3_b32 v78, v78, v79, v80
	v_or3_b32 v79, v74, v75, v76
	v_mul_f32_e32 v75, v202, v124
	v_mul_f32_e32 v71, v202, v71
	v_mul_f32_e32 v74, v202, v123
	v_mul_f32_e32 v76, v202, v125
	v_mul_f32_e32 v77, v202, v126
	v_rndne_f32_e32 v75, v75
	v_mul_f32_e32 v70, v202, v70
	v_mul_f32_e32 v72, v202, v72
	v_mul_f32_e32 v73, v202, v73
	v_rndne_f32_e32 v71, v71
	v_rndne_f32_e32 v74, v74
	v_cvt_i32_f32_e32 v75, v75
	v_rndne_f32_e32 v76, v76
	v_rndne_f32_e32 v77, v77
	v_rndne_f32_e32 v70, v70
	v_cvt_i32_f32_e32 v71, v71
	v_rndne_f32_e32 v72, v72
	v_rndne_f32_e32 v73, v73
	v_cvt_i32_f32_e32 v74, v74
	v_cvt_i32_f32_sdwa v76, v76 dst_sel:WORD_1 dst_unused:UNUSED_PAD src0_sel:DWORD
	v_cvt_i32_f32_e32 v77, v77
	v_cvt_i32_f32_e32 v70, v70
	v_cvt_i32_f32_sdwa v72, v72 dst_sel:WORD_1 dst_unused:UNUSED_PAD src0_sel:DWORD
	v_cvt_i32_f32_e32 v73, v73
	v_lshlrev_b32_e32 v75, 8, v75
	v_lshlrev_b32_e32 v71, 8, v71
	v_and_b32_e32 v75, 0xff00, v75
	v_and_b32_e32 v76, 0xff0000, v76
	v_perm_b32 v74, v77, v74, s14
	v_and_b32_e32 v71, 0xff00, v71
	v_and_b32_e32 v72, 0xff0000, v72
	v_perm_b32 v70, v73, v70, s14
	v_or3_b32 v74, v74, v75, v76
	v_or3_b32 v75, v70, v71, v72
	v_mul_f32_e32 v71, v202, v128
	v_mul_f32_e32 v67, v202, v67
	v_mul_f32_e32 v70, v202, v127
	v_mul_f32_e32 v72, v202, v129
	v_mul_f32_e32 v73, v202, v130
	v_rndne_f32_e32 v71, v71
	v_mul_f32_e32 v66, v202, v66
	v_mul_f32_e32 v68, v202, v68
	v_mul_f32_e32 v69, v202, v69
	v_rndne_f32_e32 v67, v67
	v_rndne_f32_e32 v70, v70
	v_cvt_i32_f32_e32 v71, v71
	v_rndne_f32_e32 v72, v72
	v_rndne_f32_e32 v73, v73
	v_rndne_f32_e32 v66, v66
	v_cvt_i32_f32_e32 v67, v67
	v_rndne_f32_e32 v68, v68
	v_rndne_f32_e32 v69, v69
	v_cvt_i32_f32_e32 v70, v70
	v_cvt_i32_f32_sdwa v72, v72 dst_sel:WORD_1 dst_unused:UNUSED_PAD src0_sel:DWORD
	v_cvt_i32_f32_e32 v73, v73
	v_cvt_i32_f32_e32 v66, v66
	v_cvt_i32_f32_sdwa v68, v68 dst_sel:WORD_1 dst_unused:UNUSED_PAD src0_sel:DWORD
	v_cvt_i32_f32_e32 v69, v69
	v_lshlrev_b32_e32 v71, 8, v71
	v_lshlrev_b32_e32 v67, 8, v67
	v_and_b32_e32 v71, 0xff00, v71
	v_and_b32_e32 v72, 0xff0000, v72
	v_perm_b32 v70, v73, v70, s14
	v_and_b32_e32 v67, 0xff00, v67
	v_and_b32_e32 v68, 0xff0000, v68
	v_perm_b32 v66, v69, v66, s14
	v_or3_b32 v70, v70, v71, v72
	v_or3_b32 v71, v66, v67, v68
	v_mul_f32_e32 v67, v202, v132
	v_mul_f32_e32 v63, v202, v63
	v_mul_f32_e32 v66, v202, v131
	v_mul_f32_e32 v68, v202, v133
	v_mul_f32_e32 v69, v202, v134
	v_rndne_f32_e32 v67, v67
	v_mul_f32_e32 v62, v202, v62
	v_mul_f32_e32 v64, v202, v64
	v_mul_f32_e32 v65, v202, v65
	v_rndne_f32_e32 v63, v63
	v_rndne_f32_e32 v66, v66
	v_cvt_i32_f32_e32 v67, v67
	v_rndne_f32_e32 v68, v68
	v_rndne_f32_e32 v69, v69
	v_rndne_f32_e32 v62, v62
	v_cvt_i32_f32_e32 v63, v63
	v_rndne_f32_e32 v64, v64
	v_rndne_f32_e32 v65, v65
	v_cvt_i32_f32_e32 v66, v66
	v_cvt_i32_f32_sdwa v68, v68 dst_sel:WORD_1 dst_unused:UNUSED_PAD src0_sel:DWORD
	v_cvt_i32_f32_e32 v69, v69
	v_cvt_i32_f32_e32 v62, v62
	v_cvt_i32_f32_sdwa v64, v64 dst_sel:WORD_1 dst_unused:UNUSED_PAD src0_sel:DWORD
	v_cvt_i32_f32_e32 v65, v65
	v_lshlrev_b32_e32 v67, 8, v67
	v_lshlrev_b32_e32 v63, 8, v63
	v_rndne_f32_e32 v3, v3
	v_and_b32_e32 v67, 0xff00, v67
	v_and_b32_e32 v68, 0xff0000, v68
	v_perm_b32 v66, v69, v66, s14
	v_and_b32_e32 v63, 0xff00, v63
	v_and_b32_e32 v64, 0xff0000, v64
	v_perm_b32 v62, v65, v62, s14
	v_rndne_f32_e32 v2, v2
	v_cvt_i32_f32_e32 v3, v3
	v_rndne_f32_e32 v4, v4
	v_rndne_f32_e32 v5, v5
	v_or3_b32 v66, v66, v67, v68
	v_or3_b32 v67, v62, v63, v64
	v_mul_f32_e32 v63, v202, v136
	v_mul_f32_e32 v59, v202, v59
	v_cvt_i32_f32_e32 v2, v2
	v_cvt_i32_f32_sdwa v4, v4 dst_sel:WORD_1 dst_unused:UNUSED_PAD src0_sel:DWORD
	v_cvt_i32_f32_e32 v5, v5
	v_mul_f32_e32 v62, v202, v135
	v_mul_f32_e32 v64, v202, v137
	v_mul_f32_e32 v65, v202, v138
	v_rndne_f32_e32 v63, v63
	v_mul_f32_e32 v58, v202, v58
	v_mul_f32_e32 v60, v202, v60
	v_mul_f32_e32 v61, v202, v61
	v_rndne_f32_e32 v59, v59
	v_rndne_f32_e32 v62, v62
	v_cvt_i32_f32_e32 v63, v63
	v_rndne_f32_e32 v64, v64
	v_rndne_f32_e32 v65, v65
	v_rndne_f32_e32 v58, v58
	v_cvt_i32_f32_e32 v59, v59
	v_rndne_f32_e32 v60, v60
	v_rndne_f32_e32 v61, v61
	v_cvt_i32_f32_e32 v62, v62
	v_cvt_i32_f32_sdwa v64, v64 dst_sel:WORD_1 dst_unused:UNUSED_PAD src0_sel:DWORD
	v_cvt_i32_f32_e32 v65, v65
	v_cvt_i32_f32_e32 v58, v58
	v_cvt_i32_f32_sdwa v60, v60 dst_sel:WORD_1 dst_unused:UNUSED_PAD src0_sel:DWORD
	v_cvt_i32_f32_e32 v61, v61
	v_lshlrev_b32_e32 v3, 8, v3
	v_and_b32_e32 v3, 0xff00, v3
	v_and_b32_e32 v4, 0xff0000, v4
	v_perm_b32 v2, v5, v2, s14
	v_or3_b32 v103, v2, v3, v4
	v_lshl_add_u64 v[2:3], s[94:95], 0, v[98:99]
	v_lshlrev_b32_e32 v63, 8, v63
	v_lshlrev_b32_e32 v59, 8, v59
	v_add_co_u32_e32 v6, vcc, s15, v2
	v_and_b32_e32 v63, 0xff00, v63
	v_and_b32_e32 v64, 0xff0000, v64
	v_perm_b32 v62, v65, v62, s14
	v_and_b32_e32 v59, 0xff00, v59
	v_and_b32_e32 v60, 0xff0000, v60
	v_perm_b32 v58, v61, v58, s14
	v_addc_co_u32_e32 v7, vcc, 0, v3, vcc
	v_or3_b32 v62, v62, v63, v64
	v_or3_b32 v63, v58, v59, v60
	global_store_dwordx2 v[6:7], v[86:87], off offset:512
	global_store_dwordx2 v[6:7], v[82:83], off offset:1024
	global_store_dwordx2 v[6:7], v[78:79], off offset:1536
	global_store_dwordx2 v[6:7], v[74:75], off offset:2048
	global_store_dwordx2 v[6:7], v[70:71], off offset:2560
	global_store_dwordx2 v[6:7], v[66:67], off offset:3072
	global_store_dwordx2 v[6:7], v[62:63], off offset:3584
	v_mul_f32_e32 v7, v202, v140
	v_mul_f32_e32 v6, v202, v139
	v_mul_f32_e32 v58, v202, v141
	v_mul_f32_e32 v59, v202, v142
	v_rndne_f32_e32 v7, v7
	v_rndne_f32_e32 v6, v6
	v_cvt_i32_f32_e32 v7, v7
	v_rndne_f32_e32 v58, v58
	v_rndne_f32_e32 v59, v59
	v_cvt_i32_f32_e32 v6, v6
	v_cvt_i32_f32_sdwa v58, v58 dst_sel:WORD_1 dst_unused:UNUSED_PAD src0_sel:DWORD
	v_cvt_i32_f32_e32 v59, v59
	v_lshlrev_b32_e32 v7, 8, v7
	v_and_b32_e32 v7, 0xff00, v7
	v_and_b32_e32 v58, 0xff0000, v58
	v_perm_b32 v6, v59, v6, s14
	v_or3_b32 v6, v6, v7, v58
	v_mul_f32_e32 v7, v202, v54
	v_mul_f32_e32 v54, v202, v55
	v_mul_f32_e32 v55, v202, v56
	v_mul_f32_e32 v56, v202, v57
	v_rndne_f32_e32 v54, v54
	v_rndne_f32_e32 v7, v7
	v_cvt_i32_f32_e32 v54, v54
	v_rndne_f32_e32 v55, v55
	v_rndne_f32_e32 v56, v56
	v_cvt_i32_f32_e32 v7, v7
	v_cvt_i32_f32_sdwa v55, v55 dst_sel:WORD_1 dst_unused:UNUSED_PAD src0_sel:DWORD
	v_cvt_i32_f32_e32 v56, v56
	s_mov_b32 s15, 0x42401000
	v_lshlrev_b32_e32 v54, 8, v54
	v_add_co_u32_e32 v4, vcc, s15, v2
	v_and_b32_e32 v54, 0xff00, v54
	v_and_b32_e32 v55, 0xff0000, v55
	v_perm_b32 v7, v56, v7, s14
	v_addc_co_u32_e32 v5, vcc, 0, v3, vcc
	v_or3_b32 v7, v7, v54, v55
	global_store_dwordx2 v[4:5], v[6:7], off
	v_mul_f32_e32 v7, v202, v144
	v_mul_f32_e32 v6, v202, v143
	v_mul_f32_e32 v54, v202, v145
	v_mul_f32_e32 v55, v202, v146
	v_rndne_f32_e32 v7, v7
	v_rndne_f32_e32 v6, v6
	v_cvt_i32_f32_e32 v7, v7
	v_rndne_f32_e32 v54, v54
	v_rndne_f32_e32 v55, v55
	v_cvt_i32_f32_e32 v6, v6
	v_cvt_i32_f32_sdwa v54, v54 dst_sel:WORD_1 dst_unused:UNUSED_PAD src0_sel:DWORD
	v_cvt_i32_f32_e32 v55, v55
	v_lshlrev_b32_e32 v7, 8, v7
	v_and_b32_e32 v7, 0xff00, v7
	v_and_b32_e32 v54, 0xff0000, v54
	v_perm_b32 v6, v55, v6, s14
	v_or3_b32 v6, v6, v7, v54
	v_mul_f32_e32 v7, v202, v50
	v_mul_f32_e32 v50, v202, v51
	v_mul_f32_e32 v51, v202, v52
	v_mul_f32_e32 v52, v202, v53
	v_rndne_f32_e32 v50, v50
	v_rndne_f32_e32 v7, v7
	v_cvt_i32_f32_e32 v50, v50
	v_rndne_f32_e32 v51, v51
	v_rndne_f32_e32 v52, v52
	v_cvt_i32_f32_e32 v7, v7
	v_cvt_i32_f32_sdwa v51, v51 dst_sel:WORD_1 dst_unused:UNUSED_PAD src0_sel:DWORD
	v_cvt_i32_f32_e32 v52, v52
	v_lshlrev_b32_e32 v50, 8, v50
	v_and_b32_e32 v50, 0xff00, v50
	v_and_b32_e32 v51, 0xff0000, v51
	v_perm_b32 v7, v52, v7, s14
	v_or3_b32 v7, v7, v50, v51
	global_store_dwordx2 v[4:5], v[6:7], off offset:512
	v_mul_f32_e32 v7, v202, v148
	v_mul_f32_e32 v6, v202, v147
	v_mul_f32_e32 v50, v202, v149
	v_mul_f32_e32 v51, v202, v150
	v_rndne_f32_e32 v7, v7
	v_rndne_f32_e32 v6, v6
	v_cvt_i32_f32_e32 v7, v7
	v_rndne_f32_e32 v50, v50
	v_rndne_f32_e32 v51, v51
	v_cvt_i32_f32_e32 v6, v6
	v_cvt_i32_f32_sdwa v50, v50 dst_sel:WORD_1 dst_unused:UNUSED_PAD src0_sel:DWORD
	v_cvt_i32_f32_e32 v51, v51
	v_lshlrev_b32_e32 v7, 8, v7
	v_and_b32_e32 v7, 0xff00, v7
	v_and_b32_e32 v50, 0xff0000, v50
	v_perm_b32 v6, v51, v6, s14
	v_or3_b32 v6, v6, v7, v50
	v_mul_f32_e32 v7, v202, v46
	v_mul_f32_e32 v46, v202, v47
	v_mul_f32_e32 v47, v202, v48
	v_mul_f32_e32 v48, v202, v49
	v_rndne_f32_e32 v46, v46
	v_rndne_f32_e32 v7, v7
	v_cvt_i32_f32_e32 v46, v46
	v_rndne_f32_e32 v47, v47
	v_rndne_f32_e32 v48, v48
	v_cvt_i32_f32_e32 v7, v7
	v_cvt_i32_f32_sdwa v47, v47 dst_sel:WORD_1 dst_unused:UNUSED_PAD src0_sel:DWORD
	v_cvt_i32_f32_e32 v48, v48
	v_lshlrev_b32_e32 v46, 8, v46
	v_and_b32_e32 v46, 0xff00, v46
	v_and_b32_e32 v47, 0xff0000, v47
	v_perm_b32 v7, v48, v7, s14
	v_or3_b32 v7, v7, v46, v47
	global_store_dwordx2 v[4:5], v[6:7], off offset:1024
	v_mul_f32_e32 v7, v202, v152
	v_mul_f32_e32 v6, v202, v151
	v_mul_f32_e32 v46, v202, v153
	v_mul_f32_e32 v47, v202, v154
	v_rndne_f32_e32 v7, v7
	v_rndne_f32_e32 v6, v6
	v_cvt_i32_f32_e32 v7, v7
	v_rndne_f32_e32 v46, v46
	v_rndne_f32_e32 v47, v47
	v_cvt_i32_f32_e32 v6, v6
	v_cvt_i32_f32_sdwa v46, v46 dst_sel:WORD_1 dst_unused:UNUSED_PAD src0_sel:DWORD
	v_cvt_i32_f32_e32 v47, v47
	v_lshlrev_b32_e32 v7, 8, v7
	v_and_b32_e32 v7, 0xff00, v7
	v_and_b32_e32 v46, 0xff0000, v46
	v_perm_b32 v6, v47, v6, s14
	v_or3_b32 v6, v6, v7, v46
	v_mul_f32_e32 v7, v202, v42
	v_mul_f32_e32 v42, v202, v43
	v_mul_f32_e32 v43, v202, v44
	v_mul_f32_e32 v44, v202, v45
	v_rndne_f32_e32 v42, v42
	v_rndne_f32_e32 v7, v7
	v_cvt_i32_f32_e32 v42, v42
	v_rndne_f32_e32 v43, v43
	v_rndne_f32_e32 v44, v44
	v_cvt_i32_f32_e32 v7, v7
	v_cvt_i32_f32_sdwa v43, v43 dst_sel:WORD_1 dst_unused:UNUSED_PAD src0_sel:DWORD
	v_cvt_i32_f32_e32 v44, v44
	v_lshlrev_b32_e32 v42, 8, v42
	v_and_b32_e32 v42, 0xff00, v42
	v_and_b32_e32 v43, 0xff0000, v43
	v_perm_b32 v7, v44, v7, s14
	v_or3_b32 v7, v7, v42, v43
	global_store_dwordx2 v[4:5], v[6:7], off offset:1536
	v_mul_f32_e32 v7, v202, v156
	v_mul_f32_e32 v6, v202, v155
	v_mul_f32_e32 v42, v202, v157
	v_mul_f32_e32 v43, v202, v158
	v_rndne_f32_e32 v7, v7
	v_rndne_f32_e32 v6, v6
	v_cvt_i32_f32_e32 v7, v7
	v_rndne_f32_e32 v42, v42
	v_rndne_f32_e32 v43, v43
	v_cvt_i32_f32_e32 v6, v6
	v_cvt_i32_f32_sdwa v42, v42 dst_sel:WORD_1 dst_unused:UNUSED_PAD src0_sel:DWORD
	v_cvt_i32_f32_e32 v43, v43
	v_lshlrev_b32_e32 v7, 8, v7
	v_and_b32_e32 v7, 0xff00, v7
	v_and_b32_e32 v42, 0xff0000, v42
	v_perm_b32 v6, v43, v6, s14
	v_or3_b32 v6, v6, v7, v42
	v_mul_f32_e32 v7, v202, v38
	v_mul_f32_e32 v38, v202, v39
	v_mul_f32_e32 v39, v202, v40
	v_mul_f32_e32 v40, v202, v41
	v_rndne_f32_e32 v38, v38
	v_rndne_f32_e32 v7, v7
	v_cvt_i32_f32_e32 v38, v38
	v_rndne_f32_e32 v39, v39
	v_rndne_f32_e32 v40, v40
	v_cvt_i32_f32_e32 v7, v7
	v_cvt_i32_f32_sdwa v39, v39 dst_sel:WORD_1 dst_unused:UNUSED_PAD src0_sel:DWORD
	v_cvt_i32_f32_e32 v40, v40
	v_lshlrev_b32_e32 v38, 8, v38
	v_and_b32_e32 v38, 0xff00, v38
	v_and_b32_e32 v39, 0xff0000, v39
	v_perm_b32 v7, v40, v7, s14
	v_or3_b32 v7, v7, v38, v39
	global_store_dwordx2 v[4:5], v[6:7], off offset:2048
	v_mul_f32_e32 v7, v202, v160
	v_mul_f32_e32 v6, v202, v159
	v_mul_f32_e32 v38, v202, v161
	v_mul_f32_e32 v39, v202, v162
	v_rndne_f32_e32 v7, v7
	v_rndne_f32_e32 v6, v6
	v_cvt_i32_f32_e32 v7, v7
	v_rndne_f32_e32 v38, v38
	v_rndne_f32_e32 v39, v39
	v_cvt_i32_f32_e32 v6, v6
	v_cvt_i32_f32_sdwa v38, v38 dst_sel:WORD_1 dst_unused:UNUSED_PAD src0_sel:DWORD
	v_cvt_i32_f32_e32 v39, v39
	v_lshlrev_b32_e32 v7, 8, v7
	v_and_b32_e32 v7, 0xff00, v7
	v_and_b32_e32 v38, 0xff0000, v38
	v_perm_b32 v6, v39, v6, s14
	v_or3_b32 v6, v6, v7, v38
	v_mul_f32_e32 v7, v202, v34
	v_mul_f32_e32 v34, v202, v35
	v_mul_f32_e32 v35, v202, v36
	v_mul_f32_e32 v36, v202, v37
	v_rndne_f32_e32 v34, v34
	v_rndne_f32_e32 v7, v7
	v_cvt_i32_f32_e32 v34, v34
	v_rndne_f32_e32 v35, v35
	v_rndne_f32_e32 v36, v36
	v_cvt_i32_f32_e32 v7, v7
	v_cvt_i32_f32_sdwa v35, v35 dst_sel:WORD_1 dst_unused:UNUSED_PAD src0_sel:DWORD
	v_cvt_i32_f32_e32 v36, v36
	v_lshlrev_b32_e32 v34, 8, v34
	v_and_b32_e32 v34, 0xff00, v34
	v_and_b32_e32 v35, 0xff0000, v35
	v_perm_b32 v7, v36, v7, s14
	v_or3_b32 v7, v7, v34, v35
	global_store_dwordx2 v[4:5], v[6:7], off offset:2560
	v_mul_f32_e32 v7, v202, v164
	v_mul_f32_e32 v6, v202, v163
	v_mul_f32_e32 v34, v202, v165
	v_mul_f32_e32 v35, v202, v166
	v_rndne_f32_e32 v7, v7
	v_rndne_f32_e32 v6, v6
	v_cvt_i32_f32_e32 v7, v7
	v_rndne_f32_e32 v34, v34
	v_rndne_f32_e32 v35, v35
	v_cvt_i32_f32_e32 v6, v6
	v_cvt_i32_f32_sdwa v34, v34 dst_sel:WORD_1 dst_unused:UNUSED_PAD src0_sel:DWORD
	v_cvt_i32_f32_e32 v35, v35
	v_lshlrev_b32_e32 v7, 8, v7
	v_and_b32_e32 v7, 0xff00, v7
	v_and_b32_e32 v34, 0xff0000, v34
	v_perm_b32 v6, v35, v6, s14
	v_or3_b32 v6, v6, v7, v34
	v_mul_f32_e32 v7, v202, v30
	v_mul_f32_e32 v30, v202, v31
	v_mul_f32_e32 v31, v202, v32
	v_mul_f32_e32 v32, v202, v33
	v_rndne_f32_e32 v30, v30
	v_rndne_f32_e32 v7, v7
	v_cvt_i32_f32_e32 v30, v30
	v_rndne_f32_e32 v31, v31
	v_rndne_f32_e32 v32, v32
	v_cvt_i32_f32_e32 v7, v7
	v_cvt_i32_f32_sdwa v31, v31 dst_sel:WORD_1 dst_unused:UNUSED_PAD src0_sel:DWORD
	v_cvt_i32_f32_e32 v32, v32
	v_lshlrev_b32_e32 v30, 8, v30
	v_and_b32_e32 v30, 0xff00, v30
	v_and_b32_e32 v31, 0xff0000, v31
	v_perm_b32 v7, v32, v7, s14
	v_or3_b32 v7, v7, v30, v31
	global_store_dwordx2 v[4:5], v[6:7], off offset:3072
	v_mul_f32_e32 v7, v202, v168
	v_mul_f32_e32 v6, v202, v167
	v_mul_f32_e32 v30, v202, v169
	v_mul_f32_e32 v31, v202, v170
	v_rndne_f32_e32 v7, v7
	v_rndne_f32_e32 v6, v6
	v_cvt_i32_f32_e32 v7, v7
	v_rndne_f32_e32 v30, v30
	v_rndne_f32_e32 v31, v31
	v_cvt_i32_f32_e32 v6, v6
	v_cvt_i32_f32_sdwa v30, v30 dst_sel:WORD_1 dst_unused:UNUSED_PAD src0_sel:DWORD
	v_cvt_i32_f32_e32 v31, v31
	v_lshlrev_b32_e32 v7, 8, v7
	v_and_b32_e32 v7, 0xff00, v7
	v_and_b32_e32 v30, 0xff0000, v30
	v_perm_b32 v6, v31, v6, s14
	v_or3_b32 v6, v6, v7, v30
	v_mul_f32_e32 v7, v202, v26
	v_mul_f32_e32 v26, v202, v27
	v_mul_f32_e32 v27, v202, v28
	v_mul_f32_e32 v28, v202, v29
	v_rndne_f32_e32 v26, v26
	v_rndne_f32_e32 v7, v7
	v_cvt_i32_f32_e32 v26, v26
	v_rndne_f32_e32 v27, v27
	v_rndne_f32_e32 v28, v28
	v_cvt_i32_f32_e32 v7, v7
	v_cvt_i32_f32_sdwa v27, v27 dst_sel:WORD_1 dst_unused:UNUSED_PAD src0_sel:DWORD
	v_cvt_i32_f32_e32 v28, v28
	v_lshlrev_b32_e32 v26, 8, v26
	v_and_b32_e32 v26, 0xff00, v26
	v_and_b32_e32 v27, 0xff0000, v27
	v_perm_b32 v7, v28, v7, s14
	v_or3_b32 v7, v7, v26, v27
	global_store_dwordx2 v[4:5], v[102:103], off offset:-4096
	global_store_dwordx2 v[4:5], v[6:7], off offset:3584
	v_mul_f32_e32 v5, v202, v172
	v_mul_f32_e32 v4, v202, v171
	v_mul_f32_e32 v6, v202, v173
	v_mul_f32_e32 v7, v202, v174
	v_rndne_f32_e32 v5, v5
	v_rndne_f32_e32 v4, v4
	v_cvt_i32_f32_e32 v5, v5
	v_rndne_f32_e32 v6, v6
	v_rndne_f32_e32 v7, v7
	v_cvt_i32_f32_e32 v4, v4
	v_cvt_i32_f32_sdwa v6, v6 dst_sel:WORD_1 dst_unused:UNUSED_PAD src0_sel:DWORD
	v_cvt_i32_f32_e32 v7, v7
	v_lshlrev_b32_e32 v5, 8, v5
	v_and_b32_e32 v5, 0xff00, v5
	v_and_b32_e32 v6, 0xff0000, v6
	v_perm_b32 v4, v7, v4, s14
	v_or3_b32 v4, v4, v5, v6
	v_mul_f32_e32 v6, v202, v23
	v_mul_f32_e32 v5, v202, v22
	v_mul_f32_e32 v7, v202, v24
	v_mul_f32_e32 v22, v202, v25
	v_rndne_f32_e32 v6, v6
	v_rndne_f32_e32 v5, v5
	v_cvt_i32_f32_e32 v6, v6
	v_rndne_f32_e32 v7, v7
	v_rndne_f32_e32 v22, v22
	v_cvt_i32_f32_e32 v5, v5
	v_cvt_i32_f32_sdwa v7, v7 dst_sel:WORD_1 dst_unused:UNUSED_PAD src0_sel:DWORD
	v_cvt_i32_f32_e32 v22, v22
	v_lshlrev_b32_e32 v6, 8, v6
	v_and_b32_e32 v6, 0xff00, v6
	v_and_b32_e32 v7, 0xff0000, v7
	v_perm_b32 v5, v22, v5, s14
	s_mov_b32 s15, 0x42402000
	v_or3_b32 v5, v5, v6, v7
	v_add_co_u32_e32 v6, vcc, s15, v2
	v_mul_f32_e32 v22, v202, v177
	s_nop 0
	v_addc_co_u32_e32 v7, vcc, 0, v3, vcc
	global_store_dwordx2 v[6:7], v[4:5], off
	v_mul_f32_e32 v5, v202, v176
	v_mul_f32_e32 v4, v202, v175
	v_mul_f32_e32 v23, v202, v178
	v_rndne_f32_e32 v5, v5
	v_rndne_f32_e32 v4, v4
	v_cvt_i32_f32_e32 v5, v5
	v_rndne_f32_e32 v22, v22
	v_rndne_f32_e32 v23, v23
	v_cvt_i32_f32_e32 v4, v4
	v_cvt_i32_f32_sdwa v22, v22 dst_sel:WORD_1 dst_unused:UNUSED_PAD src0_sel:DWORD
	v_cvt_i32_f32_e32 v23, v23
	v_lshlrev_b32_e32 v5, 8, v5
	v_and_b32_e32 v5, 0xff00, v5
	v_and_b32_e32 v22, 0xff0000, v22
	v_perm_b32 v4, v23, v4, s14
	v_or3_b32 v4, v4, v5, v22
	v_mul_f32_e32 v5, v202, v18
	v_mul_f32_e32 v18, v202, v19
	v_mul_f32_e32 v19, v202, v20
	v_mul_f32_e32 v20, v202, v21
	v_rndne_f32_e32 v18, v18
	v_rndne_f32_e32 v5, v5
	v_cvt_i32_f32_e32 v18, v18
	v_rndne_f32_e32 v19, v19
	v_rndne_f32_e32 v20, v20
	v_cvt_i32_f32_e32 v5, v5
	v_cvt_i32_f32_sdwa v19, v19 dst_sel:WORD_1 dst_unused:UNUSED_PAD src0_sel:DWORD
	v_cvt_i32_f32_e32 v20, v20
	v_lshlrev_b32_e32 v18, 8, v18
	v_and_b32_e32 v18, 0xff00, v18
	v_and_b32_e32 v19, 0xff0000, v19
	v_perm_b32 v5, v20, v5, s14
	v_or3_b32 v5, v5, v18, v19
	global_store_dwordx2 v[6:7], v[4:5], off offset:512
	v_mul_f32_e32 v5, v202, v180
	v_mul_f32_e32 v4, v202, v179
	v_mul_f32_e32 v18, v202, v181
	v_mul_f32_e32 v19, v202, v182
	v_rndne_f32_e32 v5, v5
	v_rndne_f32_e32 v4, v4
	v_cvt_i32_f32_e32 v5, v5
	v_rndne_f32_e32 v18, v18
	v_rndne_f32_e32 v19, v19
	v_cvt_i32_f32_e32 v4, v4
	v_cvt_i32_f32_sdwa v18, v18 dst_sel:WORD_1 dst_unused:UNUSED_PAD src0_sel:DWORD
	v_cvt_i32_f32_e32 v19, v19
	v_lshlrev_b32_e32 v5, 8, v5
	v_and_b32_e32 v5, 0xff00, v5
	v_and_b32_e32 v18, 0xff0000, v18
	v_perm_b32 v4, v19, v4, s14
	v_or3_b32 v4, v4, v5, v18
	v_mul_f32_e32 v5, v202, v14
	v_mul_f32_e32 v14, v202, v15
	v_mul_f32_e32 v15, v202, v16
	v_mul_f32_e32 v16, v202, v17
	v_rndne_f32_e32 v14, v14
	v_rndne_f32_e32 v5, v5
	v_cvt_i32_f32_e32 v14, v14
	v_rndne_f32_e32 v15, v15
	v_rndne_f32_e32 v16, v16
	v_cvt_i32_f32_e32 v5, v5
	v_cvt_i32_f32_sdwa v15, v15 dst_sel:WORD_1 dst_unused:UNUSED_PAD src0_sel:DWORD
	v_cvt_i32_f32_e32 v16, v16
	v_lshlrev_b32_e32 v14, 8, v14
	v_and_b32_e32 v14, 0xff00, v14
	v_and_b32_e32 v15, 0xff0000, v15
	v_perm_b32 v5, v16, v5, s14
	v_or3_b32 v5, v5, v14, v15
	global_store_dwordx2 v[6:7], v[4:5], off offset:1024
	v_mul_f32_e32 v5, v202, v184
	v_mul_f32_e32 v4, v202, v183
	v_mul_f32_e32 v14, v202, v185
	v_mul_f32_e32 v15, v202, v186
	v_rndne_f32_e32 v5, v5
	v_rndne_f32_e32 v4, v4
	v_cvt_i32_f32_e32 v5, v5
	v_rndne_f32_e32 v14, v14
	v_rndne_f32_e32 v15, v15
	v_cvt_i32_f32_e32 v4, v4
	v_cvt_i32_f32_sdwa v14, v14 dst_sel:WORD_1 dst_unused:UNUSED_PAD src0_sel:DWORD
	v_cvt_i32_f32_e32 v15, v15
	v_lshlrev_b32_e32 v5, 8, v5
	v_and_b32_e32 v5, 0xff00, v5
	v_and_b32_e32 v14, 0xff0000, v14
	v_perm_b32 v4, v15, v4, s14
	v_or3_b32 v4, v4, v5, v14
	v_mul_f32_e32 v5, v202, v10
	v_mul_f32_e32 v10, v202, v11
	v_mul_f32_e32 v11, v202, v12
	v_mul_f32_e32 v12, v202, v13
	v_rndne_f32_e32 v10, v10
	v_rndne_f32_e32 v5, v5
	v_cvt_i32_f32_e32 v10, v10
	v_rndne_f32_e32 v11, v11
	v_rndne_f32_e32 v12, v12
	v_cvt_i32_f32_e32 v5, v5
	v_cvt_i32_f32_sdwa v11, v11 dst_sel:WORD_1 dst_unused:UNUSED_PAD src0_sel:DWORD
	v_cvt_i32_f32_e32 v12, v12
	v_lshlrev_b32_e32 v10, 8, v10
	v_and_b32_e32 v10, 0xff00, v10
	v_and_b32_e32 v11, 0xff0000, v11
	v_perm_b32 v5, v12, v5, s14
	v_or3_b32 v5, v5, v10, v11
	global_store_dwordx2 v[6:7], v[4:5], off offset:1536
	v_mul_f32_e32 v5, v202, v190
	v_mul_f32_e32 v4, v202, v189
	v_mul_f32_e32 v10, v202, v191
	v_mul_f32_e32 v11, v202, v192
	v_rndne_f32_e32 v5, v5
	v_rndne_f32_e32 v4, v4
	v_cvt_i32_f32_e32 v5, v5
	v_rndne_f32_e32 v10, v10
	v_rndne_f32_e32 v11, v11
	v_cvt_i32_f32_e32 v4, v4
	v_cvt_i32_f32_sdwa v10, v10 dst_sel:WORD_1 dst_unused:UNUSED_PAD src0_sel:DWORD
	v_cvt_i32_f32_e32 v11, v11
	v_lshlrev_b32_e32 v5, 8, v5
	v_and_b32_e32 v5, 0xff00, v5
	v_and_b32_e32 v10, 0xff0000, v10
	v_perm_b32 v4, v11, v4, s14
	v_or3_b32 v4, v4, v5, v10
	v_mul_f32_e32 v5, v202, v8
	v_mul_f32_e32 v8, v202, v9
	v_mul_f32_e32 v9, v202, v187
	v_mul_f32_e32 v10, v202, v188
	v_rndne_f32_e32 v8, v8
	v_rndne_f32_e32 v5, v5
	v_cvt_i32_f32_e32 v8, v8
	v_rndne_f32_e32 v9, v9
	v_rndne_f32_e32 v10, v10
	v_cvt_i32_f32_e32 v5, v5
	v_cvt_i32_f32_sdwa v9, v9 dst_sel:WORD_1 dst_unused:UNUSED_PAD src0_sel:DWORD
	v_cvt_i32_f32_e32 v10, v10
	v_lshlrev_b32_e32 v8, 8, v8
	v_and_b32_e32 v8, 0xff00, v8
	v_and_b32_e32 v9, 0xff0000, v9
	v_perm_b32 v5, v10, v5, s14
	v_or3_b32 v5, v5, v8, v9
	global_store_dwordx2 v[6:7], v[4:5], off offset:2048
	s_and_saveexec_b64 s[42:43], s[0:1]
	s_cbranch_execz .LBB0_185
	v_mul_f32_e32 v5, v202, v199
	v_mul_f32_e32 v4, v202, v198
	v_mul_f32_e32 v6, v202, v200
	v_mul_f32_e32 v7, v202, v201
	v_rndne_f32_e32 v5, v5
	v_rndne_f32_e32 v4, v4
	v_cvt_i32_f32_e32 v5, v5
	v_rndne_f32_e32 v6, v6
	v_rndne_f32_e32 v7, v7
	v_cvt_i32_f32_e32 v4, v4
	v_cvt_i32_f32_sdwa v6, v6 dst_sel:WORD_1 dst_unused:UNUSED_PAD src0_sel:DWORD
	v_cvt_i32_f32_e32 v7, v7
	v_lshlrev_b32_e32 v5, 8, v5
	v_and_b32_e32 v5, 0xff00, v5
	v_and_b32_e32 v6, 0xff0000, v6
	v_perm_b32 v4, v7, v4, s14
	v_or3_b32 v4, v4, v5, v6
	v_mul_f32_e32 v6, v202, v195
	v_mul_f32_e32 v5, v202, v194
	v_mul_f32_e32 v7, v202, v196
	v_mul_f32_e32 v8, v202, v197
	v_rndne_f32_e32 v6, v6
	v_rndne_f32_e32 v5, v5
	v_cvt_i32_f32_e32 v6, v6
	v_rndne_f32_e32 v7, v7
	v_rndne_f32_e32 v8, v8
	v_cvt_i32_f32_e32 v5, v5
	v_cvt_i32_f32_sdwa v7, v7 dst_sel:WORD_1 dst_unused:UNUSED_PAD src0_sel:DWORD
	v_cvt_i32_f32_e32 v8, v8
	v_lshlrev_b32_e32 v6, 8, v6
	v_and_b32_e32 v6, 0xff00, v6
	v_and_b32_e32 v7, 0xff0000, v7
	v_perm_b32 v5, v8, v5, s14
	v_add_co_u32_e32 v2, vcc, 0x42402000, v2
	v_or3_b32 v5, v5, v6, v7
	s_nop 0
	v_addc_co_u32_e32 v3, vcc, 0, v3, vcc
	global_store_dwordx2 v[2:3], v[4:5], off offset:2560
